# GEMM K-loops: per-phase s_setprio flips deleted (A/B of the flips on top of the slimmed load segments)
# speedup vs baseline: 1.0283x; 1.0042x over previous
.LBB0_34:
	ds_read_b128 v[164:167], v151
	ds_read_b128 v[168:171], v151 offset:1024
	ds_read_b128 v[172:175], v151 offset:2048
	ds_read_b128 v[176:179], v151 offset:3072
	v_lshl_add_u64 v[204:205], v[138:139], 0, s[12:13]
	v_lshl_add_u64 v[228:229], v[204:205], 0, s[60:61]
	s_add_i32 m0, s1, 0xc000
	ds_read_b128 v[180:183], v0
	ds_read_b128 v[184:187], v0 offset:1024
	ds_read_b128 v[188:191], v0 offset:2048
	ds_read_b128 v[192:195], v0 offset:3072
	ds_read_b128 v[196:199], v0 offset:4096
	ds_read_b128 v[200:203], v0 offset:5120
	ds_read_b128 v[222:225], v0 offset:6144
	ds_read_b128 v[232:235], v0 offset:7168
	global_load_lds_dwordx4 v[228:229], off
	v_lshl_add_u64 v[210:211], v[140:141], 0, s[12:13]
	s_add_i32 m0, s1, 0xe000
	v_lshl_add_u64 v[152:153], v[210:211], 0, s[60:61]
	global_load_lds_dwordx4 v[152:153], off
	s_waitcnt lgkmcnt(8)
	s_barrier
	s_waitcnt lgkmcnt(0)
	v_mfma_f32_16x16x32_bf16 v[126:129], v[164:167], v[180:183], v[126:129]
	v_mfma_f32_16x16x32_bf16 v[122:125], v[172:175], v[180:183], v[122:125]
	v_mfma_f32_16x16x32_bf16 v[118:121], v[164:167], v[188:191], v[118:121]
	v_mfma_f32_16x16x32_bf16 v[114:117], v[172:175], v[188:191], v[114:117]
	v_mfma_f32_16x16x32_bf16 v[110:113], v[164:167], v[196:199], v[110:113]
	v_mfma_f32_16x16x32_bf16 v[106:109], v[172:175], v[196:199], v[106:109]
	v_mfma_f32_16x16x32_bf16 v[102:105], v[164:167], v[222:225], v[102:105]
	v_mfma_f32_16x16x32_bf16 v[98:101], v[172:175], v[222:225], v[98:101]
	v_mfma_f32_16x16x32_bf16 v[126:129], v[168:171], v[184:187], v[126:129]
	v_mfma_f32_16x16x32_bf16 v[122:125], v[176:179], v[184:187], v[122:125]
	v_mfma_f32_16x16x32_bf16 v[118:121], v[168:171], v[192:195], v[118:121]
	v_mfma_f32_16x16x32_bf16 v[114:117], v[176:179], v[192:195], v[114:117]
	v_mfma_f32_16x16x32_bf16 v[110:113], v[168:171], v[200:203], v[110:113]
	v_mfma_f32_16x16x32_bf16 v[106:109], v[176:179], v[200:203], v[106:109]
	v_mfma_f32_16x16x32_bf16 v[102:105], v[168:171], v[232:235], v[102:105]
	v_mfma_f32_16x16x32_bf16 v[98:101], v[176:179], v[232:235], v[98:101]
	s_barrier
	v_lshl_add_u64 v[216:217], v[134:135], 0, s[12:13]
	s_add_i32 m0, s1, 0xff00
	ds_read_b128 v[236:239], v151 offset:16384
	ds_read_b128 v[240:243], v151 offset:17408
	ds_read_b128 v[244:247], v151 offset:18432
	ds_read_b128 v[248:251], v151 offset:19456
	global_load_lds_dwordx4 v[216:217], off offset:256
	s_add_i32 m0, s1, 0x11f00
	v_lshl_add_u64 v[218:219], v[136:137], 0, s[12:13]
	global_load_lds_dwordx4 v[218:219], off offset:256
	s_barrier
	s_waitcnt lgkmcnt(0)
	v_mfma_f32_16x16x32_bf16 v[94:97], v[236:239], v[180:183], v[94:97]
	v_mfma_f32_16x16x32_bf16 v[90:93], v[244:247], v[180:183], v[90:93]
	v_mfma_f32_16x16x32_bf16 v[86:89], v[236:239], v[188:191], v[86:89]
	v_mfma_f32_16x16x32_bf16 v[70:73], v[244:247], v[188:191], v[70:73]
	v_mfma_f32_16x16x32_bf16 v[62:65], v[236:239], v[196:199], v[62:65]
	v_mfma_f32_16x16x32_bf16 v[58:61], v[244:247], v[196:199], v[58:61]
	v_mfma_f32_16x16x32_bf16 v[54:57], v[236:239], v[222:225], v[54:57]
	v_mfma_f32_16x16x32_bf16 v[50:53], v[244:247], v[222:225], v[50:53]
	v_mfma_f32_16x16x32_bf16 v[94:97], v[240:243], v[184:187], v[94:97]
	v_mfma_f32_16x16x32_bf16 v[90:93], v[248:251], v[184:187], v[90:93]
	v_mfma_f32_16x16x32_bf16 v[86:89], v[240:243], v[192:195], v[86:89]
	v_mfma_f32_16x16x32_bf16 v[70:73], v[248:251], v[192:195], v[70:73]
	v_mfma_f32_16x16x32_bf16 v[62:65], v[240:243], v[200:203], v[62:65]
	v_mfma_f32_16x16x32_bf16 v[58:61], v[248:251], v[200:203], v[58:61]
	v_mfma_f32_16x16x32_bf16 v[54:57], v[240:243], v[232:235], v[54:57]
	v_mfma_f32_16x16x32_bf16 v[50:53], v[248:251], v[232:235], v[50:53]
	v_lshl_add_u64 v[158:159], v[204:205], 0, s[74:75]
	s_mov_b32 m0, s1
	s_barrier
	ds_read_b128 v[180:183], v0 offset:16384
	ds_read_b128 v[184:187], v0 offset:17408
	ds_read_b128 v[188:191], v0 offset:18432
	ds_read_b128 v[192:195], v0 offset:19456
	ds_read_b128 v[196:199], v0 offset:20480
	ds_read_b128 v[200:203], v0 offset:21504
	ds_read_b128 v[222:225], v0 offset:22528
	ds_read_b128 v[232:235], v0 offset:23552
	global_load_lds_dwordx4 v[158:159], off
	s_add_i32 m0, s1, 0x1f00
	s_nop 0
	global_load_lds_dwordx4 v[210:211], off offset:256
	s_barrier
	s_waitcnt lgkmcnt(0)
	v_mfma_f32_16x16x32_bf16 v[46:49], v[164:167], v[180:183], v[46:49]
	v_mfma_f32_16x16x32_bf16 v[42:45], v[172:175], v[180:183], v[42:45]
	v_mfma_f32_16x16x32_bf16 v[38:41], v[164:167], v[188:191], v[38:41]
	v_mfma_f32_16x16x32_bf16 v[34:37], v[172:175], v[188:191], v[34:37]
	v_mfma_f32_16x16x32_bf16 v[30:33], v[164:167], v[196:199], v[30:33]
	v_mfma_f32_16x16x32_bf16 v[26:29], v[172:175], v[196:199], v[26:29]
	v_mfma_f32_16x16x32_bf16 v[22:25], v[164:167], v[222:225], v[22:25]
	v_mfma_f32_16x16x32_bf16 v[18:21], v[172:175], v[222:225], v[18:21]
	v_mfma_f32_16x16x32_bf16 v[46:49], v[168:171], v[184:187], v[46:49]
	v_mfma_f32_16x16x32_bf16 v[42:45], v[176:179], v[184:187], v[42:45]
	v_mfma_f32_16x16x32_bf16 v[38:41], v[168:171], v[192:195], v[38:41]
	v_mfma_f32_16x16x32_bf16 v[34:37], v[176:179], v[192:195], v[34:37]
	v_mfma_f32_16x16x32_bf16 v[30:33], v[168:171], v[200:203], v[30:33]
	v_mfma_f32_16x16x32_bf16 v[26:29], v[176:179], v[200:203], v[26:29]
	v_mfma_f32_16x16x32_bf16 v[22:25], v[168:171], v[232:235], v[22:25]
	v_mfma_f32_16x16x32_bf16 v[18:21], v[176:179], v[232:235], v[18:21]
	s_barrier
	s_add_i32 m0, s1, 0x14000
	v_lshl_add_u64 v[154:155], v[216:217], 0, s[18:19]
	global_load_lds_dwordx4 v[154:155], off
	s_add_i32 m0, s1, 0x16000
	v_lshl_add_u64 v[156:157], v[218:219], 0, s[18:19]
	global_load_lds_dwordx4 v[156:157], off
	s_waitcnt vmcnt(6)
	s_barrier
	v_mfma_f32_16x16x32_bf16 v[14:17], v[236:239], v[180:183], v[14:17]
	v_mfma_f32_16x16x32_bf16 v[10:13], v[244:247], v[180:183], v[10:13]
	v_mfma_f32_16x16x32_bf16 v[6:9], v[236:239], v[188:191], v[6:9]
	v_mfma_f32_16x16x32_bf16 v[2:5], v[244:247], v[188:191], v[2:5]
	v_mfma_f32_16x16x32_bf16 v[66:69], v[236:239], v[196:199], v[66:69]
	v_mfma_f32_16x16x32_bf16 v[74:77], v[244:247], v[196:199], v[74:77]
	v_mfma_f32_16x16x32_bf16 v[78:81], v[236:239], v[222:225], v[78:81]
	v_mfma_f32_16x16x32_bf16 v[82:85], v[244:247], v[222:225], v[82:85]
	v_mfma_f32_16x16x32_bf16 v[14:17], v[240:243], v[184:187], v[14:17]
	v_mfma_f32_16x16x32_bf16 v[10:13], v[248:251], v[184:187], v[10:13]
	v_mfma_f32_16x16x32_bf16 v[6:9], v[240:243], v[192:195], v[6:9]
	v_mfma_f32_16x16x32_bf16 v[2:5], v[248:251], v[192:195], v[2:5]
	v_mfma_f32_16x16x32_bf16 v[66:69], v[240:243], v[200:203], v[66:69]
	v_mfma_f32_16x16x32_bf16 v[74:77], v[248:251], v[200:203], v[74:77]
	v_mfma_f32_16x16x32_bf16 v[78:81], v[240:243], v[232:235], v[78:81]
	v_mfma_f32_16x16x32_bf16 v[82:85], v[248:251], v[232:235], v[82:85]
	s_barrier
	ds_read_b128 v[164:167], v151 offset:32768
	ds_read_b128 v[168:171], v151 offset:33792
	ds_read_b128 v[172:175], v151 offset:34816
	ds_read_b128 v[176:179], v151 offset:35840
	s_add_i32 m0, s1, 0x3f80
	ds_read_b128 v[180:183], v0 offset:32768
	ds_read_b128 v[184:187], v0 offset:33792
	ds_read_b128 v[188:191], v0 offset:34816
	ds_read_b128 v[192:195], v0 offset:35840
	ds_read_b128 v[196:199], v0 offset:36864
	ds_read_b128 v[200:203], v0 offset:37888
	ds_read_b128 v[222:225], v0 offset:38912
	ds_read_b128 v[232:235], v0 offset:39936
	global_load_lds_dwordx4 v[228:229], off offset:128
	s_add_i32 m0, s1, 0x5f80
	s_nop 0
	global_load_lds_dwordx4 v[152:153], off offset:128
	s_waitcnt lgkmcnt(8)
	s_barrier
	s_waitcnt lgkmcnt(0)
	v_mfma_f32_16x16x32_bf16 v[126:129], v[164:167], v[180:183], v[126:129]
	v_mfma_f32_16x16x32_bf16 v[122:125], v[172:175], v[180:183], v[122:125]
	v_mfma_f32_16x16x32_bf16 v[118:121], v[164:167], v[188:191], v[118:121]
	v_mfma_f32_16x16x32_bf16 v[114:117], v[172:175], v[188:191], v[114:117]
	v_mfma_f32_16x16x32_bf16 v[110:113], v[164:167], v[196:199], v[110:113]
	v_mfma_f32_16x16x32_bf16 v[106:109], v[172:175], v[196:199], v[106:109]
	v_mfma_f32_16x16x32_bf16 v[102:105], v[164:167], v[222:225], v[102:105]
	v_mfma_f32_16x16x32_bf16 v[98:101], v[172:175], v[222:225], v[98:101]
	v_mfma_f32_16x16x32_bf16 v[126:129], v[168:171], v[184:187], v[126:129]
	v_mfma_f32_16x16x32_bf16 v[122:125], v[176:179], v[184:187], v[122:125]
	v_mfma_f32_16x16x32_bf16 v[118:121], v[168:171], v[192:195], v[118:121]
	v_mfma_f32_16x16x32_bf16 v[114:117], v[176:179], v[192:195], v[114:117]
	v_mfma_f32_16x16x32_bf16 v[110:113], v[168:171], v[200:203], v[110:113]
	v_mfma_f32_16x16x32_bf16 v[106:109], v[176:179], v[200:203], v[106:109]
	v_mfma_f32_16x16x32_bf16 v[102:105], v[168:171], v[232:235], v[102:105]
	v_mfma_f32_16x16x32_bf16 v[98:101], v[176:179], v[232:235], v[98:101]
	s_barrier
	s_add_i32 m0, s1, 0x17e80
	ds_read_b128 v[236:239], v151 offset:49152
	ds_read_b128 v[240:243], v151 offset:50176
	ds_read_b128 v[244:247], v151 offset:51200
	ds_read_b128 v[248:251], v151 offset:52224
	global_load_lds_dwordx4 v[216:217], off offset:384
	s_add_i32 m0, s1, 0x19e80
	s_nop 0
	global_load_lds_dwordx4 v[218:219], off offset:384
	s_barrier
	s_waitcnt lgkmcnt(0)
	v_mfma_f32_16x16x32_bf16 v[94:97], v[236:239], v[180:183], v[94:97]
	v_mfma_f32_16x16x32_bf16 v[90:93], v[244:247], v[180:183], v[90:93]
	v_mfma_f32_16x16x32_bf16 v[86:89], v[236:239], v[188:191], v[86:89]
	v_mfma_f32_16x16x32_bf16 v[70:73], v[244:247], v[188:191], v[70:73]
	v_mfma_f32_16x16x32_bf16 v[62:65], v[236:239], v[196:199], v[62:65]
	v_mfma_f32_16x16x32_bf16 v[58:61], v[244:247], v[196:199], v[58:61]
	v_mfma_f32_16x16x32_bf16 v[54:57], v[236:239], v[222:225], v[54:57]
	v_mfma_f32_16x16x32_bf16 v[50:53], v[244:247], v[222:225], v[50:53]
	v_mfma_f32_16x16x32_bf16 v[94:97], v[240:243], v[184:187], v[94:97]
	v_mfma_f32_16x16x32_bf16 v[90:93], v[248:251], v[184:187], v[90:93]
	v_mfma_f32_16x16x32_bf16 v[86:89], v[240:243], v[192:195], v[86:89]
	v_mfma_f32_16x16x32_bf16 v[70:73], v[248:251], v[192:195], v[70:73]
	v_mfma_f32_16x16x32_bf16 v[62:65], v[240:243], v[200:203], v[62:65]
	v_mfma_f32_16x16x32_bf16 v[58:61], v[248:251], v[200:203], v[58:61]
	v_mfma_f32_16x16x32_bf16 v[54:57], v[240:243], v[232:235], v[54:57]
	v_mfma_f32_16x16x32_bf16 v[50:53], v[248:251], v[232:235], v[50:53]
	s_add_i32 m0, s1, 0x7e80
	s_barrier
	ds_read_b128 v[180:183], v0 offset:49152
	ds_read_b128 v[184:187], v0 offset:50176
	ds_read_b128 v[188:191], v0 offset:51200
	ds_read_b128 v[192:195], v0 offset:52224
	ds_read_b128 v[196:199], v0 offset:53248
	ds_read_b128 v[200:203], v0 offset:54272
	ds_read_b128 v[222:225], v0 offset:55296
	ds_read_b128 v[232:235], v0 offset:56320
	global_load_lds_dwordx4 v[204:205], off offset:384
	s_add_i32 m0, s1, 0x9e80
	s_nop 0
	global_load_lds_dwordx4 v[210:211], off offset:384
	s_barrier
	s_waitcnt lgkmcnt(0)
	v_mfma_f32_16x16x32_bf16 v[46:49], v[164:167], v[180:183], v[46:49]
	v_mfma_f32_16x16x32_bf16 v[42:45], v[172:175], v[180:183], v[42:45]
	v_mfma_f32_16x16x32_bf16 v[38:41], v[164:167], v[188:191], v[38:41]
	v_mfma_f32_16x16x32_bf16 v[34:37], v[172:175], v[188:191], v[34:37]
	v_mfma_f32_16x16x32_bf16 v[30:33], v[164:167], v[196:199], v[30:33]
	v_mfma_f32_16x16x32_bf16 v[26:29], v[172:175], v[196:199], v[26:29]
	v_mfma_f32_16x16x32_bf16 v[22:25], v[164:167], v[222:225], v[22:25]
	v_mfma_f32_16x16x32_bf16 v[18:21], v[172:175], v[222:225], v[18:21]
	v_mfma_f32_16x16x32_bf16 v[46:49], v[168:171], v[184:187], v[46:49]
	v_mfma_f32_16x16x32_bf16 v[42:45], v[176:179], v[184:187], v[42:45]
	v_mfma_f32_16x16x32_bf16 v[38:41], v[168:171], v[192:195], v[38:41]
	v_mfma_f32_16x16x32_bf16 v[34:37], v[176:179], v[192:195], v[34:37]
	v_mfma_f32_16x16x32_bf16 v[30:33], v[168:171], v[200:203], v[30:33]
	v_mfma_f32_16x16x32_bf16 v[26:29], v[176:179], v[200:203], v[26:29]
	v_mfma_f32_16x16x32_bf16 v[22:25], v[168:171], v[232:235], v[22:25]
	v_mfma_f32_16x16x32_bf16 v[18:21], v[176:179], v[232:235], v[18:21]
	s_barrier
	s_add_i32 m0, s1, 0x1bf80
	s_nop 0
	global_load_lds_dwordx4 v[154:155], off offset:128
	s_add_i32 m0, s1, 0x1df80
	s_nop 0
	global_load_lds_dwordx4 v[156:157], off offset:128
	s_waitcnt vmcnt(6)
	s_barrier
	v_mfma_f32_16x16x32_bf16 v[14:17], v[236:239], v[180:183], v[14:17]
	v_mfma_f32_16x16x32_bf16 v[10:13], v[244:247], v[180:183], v[10:13]
	v_mfma_f32_16x16x32_bf16 v[6:9], v[236:239], v[188:191], v[6:9]
	v_mfma_f32_16x16x32_bf16 v[2:5], v[244:247], v[188:191], v[2:5]
	v_mfma_f32_16x16x32_bf16 v[66:69], v[236:239], v[196:199], v[66:69]
	v_mfma_f32_16x16x32_bf16 v[74:77], v[244:247], v[196:199], v[74:77]
	v_mfma_f32_16x16x32_bf16 v[78:81], v[236:239], v[222:225], v[78:81]
	v_mfma_f32_16x16x32_bf16 v[82:85], v[244:247], v[222:225], v[82:85]
	v_mfma_f32_16x16x32_bf16 v[14:17], v[240:243], v[184:187], v[14:17]
	v_mfma_f32_16x16x32_bf16 v[10:13], v[248:251], v[184:187], v[10:13]
	v_mfma_f32_16x16x32_bf16 v[6:9], v[240:243], v[192:195], v[6:9]
	v_mfma_f32_16x16x32_bf16 v[2:5], v[248:251], v[192:195], v[2:5]
	v_mfma_f32_16x16x32_bf16 v[66:69], v[240:243], v[200:203], v[66:69]
	v_mfma_f32_16x16x32_bf16 v[74:77], v[248:251], v[200:203], v[74:77]
	v_mfma_f32_16x16x32_bf16 v[78:81], v[240:243], v[232:235], v[78:81]
	v_mfma_f32_16x16x32_bf16 v[82:85], v[248:251], v[232:235], v[82:85]
	s_add_i32 s0, s0, 2
	s_add_u32 s12, s12, 0x100
	s_addc_u32 s13, s13, 0
	s_cmp_lt_u32 s0, 28
	s_barrier
	s_cbranch_scc1 .LBB0_34
	s_add_i32 s1, s1, 0x1e000
	s_mov_b64 s[12:13], 0xf80
	v_readfirstlane_b32 s0, v162
	v_lshl_add_u64 v[132:133], v[132:133], 0, s[12:13]
	s_mov_b32 m0, s0
	v_readfirstlane_b32 s0, v163
	ds_read_b128 v[134:137], v151
	ds_read_b128 v[138:141], v151 offset:1024
	ds_read_b128 v[152:155], v151 offset:2048
	ds_read_b128 v[156:159], v151 offset:3072
	ds_read_b128 v[164:167], v0
	ds_read_b128 v[168:171], v0 offset:1024
	ds_read_b128 v[172:175], v0 offset:2048
	ds_read_b128 v[176:179], v0 offset:3072
	ds_read_b128 v[180:183], v0 offset:4096
	ds_read_b128 v[184:187], v0 offset:5120
	ds_read_b128 v[188:191], v0 offset:6144
	ds_read_b128 v[192:195], v0 offset:7168
	global_load_lds_dwordx4 v[132:133], off
	v_lshl_add_u64 v[130:131], v[130:131], 0, s[12:13]
	s_mov_b32 m0, s0
	s_nop 0
	global_load_lds_dwordx4 v[130:131], off
	s_barrier
	s_waitcnt lgkmcnt(0)
	s_setprio 1
	s_waitcnt lgkmcnt(0)
	v_mfma_f32_16x16x32_bf16 v[122:125], v[152:155], v[164:167], v[122:125]
	v_mfma_f32_16x16x32_bf16 v[118:121], v[134:137], v[172:175], v[118:121]
	v_mfma_f32_16x16x32_bf16 v[114:117], v[152:155], v[172:175], v[114:117]
	v_mfma_f32_16x16x32_bf16 v[102:105], v[134:137], v[188:191], v[102:105]
	v_mfma_f32_16x16x32_bf16 v[98:101], v[152:155], v[188:191], v[98:101]
	v_mfma_f32_16x16x32_bf16 v[126:129], v[134:137], v[164:167], v[126:129]
	v_mfma_f32_16x16x32_bf16 v[122:125], v[156:159], v[168:171], v[122:125]
	v_mfma_f32_16x16x32_bf16 v[118:121], v[138:141], v[176:179], v[118:121]
	v_mfma_f32_16x16x32_bf16 v[114:117], v[156:159], v[176:179], v[114:117]
	v_mfma_f32_16x16x32_bf16 v[110:113], v[134:137], v[180:183], v[110:113]
	v_mfma_f32_16x16x32_bf16 v[106:109], v[152:155], v[180:183], v[106:109]
	v_mfma_f32_16x16x32_bf16 v[102:105], v[138:141], v[192:195], v[102:105]
	v_mfma_f32_16x16x32_bf16 v[98:101], v[156:159], v[192:195], v[98:101]
	v_mfma_f32_16x16x32_bf16 v[126:129], v[138:141], v[168:171], v[126:129]
	v_mfma_f32_16x16x32_bf16 v[130:133], v[138:141], v[184:187], v[110:113]
	v_mfma_f32_16x16x32_bf16 v[160:163], v[156:159], v[184:187], v[106:109]
	s_setprio 0
	s_barrier
	ds_read_b128 v[106:109], v151 offset:16384
	ds_read_b128 v[110:113], v151 offset:17408
	ds_read_b128 v[196:199], v151 offset:18432
	ds_read_b128 v[200:203], v151 offset:19456
	s_barrier
	s_waitcnt lgkmcnt(0)
	s_setprio 1
	s_waitcnt lgkmcnt(3)
	v_mfma_f32_16x16x32_bf16 v[86:89], v[106:109], v[172:175], v[86:89]
	s_waitcnt lgkmcnt(1)
	v_mfma_f32_16x16x32_bf16 v[70:73], v[196:199], v[172:175], v[70:73]
	v_mfma_f32_16x16x32_bf16 v[62:65], v[106:109], v[180:183], v[62:65]
	v_mfma_f32_16x16x32_bf16 v[58:61], v[196:199], v[180:183], v[58:61]
	v_mfma_f32_16x16x32_bf16 v[54:57], v[106:109], v[188:191], v[54:57]
	v_mfma_f32_16x16x32_bf16 v[50:53], v[196:199], v[188:191], v[50:53]
	v_mfma_f32_16x16x32_bf16 v[94:97], v[106:109], v[164:167], v[94:97]
	v_mfma_f32_16x16x32_bf16 v[90:93], v[196:199], v[164:167], v[90:93]
	v_mfma_f32_16x16x32_bf16 v[86:89], v[110:113], v[176:179], v[86:89]
	s_waitcnt lgkmcnt(0)
	v_mfma_f32_16x16x32_bf16 v[70:73], v[200:203], v[176:179], v[70:73]
	v_mfma_f32_16x16x32_bf16 v[62:65], v[110:113], v[184:187], v[62:65]
	v_mfma_f32_16x16x32_bf16 v[58:61], v[200:203], v[184:187], v[58:61]
	v_mfma_f32_16x16x32_bf16 v[54:57], v[110:113], v[192:195], v[54:57]
	v_mfma_f32_16x16x32_bf16 v[50:53], v[200:203], v[192:195], v[50:53]
	v_mfma_f32_16x16x32_bf16 v[222:225], v[110:113], v[168:171], v[94:97]
	v_mfma_f32_16x16x32_bf16 v[164:167], v[200:203], v[168:171], v[90:93]
	s_setprio 0
	s_barrier
	s_nop 0
	ds_read_b128 v[90:93], v0 offset:16384
	ds_read_b128 v[94:97], v0 offset:17408
	ds_read_b128 v[168:171], v0 offset:18432
	ds_read_b128 v[172:175], v0 offset:19456
	ds_read_b128 v[176:179], v0 offset:20480
	ds_read_b128 v[180:183], v0 offset:21504
	ds_read_b128 v[184:187], v0 offset:22528
	ds_read_b128 v[188:191], v0 offset:23552
	s_waitcnt vmcnt(4)
	s_barrier
	s_waitcnt lgkmcnt(0)
	s_setprio 1
	s_waitcnt lgkmcnt(7)
	v_mfma_f32_16x16x32_bf16 v[46:49], v[134:137], v[90:93], v[46:49]
	v_mfma_f32_16x16x32_bf16 v[42:45], v[152:155], v[90:93], v[42:45]
	s_waitcnt lgkmcnt(5)
	v_mfma_f32_16x16x32_bf16 v[38:41], v[134:137], v[168:171], v[38:41]
	v_mfma_f32_16x16x32_bf16 v[34:37], v[152:155], v[168:171], v[34:37]
	s_waitcnt lgkmcnt(3)
	v_mfma_f32_16x16x32_bf16 v[30:33], v[134:137], v[176:179], v[30:33]
	v_mfma_f32_16x16x32_bf16 v[26:29], v[152:155], v[176:179], v[26:29]
	s_waitcnt lgkmcnt(1)
	v_mfma_f32_16x16x32_bf16 v[22:25], v[134:137], v[184:187], v[22:25]
	v_mfma_f32_16x16x32_bf16 v[18:21], v[152:155], v[184:187], v[18:21]
	v_mfma_f32_16x16x32_bf16 v[46:49], v[138:141], v[94:97], v[46:49]
	v_mfma_f32_16x16x32_bf16 v[42:45], v[156:159], v[94:97], v[42:45]
	v_mfma_f32_16x16x32_bf16 v[38:41], v[138:141], v[172:175], v[38:41]
	v_mfma_f32_16x16x32_bf16 v[34:37], v[156:159], v[172:175], v[34:37]
	v_mfma_f32_16x16x32_bf16 v[30:33], v[138:141], v[180:183], v[30:33]
	v_mfma_f32_16x16x32_bf16 v[26:29], v[156:159], v[180:183], v[26:29]
	s_waitcnt lgkmcnt(0)
	v_mfma_f32_16x16x32_bf16 v[22:25], v[138:141], v[188:191], v[22:25]
	v_mfma_f32_16x16x32_bf16 v[18:21], v[156:159], v[188:191], v[18:21]
	s_setprio 0
	s_setprio 1
	v_mfma_f32_16x16x32_bf16 v[10:13], v[196:199], v[90:93], v[10:13]
	v_mfma_f32_16x16x32_bf16 v[152:155], v[200:203], v[94:97], v[10:13]
	v_mfma_f32_16x16x32_bf16 v[10:13], v[106:109], v[176:179], v[66:69]
	v_mfma_f32_16x16x32_bf16 v[156:159], v[110:113], v[180:183], v[10:13]
	v_mfma_f32_16x16x32_bf16 v[10:13], v[196:199], v[176:179], v[74:77]
	v_mfma_f32_16x16x32_bf16 v[6:9], v[106:109], v[168:171], v[6:9]
	v_mfma_f32_16x16x32_bf16 v[2:5], v[196:199], v[168:171], v[2:5]
	v_mfma_f32_16x16x32_bf16 v[168:171], v[200:203], v[180:183], v[10:13]
	v_mfma_f32_16x16x32_bf16 v[10:13], v[106:109], v[184:187], v[78:81]
	v_mfma_f32_16x16x32_bf16 v[14:17], v[106:109], v[90:93], v[14:17]
	v_mfma_f32_16x16x32_bf16 v[6:9], v[110:113], v[172:175], v[6:9]
	v_mfma_f32_16x16x32_bf16 v[2:5], v[200:203], v[172:175], v[2:5]
	v_mfma_f32_16x16x32_bf16 v[172:175], v[110:113], v[188:191], v[10:13]
	v_mfma_f32_16x16x32_bf16 v[10:13], v[196:199], v[184:187], v[82:85]
	v_mfma_f32_16x16x32_bf16 v[134:137], v[110:113], v[94:97], v[14:17]
	v_mfma_f32_16x16x32_bf16 v[176:179], v[200:203], v[188:191], v[10:13]
	s_setprio 0
	s_barrier
	s_nop 3
	ds_read_b128 v[10:13], v151 offset:32768
	ds_read_b128 v[14:17], v151 offset:33792
	ds_read_b128 v[180:183], v151 offset:34816
	ds_read_b128 v[184:187], v151 offset:35840
	ds_read_b128 v[66:69], v0 offset:32768
	ds_read_b128 v[82:85], v0 offset:33792
	ds_read_b128 v[188:191], v0 offset:34816
	ds_read_b128 v[192:195], v0 offset:35840
	ds_read_b128 v[196:199], v0 offset:36864
	ds_read_b128 v[200:203], v0 offset:37888
	ds_read_b128 v[232:235], v0 offset:38912
	ds_read_b128 v[236:239], v0 offset:39936
	s_waitcnt vmcnt(2)
	s_barrier
	s_waitcnt lgkmcnt(0)
	s_setprio 1
	s_waitcnt lgkmcnt(7)
	v_mfma_f32_16x16x32_bf16 v[74:77], v[10:13], v[66:69], v[126:129]
	s_waitcnt lgkmcnt(6)
	v_mfma_f32_16x16x32_bf16 v[138:141], v[14:17], v[82:85], v[74:77]
	v_mfma_f32_16x16x32_bf16 v[74:77], v[180:183], v[66:69], v[122:125]
	v_mfma_f32_16x16x32_bf16 v[122:125], v[184:187], v[82:85], v[74:77]
	s_waitcnt lgkmcnt(5)
	v_mfma_f32_16x16x32_bf16 v[74:77], v[10:13], v[188:191], v[118:121]
	s_waitcnt lgkmcnt(4)
	v_mfma_f32_16x16x32_bf16 v[110:113], v[14:17], v[192:195], v[74:77]
	v_mfma_f32_16x16x32_bf16 v[74:77], v[180:183], v[188:191], v[114:117]
	v_mfma_f32_16x16x32_bf16 v[106:109], v[184:187], v[192:195], v[74:77]
	s_waitcnt lgkmcnt(3)
	v_mfma_f32_16x16x32_bf16 v[74:77], v[10:13], v[196:199], v[130:133]
	s_waitcnt lgkmcnt(2)
	v_mfma_f32_16x16x32_bf16 v[94:97], v[14:17], v[200:203], v[74:77]
	v_mfma_f32_16x16x32_bf16 v[74:77], v[180:183], v[196:199], v[160:163]
	v_mfma_f32_16x16x32_bf16 v[90:93], v[184:187], v[200:203], v[74:77]
	s_waitcnt lgkmcnt(1)
	v_mfma_f32_16x16x32_bf16 v[74:77], v[10:13], v[232:235], v[102:105]
	s_waitcnt lgkmcnt(0)
	v_mfma_f32_16x16x32_bf16 v[78:81], v[14:17], v[236:239], v[74:77]
	v_mfma_f32_16x16x32_bf16 v[74:77], v[180:183], v[232:235], v[98:101]
	v_mfma_f32_16x16x32_bf16 v[74:77], v[184:187], v[236:239], v[74:77]
	s_setprio 0
	s_barrier
	ds_read_b128 v[126:129], v151 offset:49152
	ds_read_b128 v[130:133], v151 offset:50176
	ds_read_b128 v[160:163], v151 offset:51200
	ds_read_b128 v[148:151], v151 offset:52224
	s_waitcnt vmcnt(0)
	s_barrier
	s_waitcnt lgkmcnt(0)
	s_setprio 1
	s_waitcnt lgkmcnt(3)
	v_mfma_f32_16x16x32_bf16 v[98:101], v[126:129], v[66:69], v[222:225]
	s_waitcnt lgkmcnt(1)
	v_mfma_f32_16x16x32_bf16 v[66:69], v[160:163], v[66:69], v[164:167]
	s_waitcnt lgkmcnt(0)
	v_mfma_f32_16x16x32_bf16 v[114:117], v[148:151], v[82:85], v[66:69]
	v_mfma_f32_16x16x32_bf16 v[66:69], v[126:129], v[188:191], v[86:89]
	v_mfma_f32_16x16x32_bf16 v[102:105], v[130:133], v[192:195], v[66:69]
	v_mfma_f32_16x16x32_bf16 v[66:69], v[160:163], v[188:191], v[70:73]
	v_mfma_f32_16x16x32_bf16 v[62:65], v[126:129], v[196:199], v[62:65]
	v_mfma_f32_16x16x32_bf16 v[58:61], v[160:163], v[196:199], v[58:61]
	v_mfma_f32_16x16x32_bf16 v[54:57], v[126:129], v[232:235], v[54:57]
	v_mfma_f32_16x16x32_bf16 v[50:53], v[160:163], v[232:235], v[50:53]
	v_mfma_f32_16x16x32_bf16 v[118:121], v[130:133], v[82:85], v[98:101]
	v_mfma_f32_16x16x32_bf16 v[98:101], v[148:151], v[192:195], v[66:69]
	v_mfma_f32_16x16x32_bf16 v[86:89], v[130:133], v[200:203], v[62:65]
	v_mfma_f32_16x16x32_bf16 v[82:85], v[148:151], v[200:203], v[58:61]
	v_mfma_f32_16x16x32_bf16 v[70:73], v[130:133], v[236:239], v[54:57]
	v_mfma_f32_16x16x32_bf16 v[66:69], v[148:151], v[236:239], v[50:53]
	s_setprio 0
	s_barrier
	s_nop 0
	ds_read_b128 v[50:53], v0 offset:49152
	ds_read_b128 v[164:167], v0 offset:50176
	ds_read_b128 v[188:191], v0 offset:51200
	ds_read_b128 v[192:195], v0 offset:52224
	ds_read_b128 v[196:199], v0 offset:53248
	ds_read_b128 v[200:203], v0 offset:54272
	ds_read_b128 v[222:225], v0 offset:55296
	ds_read_b128 v[232:235], v0 offset:56320
	s_barrier
	s_waitcnt lgkmcnt(0)
	s_setprio 1
	s_waitcnt lgkmcnt(7)
	v_mfma_f32_16x16x32_bf16 v[46:49], v[10:13], v[50:53], v[46:49]
	s_waitcnt lgkmcnt(5)
	v_mfma_f32_16x16x32_bf16 v[38:41], v[10:13], v[188:191], v[38:41]
	s_waitcnt lgkmcnt(3)
	v_mfma_f32_16x16x32_bf16 v[30:33], v[10:13], v[196:199], v[30:33]
	s_waitcnt lgkmcnt(1)
	v_mfma_f32_16x16x32_bf16 v[10:13], v[10:13], v[222:225], v[22:25]
	v_mfma_f32_16x16x32_bf16 v[62:65], v[14:17], v[164:167], v[46:49]
	v_mfma_f32_16x16x32_bf16 v[42:45], v[180:183], v[50:53], v[42:45]
	v_mfma_f32_16x16x32_bf16 v[46:49], v[14:17], v[192:195], v[38:41]
	v_mfma_f32_16x16x32_bf16 v[34:37], v[180:183], v[188:191], v[34:37]
	v_mfma_f32_16x16x32_bf16 v[30:33], v[14:17], v[200:203], v[30:33]
	v_mfma_f32_16x16x32_bf16 v[26:29], v[180:183], v[196:199], v[26:29]
	s_waitcnt lgkmcnt(0)
	v_mfma_f32_16x16x32_bf16 v[14:17], v[14:17], v[232:235], v[10:13]
	v_mfma_f32_16x16x32_bf16 v[10:13], v[180:183], v[222:225], v[18:21]
	v_mfma_f32_16x16x32_bf16 v[58:61], v[184:187], v[164:167], v[42:45]
	v_mfma_f32_16x16x32_bf16 v[42:45], v[184:187], v[192:195], v[34:37]
	v_mfma_f32_16x16x32_bf16 v[26:29], v[184:187], v[200:203], v[26:29]
	v_mfma_f32_16x16x32_bf16 v[10:13], v[184:187], v[232:235], v[10:13]
	s_setprio 0
	s_setprio 1
	v_mfma_f32_16x16x32_bf16 v[2:5], v[160:163], v[188:191], v[2:5]
	v_mfma_f32_16x16x32_bf16 v[18:21], v[126:129], v[50:53], v[134:137]
	v_mfma_f32_16x16x32_bf16 v[34:37], v[148:151], v[192:195], v[2:5]
	v_mfma_f32_16x16x32_bf16 v[2:5], v[126:129], v[196:199], v[156:159]
	v_mfma_f32_16x16x32_bf16 v[54:57], v[130:133], v[164:167], v[18:21]
	v_mfma_f32_16x16x32_bf16 v[18:21], v[160:163], v[50:53], v[152:155]
	v_mfma_f32_16x16x32_bf16 v[22:25], v[130:133], v[200:203], v[2:5]
	v_mfma_f32_16x16x32_bf16 v[2:5], v[160:163], v[196:199], v[168:171]
	v_mfma_f32_16x16x32_bf16 v[50:53], v[148:151], v[164:167], v[18:21]
	v_mfma_f32_16x16x32_bf16 v[6:9], v[126:129], v[188:191], v[6:9]
	v_mfma_f32_16x16x32_bf16 v[18:21], v[148:151], v[200:203], v[2:5]
	v_mfma_f32_16x16x32_bf16 v[2:5], v[126:129], v[222:225], v[172:175]
	v_mfma_f32_16x16x32_bf16 v[38:41], v[130:133], v[192:195], v[6:9]
	v_mfma_f32_16x16x32_bf16 v[6:9], v[130:133], v[232:235], v[2:5]
	v_mfma_f32_16x16x32_bf16 v[2:5], v[160:163], v[222:225], v[176:179]
	v_mfma_f32_16x16x32_bf16 v[2:5], v[148:151], v[232:235], v[2:5]
	s_setprio 0
	s_movk_i32 s0, 0x100
	v_cmp_gt_u32_e32 vcc, s0, v142
	s_barrier
	s_and_saveexec_b64 s[0:1], vcc
	s_cbranch_execz .LBB0_37
	s_barrier

.LBB0_85:
	ds_read_b128 v[164:167], v151
	ds_read_b128 v[168:171], v151 offset:1024
	ds_read_b128 v[172:175], v151 offset:2048
	ds_read_b128 v[176:179], v151 offset:3072
	v_lshl_add_u64 v[204:205], v[138:139], 0, s[10:11]
	v_lshl_add_u64 v[228:229], v[204:205], 0, s[60:61]
	s_add_i32 m0, s1, 0xc000
	ds_read_b128 v[180:183], v0
	ds_read_b128 v[184:187], v0 offset:1024
	ds_read_b128 v[188:191], v0 offset:2048
	ds_read_b128 v[192:195], v0 offset:3072
	ds_read_b128 v[196:199], v0 offset:4096
	ds_read_b128 v[200:203], v0 offset:5120
	ds_read_b128 v[222:225], v0 offset:6144
	ds_read_b128 v[232:235], v0 offset:7168
	global_load_lds_dwordx4 v[228:229], off
	v_lshl_add_u64 v[210:211], v[140:141], 0, s[10:11]
	s_add_i32 m0, s1, 0xe000
	v_lshl_add_u64 v[152:153], v[210:211], 0, s[60:61]
	global_load_lds_dwordx4 v[152:153], off
	s_waitcnt lgkmcnt(8)
	s_barrier
	s_waitcnt lgkmcnt(0)
	v_mfma_f32_16x16x32_bf16 v[126:129], v[164:167], v[180:183], v[126:129]
	v_mfma_f32_16x16x32_bf16 v[122:125], v[172:175], v[180:183], v[122:125]
	v_mfma_f32_16x16x32_bf16 v[118:121], v[164:167], v[188:191], v[118:121]
	v_mfma_f32_16x16x32_bf16 v[114:117], v[172:175], v[188:191], v[114:117]
	v_mfma_f32_16x16x32_bf16 v[110:113], v[164:167], v[196:199], v[110:113]
	v_mfma_f32_16x16x32_bf16 v[106:109], v[172:175], v[196:199], v[106:109]
	v_mfma_f32_16x16x32_bf16 v[102:105], v[164:167], v[222:225], v[102:105]
	v_mfma_f32_16x16x32_bf16 v[98:101], v[172:175], v[222:225], v[98:101]
	v_mfma_f32_16x16x32_bf16 v[126:129], v[168:171], v[184:187], v[126:129]
	v_mfma_f32_16x16x32_bf16 v[122:125], v[176:179], v[184:187], v[122:125]
	v_mfma_f32_16x16x32_bf16 v[118:121], v[168:171], v[192:195], v[118:121]
	v_mfma_f32_16x16x32_bf16 v[114:117], v[176:179], v[192:195], v[114:117]
	v_mfma_f32_16x16x32_bf16 v[110:113], v[168:171], v[200:203], v[110:113]
	v_mfma_f32_16x16x32_bf16 v[106:109], v[176:179], v[200:203], v[106:109]
	v_mfma_f32_16x16x32_bf16 v[102:105], v[168:171], v[232:235], v[102:105]
	v_mfma_f32_16x16x32_bf16 v[98:101], v[176:179], v[232:235], v[98:101]
	s_barrier
	v_lshl_add_u64 v[216:217], v[134:135], 0, s[10:11]
	s_add_i32 m0, s1, 0xff00
	ds_read_b128 v[236:239], v151 offset:16384
	ds_read_b128 v[240:243], v151 offset:17408
	ds_read_b128 v[244:247], v151 offset:18432
	ds_read_b128 v[248:251], v151 offset:19456
	global_load_lds_dwordx4 v[216:217], off offset:256
	s_add_i32 m0, s1, 0x11f00
	v_lshl_add_u64 v[218:219], v[136:137], 0, s[10:11]
	global_load_lds_dwordx4 v[218:219], off offset:256
	s_barrier
	s_waitcnt lgkmcnt(0)
	v_mfma_f32_16x16x32_bf16 v[94:97], v[236:239], v[180:183], v[94:97]
	v_mfma_f32_16x16x32_bf16 v[90:93], v[244:247], v[180:183], v[90:93]
	v_mfma_f32_16x16x32_bf16 v[86:89], v[236:239], v[188:191], v[86:89]
	v_mfma_f32_16x16x32_bf16 v[82:85], v[244:247], v[188:191], v[82:85]
	v_mfma_f32_16x16x32_bf16 v[78:81], v[236:239], v[196:199], v[78:81]
	v_mfma_f32_16x16x32_bf16 v[74:77], v[244:247], v[196:199], v[74:77]
	v_mfma_f32_16x16x32_bf16 v[70:73], v[236:239], v[222:225], v[70:73]
	v_mfma_f32_16x16x32_bf16 v[66:69], v[244:247], v[222:225], v[66:69]
	v_mfma_f32_16x16x32_bf16 v[94:97], v[240:243], v[184:187], v[94:97]
	v_mfma_f32_16x16x32_bf16 v[90:93], v[248:251], v[184:187], v[90:93]
	v_mfma_f32_16x16x32_bf16 v[86:89], v[240:243], v[192:195], v[86:89]
	v_mfma_f32_16x16x32_bf16 v[82:85], v[248:251], v[192:195], v[82:85]
	v_mfma_f32_16x16x32_bf16 v[78:81], v[240:243], v[200:203], v[78:81]
	v_mfma_f32_16x16x32_bf16 v[74:77], v[248:251], v[200:203], v[74:77]
	v_mfma_f32_16x16x32_bf16 v[70:73], v[240:243], v[232:235], v[70:73]
	v_mfma_f32_16x16x32_bf16 v[66:69], v[248:251], v[232:235], v[66:69]
	v_lshl_add_u64 v[158:159], v[204:205], 0, s[74:75]
	s_mov_b32 m0, s1
	s_barrier
	ds_read_b128 v[180:183], v0 offset:16384
	ds_read_b128 v[184:187], v0 offset:17408
	ds_read_b128 v[188:191], v0 offset:18432
	ds_read_b128 v[192:195], v0 offset:19456
	ds_read_b128 v[196:199], v0 offset:20480
	ds_read_b128 v[200:203], v0 offset:21504
	ds_read_b128 v[222:225], v0 offset:22528
	ds_read_b128 v[232:235], v0 offset:23552
	global_load_lds_dwordx4 v[158:159], off
	s_add_i32 m0, s1, 0x1f00
	s_nop 0
	global_load_lds_dwordx4 v[210:211], off offset:256
	s_barrier
	s_waitcnt lgkmcnt(0)
	v_mfma_f32_16x16x32_bf16 v[62:65], v[164:167], v[180:183], v[62:65]
	v_mfma_f32_16x16x32_bf16 v[58:61], v[172:175], v[180:183], v[58:61]
	v_mfma_f32_16x16x32_bf16 v[54:57], v[164:167], v[188:191], v[54:57]
	v_mfma_f32_16x16x32_bf16 v[50:53], v[172:175], v[188:191], v[50:53]
	v_mfma_f32_16x16x32_bf16 v[46:49], v[164:167], v[196:199], v[46:49]
	v_mfma_f32_16x16x32_bf16 v[42:45], v[172:175], v[196:199], v[42:45]
	v_mfma_f32_16x16x32_bf16 v[38:41], v[164:167], v[222:225], v[38:41]
	v_mfma_f32_16x16x32_bf16 v[34:37], v[172:175], v[222:225], v[34:37]
	v_mfma_f32_16x16x32_bf16 v[62:65], v[168:171], v[184:187], v[62:65]
	v_mfma_f32_16x16x32_bf16 v[58:61], v[176:179], v[184:187], v[58:61]
	v_mfma_f32_16x16x32_bf16 v[54:57], v[168:171], v[192:195], v[54:57]
	v_mfma_f32_16x16x32_bf16 v[50:53], v[176:179], v[192:195], v[50:53]
	v_mfma_f32_16x16x32_bf16 v[46:49], v[168:171], v[200:203], v[46:49]
	v_mfma_f32_16x16x32_bf16 v[42:45], v[176:179], v[200:203], v[42:45]
	v_mfma_f32_16x16x32_bf16 v[38:41], v[168:171], v[232:235], v[38:41]
	v_mfma_f32_16x16x32_bf16 v[34:37], v[176:179], v[232:235], v[34:37]
	s_barrier
	s_add_i32 m0, s1, 0x14000
	v_lshl_add_u64 v[154:155], v[216:217], 0, s[18:19]
	global_load_lds_dwordx4 v[154:155], off
	s_add_i32 m0, s1, 0x16000
	v_lshl_add_u64 v[156:157], v[218:219], 0, s[18:19]
	global_load_lds_dwordx4 v[156:157], off
	s_waitcnt vmcnt(6)
	s_barrier
	v_mfma_f32_16x16x32_bf16 v[30:33], v[236:239], v[180:183], v[30:33]
	v_mfma_f32_16x16x32_bf16 v[26:29], v[244:247], v[180:183], v[26:29]
	v_mfma_f32_16x16x32_bf16 v[22:25], v[236:239], v[188:191], v[22:25]
	v_mfma_f32_16x16x32_bf16 v[18:21], v[244:247], v[188:191], v[18:21]
	v_mfma_f32_16x16x32_bf16 v[14:17], v[236:239], v[196:199], v[14:17]
	v_mfma_f32_16x16x32_bf16 v[10:13], v[244:247], v[196:199], v[10:13]
	v_mfma_f32_16x16x32_bf16 v[6:9], v[236:239], v[222:225], v[6:9]
	v_mfma_f32_16x16x32_bf16 v[2:5], v[244:247], v[222:225], v[2:5]
	v_mfma_f32_16x16x32_bf16 v[30:33], v[240:243], v[184:187], v[30:33]
	v_mfma_f32_16x16x32_bf16 v[26:29], v[248:251], v[184:187], v[26:29]
	v_mfma_f32_16x16x32_bf16 v[22:25], v[240:243], v[192:195], v[22:25]
	v_mfma_f32_16x16x32_bf16 v[18:21], v[248:251], v[192:195], v[18:21]
	v_mfma_f32_16x16x32_bf16 v[14:17], v[240:243], v[200:203], v[14:17]
	v_mfma_f32_16x16x32_bf16 v[10:13], v[248:251], v[200:203], v[10:13]
	v_mfma_f32_16x16x32_bf16 v[6:9], v[240:243], v[232:235], v[6:9]
	v_mfma_f32_16x16x32_bf16 v[2:5], v[248:251], v[232:235], v[2:5]
	s_barrier
	ds_read_b128 v[164:167], v151 offset:32768
	ds_read_b128 v[168:171], v151 offset:33792
	ds_read_b128 v[172:175], v151 offset:34816
	ds_read_b128 v[176:179], v151 offset:35840
	s_add_i32 m0, s1, 0x3f80
	ds_read_b128 v[180:183], v0 offset:32768
	ds_read_b128 v[184:187], v0 offset:33792
	ds_read_b128 v[188:191], v0 offset:34816
	ds_read_b128 v[192:195], v0 offset:35840
	ds_read_b128 v[196:199], v0 offset:36864
	ds_read_b128 v[200:203], v0 offset:37888
	ds_read_b128 v[222:225], v0 offset:38912
	ds_read_b128 v[232:235], v0 offset:39936
	global_load_lds_dwordx4 v[228:229], off offset:128
	s_add_i32 m0, s1, 0x5f80
	s_nop 0
	global_load_lds_dwordx4 v[152:153], off offset:128
	s_waitcnt lgkmcnt(8)
	s_barrier
	s_waitcnt lgkmcnt(0)
	v_mfma_f32_16x16x32_bf16 v[126:129], v[164:167], v[180:183], v[126:129]
	v_mfma_f32_16x16x32_bf16 v[122:125], v[172:175], v[180:183], v[122:125]
	v_mfma_f32_16x16x32_bf16 v[118:121], v[164:167], v[188:191], v[118:121]
	v_mfma_f32_16x16x32_bf16 v[114:117], v[172:175], v[188:191], v[114:117]
	v_mfma_f32_16x16x32_bf16 v[110:113], v[164:167], v[196:199], v[110:113]
	v_mfma_f32_16x16x32_bf16 v[106:109], v[172:175], v[196:199], v[106:109]
	v_mfma_f32_16x16x32_bf16 v[102:105], v[164:167], v[222:225], v[102:105]
	v_mfma_f32_16x16x32_bf16 v[98:101], v[172:175], v[222:225], v[98:101]
	v_mfma_f32_16x16x32_bf16 v[126:129], v[168:171], v[184:187], v[126:129]
	v_mfma_f32_16x16x32_bf16 v[122:125], v[176:179], v[184:187], v[122:125]
	v_mfma_f32_16x16x32_bf16 v[118:121], v[168:171], v[192:195], v[118:121]
	v_mfma_f32_16x16x32_bf16 v[114:117], v[176:179], v[192:195], v[114:117]
	v_mfma_f32_16x16x32_bf16 v[110:113], v[168:171], v[200:203], v[110:113]
	v_mfma_f32_16x16x32_bf16 v[106:109], v[176:179], v[200:203], v[106:109]
	v_mfma_f32_16x16x32_bf16 v[102:105], v[168:171], v[232:235], v[102:105]
	v_mfma_f32_16x16x32_bf16 v[98:101], v[176:179], v[232:235], v[98:101]
	s_barrier
	s_add_i32 m0, s1, 0x17e80
	ds_read_b128 v[236:239], v151 offset:49152
	ds_read_b128 v[240:243], v151 offset:50176
	ds_read_b128 v[244:247], v151 offset:51200
	ds_read_b128 v[248:251], v151 offset:52224
	global_load_lds_dwordx4 v[216:217], off offset:384
	s_add_i32 m0, s1, 0x19e80
	s_nop 0
	global_load_lds_dwordx4 v[218:219], off offset:384
	s_barrier
	s_waitcnt lgkmcnt(0)
	v_mfma_f32_16x16x32_bf16 v[94:97], v[236:239], v[180:183], v[94:97]
	v_mfma_f32_16x16x32_bf16 v[90:93], v[244:247], v[180:183], v[90:93]
	v_mfma_f32_16x16x32_bf16 v[86:89], v[236:239], v[188:191], v[86:89]
	v_mfma_f32_16x16x32_bf16 v[82:85], v[244:247], v[188:191], v[82:85]
	v_mfma_f32_16x16x32_bf16 v[78:81], v[236:239], v[196:199], v[78:81]
	v_mfma_f32_16x16x32_bf16 v[74:77], v[244:247], v[196:199], v[74:77]
	v_mfma_f32_16x16x32_bf16 v[70:73], v[236:239], v[222:225], v[70:73]
	v_mfma_f32_16x16x32_bf16 v[66:69], v[244:247], v[222:225], v[66:69]
	v_mfma_f32_16x16x32_bf16 v[94:97], v[240:243], v[184:187], v[94:97]
	v_mfma_f32_16x16x32_bf16 v[90:93], v[248:251], v[184:187], v[90:93]
	v_mfma_f32_16x16x32_bf16 v[86:89], v[240:243], v[192:195], v[86:89]
	v_mfma_f32_16x16x32_bf16 v[82:85], v[248:251], v[192:195], v[82:85]
	v_mfma_f32_16x16x32_bf16 v[78:81], v[240:243], v[200:203], v[78:81]
	v_mfma_f32_16x16x32_bf16 v[74:77], v[248:251], v[200:203], v[74:77]
	v_mfma_f32_16x16x32_bf16 v[70:73], v[240:243], v[232:235], v[70:73]
	v_mfma_f32_16x16x32_bf16 v[66:69], v[248:251], v[232:235], v[66:69]
	s_add_i32 m0, s1, 0x7e80
	s_barrier
	ds_read_b128 v[180:183], v0 offset:49152
	ds_read_b128 v[184:187], v0 offset:50176
	ds_read_b128 v[188:191], v0 offset:51200
	ds_read_b128 v[192:195], v0 offset:52224
	ds_read_b128 v[196:199], v0 offset:53248
	ds_read_b128 v[200:203], v0 offset:54272
	ds_read_b128 v[222:225], v0 offset:55296
	ds_read_b128 v[232:235], v0 offset:56320
	global_load_lds_dwordx4 v[204:205], off offset:384
	s_add_i32 m0, s1, 0x9e80
	s_nop 0
	global_load_lds_dwordx4 v[210:211], off offset:384
	s_barrier
	s_waitcnt lgkmcnt(0)
	v_mfma_f32_16x16x32_bf16 v[62:65], v[164:167], v[180:183], v[62:65]
	v_mfma_f32_16x16x32_bf16 v[58:61], v[172:175], v[180:183], v[58:61]
	v_mfma_f32_16x16x32_bf16 v[54:57], v[164:167], v[188:191], v[54:57]
	v_mfma_f32_16x16x32_bf16 v[50:53], v[172:175], v[188:191], v[50:53]
	v_mfma_f32_16x16x32_bf16 v[46:49], v[164:167], v[196:199], v[46:49]
	v_mfma_f32_16x16x32_bf16 v[42:45], v[172:175], v[196:199], v[42:45]
	v_mfma_f32_16x16x32_bf16 v[38:41], v[164:167], v[222:225], v[38:41]
	v_mfma_f32_16x16x32_bf16 v[34:37], v[172:175], v[222:225], v[34:37]
	v_mfma_f32_16x16x32_bf16 v[62:65], v[168:171], v[184:187], v[62:65]
	v_mfma_f32_16x16x32_bf16 v[58:61], v[176:179], v[184:187], v[58:61]
	v_mfma_f32_16x16x32_bf16 v[54:57], v[168:171], v[192:195], v[54:57]
	v_mfma_f32_16x16x32_bf16 v[50:53], v[176:179], v[192:195], v[50:53]
	v_mfma_f32_16x16x32_bf16 v[46:49], v[168:171], v[200:203], v[46:49]
	v_mfma_f32_16x16x32_bf16 v[42:45], v[176:179], v[200:203], v[42:45]
	v_mfma_f32_16x16x32_bf16 v[38:41], v[168:171], v[232:235], v[38:41]
	v_mfma_f32_16x16x32_bf16 v[34:37], v[176:179], v[232:235], v[34:37]
	s_barrier
	s_add_i32 m0, s1, 0x1bf80
	s_nop 0
	global_load_lds_dwordx4 v[154:155], off offset:128
	s_add_i32 m0, s1, 0x1df80
	s_nop 0
	global_load_lds_dwordx4 v[156:157], off offset:128
	s_waitcnt vmcnt(6)
	s_barrier
	v_mfma_f32_16x16x32_bf16 v[30:33], v[236:239], v[180:183], v[30:33]
	v_mfma_f32_16x16x32_bf16 v[26:29], v[244:247], v[180:183], v[26:29]
	v_mfma_f32_16x16x32_bf16 v[22:25], v[236:239], v[188:191], v[22:25]
	v_mfma_f32_16x16x32_bf16 v[18:21], v[244:247], v[188:191], v[18:21]
	v_mfma_f32_16x16x32_bf16 v[14:17], v[236:239], v[196:199], v[14:17]
	v_mfma_f32_16x16x32_bf16 v[10:13], v[244:247], v[196:199], v[10:13]
	v_mfma_f32_16x16x32_bf16 v[6:9], v[236:239], v[222:225], v[6:9]
	v_mfma_f32_16x16x32_bf16 v[2:5], v[244:247], v[222:225], v[2:5]
	v_mfma_f32_16x16x32_bf16 v[30:33], v[240:243], v[184:187], v[30:33]
	v_mfma_f32_16x16x32_bf16 v[26:29], v[248:251], v[184:187], v[26:29]
	v_mfma_f32_16x16x32_bf16 v[22:25], v[240:243], v[192:195], v[22:25]
	v_mfma_f32_16x16x32_bf16 v[18:21], v[248:251], v[192:195], v[18:21]
	v_mfma_f32_16x16x32_bf16 v[14:17], v[240:243], v[200:203], v[14:17]
	v_mfma_f32_16x16x32_bf16 v[10:13], v[248:251], v[200:203], v[10:13]
	v_mfma_f32_16x16x32_bf16 v[6:9], v[240:243], v[232:235], v[6:9]
	v_mfma_f32_16x16x32_bf16 v[2:5], v[248:251], v[232:235], v[2:5]
	s_add_i32 s0, s0, 2
	s_add_u32 s10, s10, 0x100
	s_addc_u32 s11, s11, 0
	s_cmp_lt_u32 s0, 28
	s_barrier
	s_cbranch_scc1 .LBB0_85
	s_add_i32 s1, s1, 0x1e000
	s_mov_b64 s[10:11], 0xf80
	v_readfirstlane_b32 s0, v162
	v_lshl_add_u64 v[132:133], v[132:133], 0, s[10:11]
	s_mov_b32 m0, s0
	v_readfirstlane_b32 s0, v163
	ds_read_b128 v[134:137], v151
	ds_read_b128 v[138:141], v151 offset:1024
	ds_read_b128 v[152:155], v151 offset:2048
	ds_read_b128 v[156:159], v151 offset:3072
	ds_read_b128 v[164:167], v0
	ds_read_b128 v[168:171], v0 offset:1024
	ds_read_b128 v[172:175], v0 offset:2048
	ds_read_b128 v[176:179], v0 offset:3072
	ds_read_b128 v[180:183], v0 offset:4096
	ds_read_b128 v[184:187], v0 offset:5120
	ds_read_b128 v[188:191], v0 offset:6144
	ds_read_b128 v[192:195], v0 offset:7168
	global_load_lds_dwordx4 v[132:133], off
	v_lshl_add_u64 v[130:131], v[130:131], 0, s[10:11]
	s_mov_b32 m0, s0
	s_nop 0
	global_load_lds_dwordx4 v[130:131], off
	s_barrier
	s_waitcnt lgkmcnt(0)
	s_setprio 1
	s_waitcnt lgkmcnt(0)
	v_mfma_f32_16x16x32_bf16 v[126:129], v[134:137], v[164:167], v[126:129]
	v_mfma_f32_16x16x32_bf16 v[122:125], v[152:155], v[164:167], v[122:125]
	v_mfma_f32_16x16x32_bf16 v[114:117], v[152:155], v[172:175], v[114:117]
	v_mfma_f32_16x16x32_bf16 v[106:109], v[152:155], v[180:183], v[106:109]
	v_mfma_f32_16x16x32_bf16 v[98:101], v[152:155], v[188:191], v[98:101]
	v_mfma_f32_16x16x32_bf16 v[126:129], v[138:141], v[168:171], v[126:129]
	v_mfma_f32_16x16x32_bf16 v[122:125], v[156:159], v[168:171], v[122:125]
	v_mfma_f32_16x16x32_bf16 v[118:121], v[134:137], v[172:175], v[118:121]
	v_mfma_f32_16x16x32_bf16 v[114:117], v[156:159], v[176:179], v[114:117]
	v_mfma_f32_16x16x32_bf16 v[110:113], v[134:137], v[180:183], v[110:113]
	v_mfma_f32_16x16x32_bf16 v[106:109], v[156:159], v[184:187], v[106:109]
	v_mfma_f32_16x16x32_bf16 v[102:105], v[134:137], v[188:191], v[102:105]
	v_mfma_f32_16x16x32_bf16 v[98:101], v[156:159], v[192:195], v[98:101]
	v_mfma_f32_16x16x32_bf16 v[130:133], v[138:141], v[176:179], v[118:121]
	v_mfma_f32_16x16x32_bf16 v[160:163], v[138:141], v[184:187], v[110:113]
	v_mfma_f32_16x16x32_bf16 v[196:199], v[138:141], v[192:195], v[102:105]
	s_setprio 0
	s_barrier
	s_nop 0
	ds_read_b128 v[102:105], v151 offset:16384
	ds_read_b128 v[110:113], v151 offset:17408
	ds_read_b128 v[118:121], v151 offset:18432
	ds_read_b128 v[200:203], v151 offset:19456
	s_barrier
	s_waitcnt lgkmcnt(0)
	s_setprio 1
	s_waitcnt lgkmcnt(1)
	v_mfma_f32_16x16x32_bf16 v[90:93], v[118:121], v[164:167], v[90:93]
	v_mfma_f32_16x16x32_bf16 v[86:89], v[102:105], v[172:175], v[86:89]
	v_mfma_f32_16x16x32_bf16 v[82:85], v[118:121], v[172:175], v[82:85]
	v_mfma_f32_16x16x32_bf16 v[78:81], v[102:105], v[180:183], v[78:81]
	v_mfma_f32_16x16x32_bf16 v[70:73], v[102:105], v[188:191], v[70:73]
	v_mfma_f32_16x16x32_bf16 v[94:97], v[102:105], v[164:167], v[94:97]
	s_waitcnt lgkmcnt(0)
	v_mfma_f32_16x16x32_bf16 v[90:93], v[200:203], v[168:171], v[90:93]
	v_mfma_f32_16x16x32_bf16 v[86:89], v[110:113], v[176:179], v[86:89]
	v_mfma_f32_16x16x32_bf16 v[82:85], v[200:203], v[176:179], v[82:85]
	v_mfma_f32_16x16x32_bf16 v[78:81], v[110:113], v[184:187], v[78:81]
	v_mfma_f32_16x16x32_bf16 v[74:77], v[118:121], v[180:183], v[74:77]
	v_mfma_f32_16x16x32_bf16 v[70:73], v[110:113], v[192:195], v[70:73]
	v_mfma_f32_16x16x32_bf16 v[66:69], v[118:121], v[188:191], v[66:69]
	v_mfma_f32_16x16x32_bf16 v[222:225], v[110:113], v[168:171], v[94:97]
	v_mfma_f32_16x16x32_bf16 v[164:167], v[200:203], v[184:187], v[74:77]
	v_mfma_f32_16x16x32_bf16 v[168:171], v[200:203], v[192:195], v[66:69]
	s_setprio 0
	s_barrier
	s_nop 2
	ds_read_b128 v[66:69], v0 offset:16384
	ds_read_b128 v[74:77], v0 offset:17408
	ds_read_b128 v[94:97], v0 offset:18432
	ds_read_b128 v[172:175], v0 offset:19456
	ds_read_b128 v[176:179], v0 offset:20480
	ds_read_b128 v[180:183], v0 offset:21504
	ds_read_b128 v[184:187], v0 offset:22528
	ds_read_b128 v[188:191], v0 offset:23552
	s_waitcnt vmcnt(4)
	s_barrier
	s_waitcnt lgkmcnt(0)
	s_setprio 1
	s_waitcnt lgkmcnt(5)
	v_mfma_f32_16x16x32_bf16 v[54:57], v[134:137], v[94:97], v[54:57]
	v_mfma_f32_16x16x32_bf16 v[50:53], v[152:155], v[94:97], v[50:53]
	v_mfma_f32_16x16x32_bf16 v[62:65], v[134:137], v[66:69], v[62:65]
	v_mfma_f32_16x16x32_bf16 v[58:61], v[152:155], v[66:69], v[58:61]
	s_waitcnt lgkmcnt(4)
	v_mfma_f32_16x16x32_bf16 v[54:57], v[138:141], v[172:175], v[54:57]
	v_mfma_f32_16x16x32_bf16 v[50:53], v[156:159], v[172:175], v[50:53]
	s_waitcnt lgkmcnt(3)
	v_mfma_f32_16x16x32_bf16 v[46:49], v[134:137], v[176:179], v[46:49]
	v_mfma_f32_16x16x32_bf16 v[42:45], v[152:155], v[176:179], v[42:45]
	s_waitcnt lgkmcnt(1)
	v_mfma_f32_16x16x32_bf16 v[38:41], v[134:137], v[184:187], v[38:41]
	v_mfma_f32_16x16x32_bf16 v[34:37], v[152:155], v[184:187], v[34:37]
	v_mfma_f32_16x16x32_bf16 v[192:195], v[138:141], v[74:77], v[62:65]
	v_mfma_f32_16x16x32_bf16 v[232:235], v[156:159], v[74:77], v[58:61]
	v_mfma_f32_16x16x32_bf16 v[236:239], v[138:141], v[180:183], v[46:49]
	v_mfma_f32_16x16x32_bf16 v[240:243], v[156:159], v[180:183], v[42:45]
	s_waitcnt lgkmcnt(0)
	v_mfma_f32_16x16x32_bf16 v[134:137], v[138:141], v[188:191], v[38:41]
	v_mfma_f32_16x16x32_bf16 v[138:141], v[156:159], v[188:191], v[34:37]
	s_setprio 0
	s_setprio 1
	v_mfma_f32_16x16x32_bf16 v[30:33], v[102:105], v[66:69], v[30:33]
	v_mfma_f32_16x16x32_bf16 v[26:29], v[118:121], v[66:69], v[26:29]
	v_mfma_f32_16x16x32_bf16 v[14:17], v[102:105], v[176:179], v[14:17]
	v_mfma_f32_16x16x32_bf16 v[10:13], v[118:121], v[176:179], v[10:13]
	v_mfma_f32_16x16x32_bf16 v[30:33], v[110:113], v[74:77], v[30:33]
	v_mfma_f32_16x16x32_bf16 v[26:29], v[200:203], v[74:77], v[26:29]
	v_mfma_f32_16x16x32_bf16 v[22:25], v[102:105], v[94:97], v[22:25]
	v_mfma_f32_16x16x32_bf16 v[18:21], v[118:121], v[94:97], v[18:21]
	v_mfma_f32_16x16x32_bf16 v[14:17], v[110:113], v[180:183], v[14:17]
	v_mfma_f32_16x16x32_bf16 v[10:13], v[200:203], v[180:183], v[10:13]
	v_mfma_f32_16x16x32_bf16 v[6:9], v[102:105], v[184:187], v[6:9]
	v_mfma_f32_16x16x32_bf16 v[2:5], v[118:121], v[184:187], v[2:5]
	v_mfma_f32_16x16x32_bf16 v[152:155], v[110:113], v[172:175], v[22:25]
	v_mfma_f32_16x16x32_bf16 v[156:159], v[200:203], v[172:175], v[18:21]
	v_mfma_f32_16x16x32_bf16 v[172:175], v[110:113], v[188:191], v[6:9]
	v_mfma_f32_16x16x32_bf16 v[176:179], v[200:203], v[188:191], v[2:5]
	s_setprio 0
	s_barrier
	s_nop 1
	ds_read_b128 v[2:5], v151 offset:32768
	ds_read_b128 v[6:9], v151 offset:33792
	ds_read_b128 v[180:183], v151 offset:34816
	ds_read_b128 v[184:187], v151 offset:35840
	ds_read_b128 v[18:21], v0 offset:32768
	ds_read_b128 v[22:25], v0 offset:33792
	ds_read_b128 v[38:41], v0 offset:34816
	ds_read_b128 v[46:49], v0 offset:35840
	ds_read_b128 v[58:61], v0 offset:36864
	ds_read_b128 v[66:69], v0 offset:37888
	ds_read_b128 v[188:191], v0 offset:38912
	ds_read_b128 v[200:203], v0 offset:39936
	s_waitcnt vmcnt(2)
	s_barrier
	s_waitcnt lgkmcnt(0)
	s_setprio 1
	s_waitcnt lgkmcnt(7)
	v_mfma_f32_16x16x32_bf16 v[34:37], v[2:5], v[18:21], v[126:129]
	s_waitcnt lgkmcnt(6)
	v_mfma_f32_16x16x32_bf16 v[118:121], v[6:9], v[22:25], v[34:37]
	v_mfma_f32_16x16x32_bf16 v[34:37], v[180:183], v[18:21], v[122:125]
	v_mfma_f32_16x16x32_bf16 v[110:113], v[184:187], v[22:25], v[34:37]
	s_waitcnt lgkmcnt(5)
	v_mfma_f32_16x16x32_bf16 v[34:37], v[2:5], v[38:41], v[130:133]
	s_waitcnt lgkmcnt(4)
	v_mfma_f32_16x16x32_bf16 v[102:105], v[6:9], v[46:49], v[34:37]
	v_mfma_f32_16x16x32_bf16 v[34:37], v[180:183], v[38:41], v[114:117]
	v_mfma_f32_16x16x32_bf16 v[94:97], v[184:187], v[46:49], v[34:37]
	s_waitcnt lgkmcnt(3)
	v_mfma_f32_16x16x32_bf16 v[34:37], v[2:5], v[58:61], v[160:163]
	s_waitcnt lgkmcnt(2)
	v_mfma_f32_16x16x32_bf16 v[74:77], v[6:9], v[66:69], v[34:37]
	v_mfma_f32_16x16x32_bf16 v[34:37], v[180:183], v[58:61], v[106:109]
	v_mfma_f32_16x16x32_bf16 v[62:65], v[184:187], v[66:69], v[34:37]
	s_waitcnt lgkmcnt(1)
	v_mfma_f32_16x16x32_bf16 v[34:37], v[2:5], v[188:191], v[196:199]
	s_waitcnt lgkmcnt(0)
	v_mfma_f32_16x16x32_bf16 v[42:45], v[6:9], v[200:203], v[34:37]
	v_mfma_f32_16x16x32_bf16 v[34:37], v[180:183], v[188:191], v[98:101]
	v_mfma_f32_16x16x32_bf16 v[34:37], v[184:187], v[200:203], v[34:37]
	s_setprio 0
	s_barrier
	ds_read_b128 v[130:133], v151 offset:49152
	ds_read_b128 v[160:163], v151 offset:50176
	ds_read_b128 v[196:199], v151 offset:51200
	ds_read_b128 v[148:151], v151 offset:52224
	s_waitcnt vmcnt(0)
	s_barrier
	s_waitcnt lgkmcnt(0)
	s_setprio 1
	s_waitcnt lgkmcnt(3)
	v_mfma_f32_16x16x32_bf16 v[98:101], v[130:133], v[18:21], v[222:225]
	s_waitcnt lgkmcnt(1)
	v_mfma_f32_16x16x32_bf16 v[18:21], v[196:199], v[18:21], v[90:93]
	s_waitcnt lgkmcnt(0)
	v_mfma_f32_16x16x32_bf16 v[122:125], v[148:151], v[22:25], v[18:21]
	v_mfma_f32_16x16x32_bf16 v[18:21], v[130:133], v[38:41], v[86:89]
	v_mfma_f32_16x16x32_bf16 v[114:117], v[160:163], v[46:49], v[18:21]
	v_mfma_f32_16x16x32_bf16 v[18:21], v[196:199], v[38:41], v[82:85]
	v_mfma_f32_16x16x32_bf16 v[106:109], v[148:151], v[46:49], v[18:21]
	v_mfma_f32_16x16x32_bf16 v[18:21], v[130:133], v[58:61], v[78:81]
	v_mfma_f32_16x16x32_bf16 v[126:129], v[160:163], v[22:25], v[98:101]
	v_mfma_f32_16x16x32_bf16 v[98:101], v[160:163], v[66:69], v[18:21]
	v_mfma_f32_16x16x32_bf16 v[18:21], v[196:199], v[58:61], v[164:167]
	v_mfma_f32_16x16x32_bf16 v[90:93], v[148:151], v[66:69], v[18:21]
	v_mfma_f32_16x16x32_bf16 v[18:21], v[130:133], v[188:191], v[70:73]
	v_mfma_f32_16x16x32_bf16 v[66:69], v[160:163], v[200:203], v[18:21]
	v_mfma_f32_16x16x32_bf16 v[18:21], v[196:199], v[188:191], v[168:171]
	v_mfma_f32_16x16x32_bf16 v[58:61], v[148:151], v[200:203], v[18:21]
	s_setprio 0
	s_barrier
	ds_read_b128 v[82:85], v0 offset:49152
	ds_read_b128 v[164:167], v0 offset:50176
	ds_read_b128 v[168:171], v0 offset:51200
	ds_read_b128 v[188:191], v0 offset:52224
	ds_read_b128 v[200:203], v0 offset:53248
	ds_read_b128 v[222:225], v0 offset:54272
	ds_read_b128 v[244:247], v0 offset:55296
	ds_read_b128 v[248:251], v0 offset:56320
	s_barrier
	s_waitcnt lgkmcnt(0)
	s_setprio 1
	s_waitcnt lgkmcnt(7)
	v_mfma_f32_16x16x32_bf16 v[18:21], v[2:5], v[82:85], v[192:195]
	s_waitcnt lgkmcnt(6)
	v_mfma_f32_16x16x32_bf16 v[78:81], v[6:9], v[164:167], v[18:21]
	v_mfma_f32_16x16x32_bf16 v[18:21], v[180:183], v[82:85], v[232:235]
	v_mfma_f32_16x16x32_bf16 v[70:73], v[184:187], v[164:167], v[18:21]
	s_waitcnt lgkmcnt(5)
	v_mfma_f32_16x16x32_bf16 v[18:21], v[2:5], v[168:171], v[54:57]
	s_waitcnt lgkmcnt(4)
	v_mfma_f32_16x16x32_bf16 v[46:49], v[6:9], v[188:191], v[18:21]
	v_mfma_f32_16x16x32_bf16 v[18:21], v[180:183], v[168:171], v[50:53]
	v_mfma_f32_16x16x32_bf16 v[38:41], v[184:187], v[188:191], v[18:21]
	s_waitcnt lgkmcnt(3)
	v_mfma_f32_16x16x32_bf16 v[18:21], v[2:5], v[200:203], v[236:239]
	s_waitcnt lgkmcnt(1)
	v_mfma_f32_16x16x32_bf16 v[2:5], v[2:5], v[244:247], v[134:137]
	v_mfma_f32_16x16x32_bf16 v[22:25], v[6:9], v[222:225], v[18:21]
	v_mfma_f32_16x16x32_bf16 v[18:21], v[180:183], v[200:203], v[240:243]
	s_waitcnt lgkmcnt(0)
	v_mfma_f32_16x16x32_bf16 v[6:9], v[6:9], v[248:251], v[2:5]
	v_mfma_f32_16x16x32_bf16 v[2:5], v[180:183], v[244:247], v[138:141]
	v_mfma_f32_16x16x32_bf16 v[18:21], v[184:187], v[222:225], v[18:21]
	v_mfma_f32_16x16x32_bf16 v[2:5], v[184:187], v[248:251], v[2:5]
	s_setprio 0
	s_setprio 1
	v_mfma_f32_16x16x32_bf16 v[26:29], v[196:199], v[82:85], v[26:29]
	v_mfma_f32_16x16x32_bf16 v[30:33], v[130:133], v[82:85], v[30:33]
	v_mfma_f32_16x16x32_bf16 v[82:85], v[148:151], v[164:167], v[26:29]
	v_mfma_f32_16x16x32_bf16 v[26:29], v[130:133], v[168:171], v[152:155]
	v_mfma_f32_16x16x32_bf16 v[54:57], v[160:163], v[188:191], v[26:29]
	v_mfma_f32_16x16x32_bf16 v[26:29], v[196:199], v[168:171], v[156:159]
	v_mfma_f32_16x16x32_bf16 v[10:13], v[196:199], v[200:203], v[10:13]
	v_mfma_f32_16x16x32_bf16 v[50:53], v[148:151], v[188:191], v[26:29]
	v_mfma_f32_16x16x32_bf16 v[14:17], v[130:133], v[200:203], v[14:17]
	v_mfma_f32_16x16x32_bf16 v[26:29], v[148:151], v[222:225], v[10:13]
	v_mfma_f32_16x16x32_bf16 v[10:13], v[130:133], v[244:247], v[172:175]
	v_mfma_f32_16x16x32_bf16 v[86:89], v[160:163], v[164:167], v[30:33]
	v_mfma_f32_16x16x32_bf16 v[30:33], v[160:163], v[222:225], v[14:17]
	v_mfma_f32_16x16x32_bf16 v[14:17], v[160:163], v[248:251], v[10:13]
	v_mfma_f32_16x16x32_bf16 v[10:13], v[196:199], v[244:247], v[176:179]
	v_mfma_f32_16x16x32_bf16 v[10:13], v[148:151], v[248:251], v[10:13]
	s_setprio 0
	s_movk_i32 s0, 0x100
	v_cmp_gt_u32_e32 vcc, s0, v142
	s_barrier
	s_and_saveexec_b64 s[0:1], vcc
	s_cbranch_execz .LBB0_81
	s_barrier
	s_branch .LBB0_81

.LBB0_108:
	ds_read_b128 v[104:107], v99
	ds_read_b128 v[108:111], v99 offset:1024
	ds_read_b128 v[112:115], v99 offset:2048
	ds_read_b128 v[116:119], v99 offset:3072
	v_lshl_add_u64 v[152:153], v[74:75], 0, s[10:11]
	v_lshl_add_u64 v[164:165], v[152:153], 0, s[60:61]
	s_add_i32 m0, s1, 0xc000
	ds_read_b128 v[120:123], v0
	ds_read_b128 v[124:127], v0 offset:1024
	ds_read_b128 v[128:131], v0 offset:2048
	ds_read_b128 v[132:135], v0 offset:3072
	ds_read_b128 v[136:139], v0 offset:4096
	ds_read_b128 v[140:143], v0 offset:5120
	ds_read_b128 v[144:147], v0 offset:6144
	ds_read_b128 v[148:151], v0 offset:7168
	global_load_lds_dwordx4 v[164:165], off
	v_lshl_add_u64 v[154:155], v[76:77], 0, s[10:11]
	s_add_i32 m0, s1, 0xe000
	v_lshl_add_u64 v[88:89], v[154:155], 0, s[60:61]
	global_load_lds_dwordx4 v[88:89], off
	s_waitcnt lgkmcnt(8)
	s_barrier
	s_waitcnt lgkmcnt(0)
	v_mfma_f32_16x16x32_bf16 v[62:65], v[104:107], v[120:123], v[62:65]
	v_mfma_f32_16x16x32_bf16 v[58:61], v[112:115], v[120:123], v[58:61]
	v_mfma_f32_16x16x32_bf16 v[54:57], v[104:107], v[128:131], v[54:57]
	v_mfma_f32_16x16x32_bf16 v[50:53], v[112:115], v[128:131], v[50:53]
	v_mfma_f32_16x16x32_bf16 v[46:49], v[104:107], v[136:139], v[46:49]
	v_mfma_f32_16x16x32_bf16 v[42:45], v[112:115], v[136:139], v[42:45]
	v_mfma_f32_16x16x32_bf16 v[38:41], v[104:107], v[144:147], v[38:41]
	v_mfma_f32_16x16x32_bf16 v[34:37], v[112:115], v[144:147], v[34:37]
	v_mfma_f32_16x16x32_bf16 v[62:65], v[108:111], v[124:127], v[62:65]
	v_mfma_f32_16x16x32_bf16 v[58:61], v[116:119], v[124:127], v[58:61]
	v_mfma_f32_16x16x32_bf16 v[54:57], v[108:111], v[132:135], v[54:57]
	v_mfma_f32_16x16x32_bf16 v[50:53], v[116:119], v[132:135], v[50:53]
	v_mfma_f32_16x16x32_bf16 v[46:49], v[108:111], v[140:143], v[46:49]
	v_mfma_f32_16x16x32_bf16 v[42:45], v[116:119], v[140:143], v[42:45]
	v_mfma_f32_16x16x32_bf16 v[38:41], v[108:111], v[148:151], v[38:41]
	v_mfma_f32_16x16x32_bf16 v[34:37], v[116:119], v[148:151], v[34:37]
	s_barrier
	v_lshl_add_u64 v[156:157], v[70:71], 0, s[10:11]
	s_add_i32 m0, s1, 0xff00
	s_nop 0
	global_load_lds_dwordx4 v[156:157], off offset:256
	s_add_i32 m0, s1, 0x11f00
	v_lshl_add_u64 v[158:159], v[72:73], 0, s[10:11]
	global_load_lds_dwordx4 v[158:159], off offset:256
	v_lshl_add_u64 v[90:91], v[152:153], 0, s[74:75]
	s_mov_b32 m0, s1
	s_barrier
	s_waitcnt lgkmcnt(0)
	s_barrier
	ds_read_b128 v[120:123], v0 offset:16384
	ds_read_b128 v[124:127], v0 offset:17408
	ds_read_b128 v[128:131], v0 offset:18432
	ds_read_b128 v[132:135], v0 offset:19456
	ds_read_b128 v[136:139], v0 offset:20480
	ds_read_b128 v[140:143], v0 offset:21504
	ds_read_b128 v[144:147], v0 offset:22528
	ds_read_b128 v[148:151], v0 offset:23552
	global_load_lds_dwordx4 v[90:91], off
	s_add_i32 m0, s1, 0x1f00
	s_nop 0
	global_load_lds_dwordx4 v[154:155], off offset:256
	s_barrier
	s_waitcnt lgkmcnt(0)
	v_mfma_f32_16x16x32_bf16 v[2:5], v[104:107], v[120:123], v[2:5]
	v_mfma_f32_16x16x32_bf16 v[6:9], v[112:115], v[120:123], v[6:9]
	v_mfma_f32_16x16x32_bf16 v[10:13], v[104:107], v[128:131], v[10:13]
	v_mfma_f32_16x16x32_bf16 v[14:17], v[112:115], v[128:131], v[14:17]
	v_mfma_f32_16x16x32_bf16 v[18:21], v[104:107], v[136:139], v[18:21]
	v_mfma_f32_16x16x32_bf16 v[22:25], v[112:115], v[136:139], v[22:25]
	v_mfma_f32_16x16x32_bf16 v[26:29], v[104:107], v[144:147], v[26:29]
	v_mfma_f32_16x16x32_bf16 v[30:33], v[112:115], v[144:147], v[30:33]
	v_mfma_f32_16x16x32_bf16 v[2:5], v[108:111], v[124:127], v[2:5]
	v_mfma_f32_16x16x32_bf16 v[6:9], v[116:119], v[124:127], v[6:9]
	v_mfma_f32_16x16x32_bf16 v[10:13], v[108:111], v[132:135], v[10:13]
	v_mfma_f32_16x16x32_bf16 v[14:17], v[116:119], v[132:135], v[14:17]
	v_mfma_f32_16x16x32_bf16 v[18:21], v[108:111], v[140:143], v[18:21]
	v_mfma_f32_16x16x32_bf16 v[22:25], v[116:119], v[140:143], v[22:25]
	v_mfma_f32_16x16x32_bf16 v[26:29], v[108:111], v[148:151], v[26:29]
	v_mfma_f32_16x16x32_bf16 v[30:33], v[116:119], v[148:151], v[30:33]
	s_barrier
	v_lshl_add_u64 v[160:161], v[78:79], 0, s[10:11]
	s_add_i32 m0, s1, 0x13f00
	s_nop 0
	global_load_lds_dwordx4 v[160:161], off offset:256
	s_add_i32 m0, s1, 0x15f00
	v_lshl_add_u64 v[162:163], v[80:81], 0, s[10:11]
	global_load_lds_dwordx4 v[162:163], off offset:256
	s_waitcnt vmcnt(6)
	s_barrier
	s_barrier
	ds_read_b128 v[104:107], v99 offset:32768
	ds_read_b128 v[108:111], v99 offset:33792
	ds_read_b128 v[112:115], v99 offset:34816
	ds_read_b128 v[116:119], v99 offset:35840
	s_add_i32 m0, s1, 0x3f80
	ds_read_b128 v[120:123], v0 offset:32768
	ds_read_b128 v[124:127], v0 offset:33792
	ds_read_b128 v[128:131], v0 offset:34816
	ds_read_b128 v[132:135], v0 offset:35840
	ds_read_b128 v[136:139], v0 offset:36864
	ds_read_b128 v[140:143], v0 offset:37888
	ds_read_b128 v[144:147], v0 offset:38912
	ds_read_b128 v[148:151], v0 offset:39936
	global_load_lds_dwordx4 v[164:165], off offset:128
	s_add_i32 m0, s1, 0x5f80
	s_nop 0
	global_load_lds_dwordx4 v[88:89], off offset:128
	s_waitcnt lgkmcnt(8)
	s_barrier
	s_waitcnt lgkmcnt(0)
	v_mfma_f32_16x16x32_bf16 v[62:65], v[104:107], v[120:123], v[62:65]
	v_mfma_f32_16x16x32_bf16 v[58:61], v[112:115], v[120:123], v[58:61]
	v_mfma_f32_16x16x32_bf16 v[54:57], v[104:107], v[128:131], v[54:57]
	v_mfma_f32_16x16x32_bf16 v[50:53], v[112:115], v[128:131], v[50:53]
	v_mfma_f32_16x16x32_bf16 v[46:49], v[104:107], v[136:139], v[46:49]
	v_mfma_f32_16x16x32_bf16 v[42:45], v[112:115], v[136:139], v[42:45]
	v_mfma_f32_16x16x32_bf16 v[38:41], v[104:107], v[144:147], v[38:41]
	v_mfma_f32_16x16x32_bf16 v[34:37], v[112:115], v[144:147], v[34:37]
	v_mfma_f32_16x16x32_bf16 v[62:65], v[108:111], v[124:127], v[62:65]
	v_mfma_f32_16x16x32_bf16 v[58:61], v[116:119], v[124:127], v[58:61]
	v_mfma_f32_16x16x32_bf16 v[54:57], v[108:111], v[132:135], v[54:57]
	v_mfma_f32_16x16x32_bf16 v[50:53], v[116:119], v[132:135], v[50:53]
	v_mfma_f32_16x16x32_bf16 v[46:49], v[108:111], v[140:143], v[46:49]
	v_mfma_f32_16x16x32_bf16 v[42:45], v[116:119], v[140:143], v[42:45]
	v_mfma_f32_16x16x32_bf16 v[38:41], v[108:111], v[148:151], v[38:41]
	v_mfma_f32_16x16x32_bf16 v[34:37], v[116:119], v[148:151], v[34:37]
	s_barrier
	s_add_i32 m0, s1, 0x17e80
	s_nop 0
	global_load_lds_dwordx4 v[156:157], off offset:384
	s_add_i32 m0, s1, 0x19e80
	s_nop 0
	global_load_lds_dwordx4 v[158:159], off offset:384
	s_add_i32 m0, s1, 0x7e80
	s_barrier
	s_waitcnt lgkmcnt(0)
	s_barrier
	ds_read_b128 v[120:123], v0 offset:49152
	ds_read_b128 v[124:127], v0 offset:50176
	ds_read_b128 v[128:131], v0 offset:51200
	ds_read_b128 v[132:135], v0 offset:52224
	ds_read_b128 v[136:139], v0 offset:53248
	ds_read_b128 v[140:143], v0 offset:54272
	ds_read_b128 v[144:147], v0 offset:55296
	ds_read_b128 v[148:151], v0 offset:56320
	global_load_lds_dwordx4 v[152:153], off offset:384
	s_add_i32 m0, s1, 0x9e80
	s_nop 0
	global_load_lds_dwordx4 v[154:155], off offset:384
	s_barrier
	s_waitcnt lgkmcnt(0)
	v_mfma_f32_16x16x32_bf16 v[2:5], v[104:107], v[120:123], v[2:5]
	v_mfma_f32_16x16x32_bf16 v[6:9], v[112:115], v[120:123], v[6:9]
	v_mfma_f32_16x16x32_bf16 v[10:13], v[104:107], v[128:131], v[10:13]
	v_mfma_f32_16x16x32_bf16 v[14:17], v[112:115], v[128:131], v[14:17]
	v_mfma_f32_16x16x32_bf16 v[18:21], v[104:107], v[136:139], v[18:21]
	v_mfma_f32_16x16x32_bf16 v[22:25], v[112:115], v[136:139], v[22:25]
	v_mfma_f32_16x16x32_bf16 v[26:29], v[104:107], v[144:147], v[26:29]
	v_mfma_f32_16x16x32_bf16 v[30:33], v[112:115], v[144:147], v[30:33]
	v_mfma_f32_16x16x32_bf16 v[2:5], v[108:111], v[124:127], v[2:5]
	v_mfma_f32_16x16x32_bf16 v[6:9], v[116:119], v[124:127], v[6:9]
	v_mfma_f32_16x16x32_bf16 v[10:13], v[108:111], v[132:135], v[10:13]
	v_mfma_f32_16x16x32_bf16 v[14:17], v[116:119], v[132:135], v[14:17]
	v_mfma_f32_16x16x32_bf16 v[18:21], v[108:111], v[140:143], v[18:21]
	v_mfma_f32_16x16x32_bf16 v[22:25], v[116:119], v[140:143], v[22:25]
	v_mfma_f32_16x16x32_bf16 v[26:29], v[108:111], v[148:151], v[26:29]
	v_mfma_f32_16x16x32_bf16 v[30:33], v[116:119], v[148:151], v[30:33]
	s_barrier
	s_add_i32 m0, s1, 0x1be80
	s_nop 0
	global_load_lds_dwordx4 v[160:161], off offset:384
	s_add_i32 m0, s1, 0x1de80
	s_add_i32 s0, s0, 2
	global_load_lds_dwordx4 v[162:163], off offset:384
	s_waitcnt vmcnt(6)
	s_add_u32 s10, s10, 0x100
	s_addc_u32 s11, s11, 0
	s_cmp_lt_u32 s0, 28
	s_barrier
	s_barrier
	s_cbranch_scc1 .LBB0_108
	s_add_i32 s1, s1, 0x1e000
	s_mov_b64 s[10:11], 0xf80
	v_readfirstlane_b32 s0, v102
	v_lshl_add_u64 v[68:69], v[68:69], 0, s[10:11]
	s_mov_b32 m0, s0
	v_readfirstlane_b32 s0, v103
	ds_read_b128 v[70:73], v99
	ds_read_b128 v[74:77], v99 offset:1024
	ds_read_b128 v[78:81], v99 offset:2048
	ds_read_b128 v[88:91], v99 offset:3072
	ds_read_b128 v[92:95], v0
	ds_read_b128 v[104:107], v0 offset:1024
	ds_read_b128 v[108:111], v0 offset:2048
	ds_read_b128 v[112:115], v0 offset:3072
	ds_read_b128 v[116:119], v0 offset:4096
	ds_read_b128 v[120:123], v0 offset:5120
	ds_read_b128 v[124:127], v0 offset:6144
	ds_read_b128 v[128:131], v0 offset:7168
	global_load_lds_dwordx4 v[68:69], off
	v_lshl_add_u64 v[66:67], v[66:67], 0, s[10:11]
	s_mov_b32 m0, s0
	s_nop 0
	global_load_lds_dwordx4 v[66:67], off
	s_barrier
	s_waitcnt lgkmcnt(0)
	s_setprio 1
	s_waitcnt lgkmcnt(0)
	v_mfma_f32_16x16x32_bf16 v[62:65], v[70:73], v[92:95], v[62:65]
	v_mfma_f32_16x16x32_bf16 v[58:61], v[78:81], v[92:95], v[58:61]
	v_mfma_f32_16x16x32_bf16 v[54:57], v[70:73], v[108:111], v[54:57]
	v_mfma_f32_16x16x32_bf16 v[50:53], v[78:81], v[108:111], v[50:53]
	v_mfma_f32_16x16x32_bf16 v[46:49], v[70:73], v[116:119], v[46:49]
	v_mfma_f32_16x16x32_bf16 v[42:45], v[78:81], v[116:119], v[42:45]
	v_mfma_f32_16x16x32_bf16 v[38:41], v[70:73], v[124:127], v[38:41]
	v_mfma_f32_16x16x32_bf16 v[34:37], v[78:81], v[124:127], v[34:37]
	v_mfma_f32_16x16x32_bf16 v[62:65], v[74:77], v[104:107], v[62:65]
	v_mfma_f32_16x16x32_bf16 v[58:61], v[88:91], v[104:107], v[58:61]
	v_mfma_f32_16x16x32_bf16 v[54:57], v[74:77], v[112:115], v[54:57]
	v_mfma_f32_16x16x32_bf16 v[50:53], v[88:91], v[112:115], v[50:53]
	v_mfma_f32_16x16x32_bf16 v[46:49], v[74:77], v[120:123], v[46:49]
	v_mfma_f32_16x16x32_bf16 v[42:45], v[88:91], v[120:123], v[42:45]
	v_mfma_f32_16x16x32_bf16 v[38:41], v[74:77], v[128:131], v[38:41]
	v_mfma_f32_16x16x32_bf16 v[34:37], v[88:91], v[128:131], v[34:37]
	s_setprio 0
	s_barrier
	s_barrier
	s_waitcnt lgkmcnt(0)
	s_barrier
	ds_read_b128 v[66:69], v0 offset:16384
	ds_read_b128 v[92:95], v0 offset:17408
	ds_read_b128 v[100:103], v0 offset:18432
	ds_read_b128 v[104:107], v0 offset:19456
	ds_read_b128 v[108:111], v0 offset:20480
	ds_read_b128 v[112:115], v0 offset:21504
	ds_read_b128 v[116:119], v0 offset:22528
	ds_read_b128 v[120:123], v0 offset:23552
	s_waitcnt vmcnt(4)
	s_barrier
	s_waitcnt lgkmcnt(0)
	s_setprio 1
	s_waitcnt lgkmcnt(3)
	v_mfma_f32_16x16x32_bf16 v[18:21], v[70:73], v[108:111], v[18:21]
	v_mfma_f32_16x16x32_bf16 v[2:5], v[70:73], v[66:69], v[2:5]
	v_mfma_f32_16x16x32_bf16 v[6:9], v[78:81], v[66:69], v[6:9]
	s_waitcnt lgkmcnt(2)
	v_mfma_f32_16x16x32_bf16 v[66:69], v[74:77], v[112:115], v[18:21]
	v_mfma_f32_16x16x32_bf16 v[18:21], v[78:81], v[108:111], v[22:25]
	v_mfma_f32_16x16x32_bf16 v[2:5], v[74:77], v[92:95], v[2:5]
	v_mfma_f32_16x16x32_bf16 v[6:9], v[88:91], v[92:95], v[6:9]
	v_mfma_f32_16x16x32_bf16 v[10:13], v[70:73], v[100:103], v[10:13]
	v_mfma_f32_16x16x32_bf16 v[14:17], v[78:81], v[100:103], v[14:17]
	v_mfma_f32_16x16x32_bf16 v[92:95], v[88:91], v[112:115], v[18:21]
	s_waitcnt lgkmcnt(1)
	v_mfma_f32_16x16x32_bf16 v[18:21], v[70:73], v[116:119], v[26:29]
	v_mfma_f32_16x16x32_bf16 v[10:13], v[74:77], v[104:107], v[10:13]
	v_mfma_f32_16x16x32_bf16 v[14:17], v[88:91], v[104:107], v[14:17]
	s_waitcnt lgkmcnt(0)
	v_mfma_f32_16x16x32_bf16 v[70:73], v[74:77], v[120:123], v[18:21]
	v_mfma_f32_16x16x32_bf16 v[18:21], v[78:81], v[116:119], v[30:33]
	v_mfma_f32_16x16x32_bf16 v[74:77], v[88:91], v[120:123], v[18:21]
	s_setprio 0
	s_barrier
	ds_read_b128 v[78:81], v99 offset:32768
	ds_read_b128 v[88:91], v99 offset:33792
	ds_read_b128 v[100:103], v99 offset:34816
	ds_read_b128 v[96:99], v99 offset:35840
	s_nop 0
	ds_read_b128 v[18:21], v0 offset:32768
	ds_read_b128 v[22:25], v0 offset:33792
	ds_read_b128 v[26:29], v0 offset:34816
	ds_read_b128 v[30:33], v0 offset:35840
	ds_read_b128 v[104:107], v0 offset:36864
	ds_read_b128 v[108:111], v0 offset:37888
	ds_read_b128 v[112:115], v0 offset:38912
	ds_read_b128 v[116:119], v0 offset:39936
	s_waitcnt vmcnt(2)
	s_barrier
	s_waitcnt lgkmcnt(0)
	s_setprio 1
	s_waitcnt lgkmcnt(7)
	v_mfma_f32_16x16x32_bf16 v[62:65], v[78:81], v[18:21], v[62:65]
	v_mfma_f32_16x16x32_bf16 v[18:21], v[100:103], v[18:21], v[58:61]
	s_waitcnt lgkmcnt(6)
	v_mfma_f32_16x16x32_bf16 v[58:61], v[96:99], v[22:25], v[18:21]
	s_waitcnt lgkmcnt(5)
	v_mfma_f32_16x16x32_bf16 v[18:21], v[78:81], v[26:29], v[54:57]
	s_waitcnt lgkmcnt(4)
	v_mfma_f32_16x16x32_bf16 v[54:57], v[88:91], v[30:33], v[18:21]
	v_mfma_f32_16x16x32_bf16 v[18:21], v[100:103], v[26:29], v[50:53]
	v_mfma_f32_16x16x32_bf16 v[50:53], v[96:99], v[30:33], v[18:21]
	s_waitcnt lgkmcnt(3)
	v_mfma_f32_16x16x32_bf16 v[18:21], v[78:81], v[104:107], v[46:49]
	s_waitcnt lgkmcnt(2)
	v_mfma_f32_16x16x32_bf16 v[46:49], v[88:91], v[108:111], v[18:21]
	v_mfma_f32_16x16x32_bf16 v[18:21], v[100:103], v[104:107], v[42:45]
	v_mfma_f32_16x16x32_bf16 v[42:45], v[96:99], v[108:111], v[18:21]
	s_waitcnt lgkmcnt(1)
	v_mfma_f32_16x16x32_bf16 v[18:21], v[78:81], v[112:115], v[38:41]
	s_waitcnt lgkmcnt(0)
	v_mfma_f32_16x16x32_bf16 v[38:41], v[88:91], v[116:119], v[18:21]
	v_mfma_f32_16x16x32_bf16 v[18:21], v[100:103], v[112:115], v[34:37]
	v_mfma_f32_16x16x32_bf16 v[62:65], v[88:91], v[22:25], v[62:65]
	v_mfma_f32_16x16x32_bf16 v[34:37], v[96:99], v[116:119], v[18:21]
	s_setprio 0
	s_barrier
	s_waitcnt vmcnt(0)
	s_barrier
	s_waitcnt lgkmcnt(0)
	s_barrier
	s_nop 1
	ds_read_b128 v[18:21], v0 offset:49152
	ds_read_b128 v[22:25], v0 offset:50176
	ds_read_b128 v[104:107], v0 offset:51200
	ds_read_b128 v[108:111], v0 offset:52224
	ds_read_b128 v[112:115], v0 offset:53248
	ds_read_b128 v[116:119], v0 offset:54272
	ds_read_b128 v[120:123], v0 offset:55296
	ds_read_b128 v[124:127], v0 offset:56320
	s_barrier
	s_waitcnt lgkmcnt(0)
	s_setprio 1
	s_waitcnt lgkmcnt(7)
	v_mfma_f32_16x16x32_bf16 v[2:5], v[78:81], v[18:21], v[2:5]
	s_waitcnt lgkmcnt(6)
	v_mfma_f32_16x16x32_bf16 v[30:33], v[88:91], v[22:25], v[2:5]
	v_mfma_f32_16x16x32_bf16 v[2:5], v[100:103], v[18:21], v[6:9]
	v_mfma_f32_16x16x32_bf16 v[26:29], v[96:99], v[22:25], v[2:5]
	s_waitcnt lgkmcnt(5)
	v_mfma_f32_16x16x32_bf16 v[2:5], v[78:81], v[104:107], v[10:13]
	s_waitcnt lgkmcnt(4)
	v_mfma_f32_16x16x32_bf16 v[22:25], v[88:91], v[108:111], v[2:5]
	v_mfma_f32_16x16x32_bf16 v[2:5], v[100:103], v[104:107], v[14:17]
	v_mfma_f32_16x16x32_bf16 v[18:21], v[96:99], v[108:111], v[2:5]
	s_waitcnt lgkmcnt(3)
	v_mfma_f32_16x16x32_bf16 v[2:5], v[78:81], v[112:115], v[66:69]
	s_waitcnt lgkmcnt(2)
	v_mfma_f32_16x16x32_bf16 v[14:17], v[88:91], v[116:119], v[2:5]
	v_mfma_f32_16x16x32_bf16 v[2:5], v[100:103], v[112:115], v[92:95]
	v_mfma_f32_16x16x32_bf16 v[10:13], v[96:99], v[116:119], v[2:5]
	s_waitcnt lgkmcnt(1)
	v_mfma_f32_16x16x32_bf16 v[2:5], v[78:81], v[120:123], v[70:73]
	s_waitcnt lgkmcnt(0)
	v_mfma_f32_16x16x32_bf16 v[6:9], v[88:91], v[124:127], v[2:5]
	v_mfma_f32_16x16x32_bf16 v[2:5], v[100:103], v[120:123], v[74:77]
	v_mfma_f32_16x16x32_bf16 v[2:5], v[96:99], v[124:127], v[2:5]
	s_setprio 0
	s_movk_i32 s0, 0x100
	v_cmp_gt_u32_e32 vcc, s0, v82
	s_barrier
	s_and_saveexec_b64 s[0:1], vcc
	s_cbranch_execz .LBB0_111
	s_barrier

.LBB0_180:
	ds_read_b128 v[164:167], v151
	ds_read_b128 v[168:171], v151 offset:1024
	ds_read_b128 v[172:175], v151 offset:2048
	ds_read_b128 v[176:179], v151 offset:3072
	v_lshl_add_u64 v[204:205], v[138:139], 0, s[12:13]
	v_lshl_add_u64 v[228:229], v[204:205], 0, s[60:61]
	s_add_i32 m0, s1, 0xc000
	ds_read_b128 v[180:183], v0
	ds_read_b128 v[184:187], v0 offset:1024
	ds_read_b128 v[188:191], v0 offset:2048
	ds_read_b128 v[192:195], v0 offset:3072
	ds_read_b128 v[196:199], v0 offset:4096
	ds_read_b128 v[200:203], v0 offset:5120
	ds_read_b128 v[222:225], v0 offset:6144
	ds_read_b128 v[232:235], v0 offset:7168
	global_load_lds_dwordx4 v[228:229], off
	v_lshl_add_u64 v[210:211], v[140:141], 0, s[12:13]
	s_add_i32 m0, s1, 0xe000
	v_lshl_add_u64 v[152:153], v[210:211], 0, s[60:61]
	global_load_lds_dwordx4 v[152:153], off
	s_waitcnt lgkmcnt(8)
	s_barrier
	s_waitcnt lgkmcnt(0)
	v_mfma_f32_16x16x32_bf16 v[126:129], v[164:167], v[180:183], v[126:129]
	v_mfma_f32_16x16x32_bf16 v[122:125], v[172:175], v[180:183], v[122:125]
	v_mfma_f32_16x16x32_bf16 v[118:121], v[164:167], v[188:191], v[118:121]
	v_mfma_f32_16x16x32_bf16 v[114:117], v[172:175], v[188:191], v[114:117]
	v_mfma_f32_16x16x32_bf16 v[110:113], v[164:167], v[196:199], v[110:113]
	v_mfma_f32_16x16x32_bf16 v[106:109], v[172:175], v[196:199], v[106:109]
	v_mfma_f32_16x16x32_bf16 v[102:105], v[164:167], v[222:225], v[102:105]
	v_mfma_f32_16x16x32_bf16 v[98:101], v[172:175], v[222:225], v[98:101]
	v_mfma_f32_16x16x32_bf16 v[126:129], v[168:171], v[184:187], v[126:129]
	v_mfma_f32_16x16x32_bf16 v[122:125], v[176:179], v[184:187], v[122:125]
	v_mfma_f32_16x16x32_bf16 v[118:121], v[168:171], v[192:195], v[118:121]
	v_mfma_f32_16x16x32_bf16 v[114:117], v[176:179], v[192:195], v[114:117]
	v_mfma_f32_16x16x32_bf16 v[110:113], v[168:171], v[200:203], v[110:113]
	v_mfma_f32_16x16x32_bf16 v[106:109], v[176:179], v[200:203], v[106:109]
	v_mfma_f32_16x16x32_bf16 v[102:105], v[168:171], v[232:235], v[102:105]
	v_mfma_f32_16x16x32_bf16 v[98:101], v[176:179], v[232:235], v[98:101]
	s_barrier
	v_lshl_add_u64 v[216:217], v[134:135], 0, s[12:13]
	s_add_i32 m0, s1, 0xff00
	ds_read_b128 v[236:239], v151 offset:16384
	ds_read_b128 v[240:243], v151 offset:17408
	ds_read_b128 v[244:247], v151 offset:18432
	ds_read_b128 v[248:251], v151 offset:19456
	global_load_lds_dwordx4 v[216:217], off offset:256
	s_add_i32 m0, s1, 0x11f00
	v_lshl_add_u64 v[218:219], v[136:137], 0, s[12:13]
	global_load_lds_dwordx4 v[218:219], off offset:256
	s_barrier
	s_waitcnt lgkmcnt(0)
	v_mfma_f32_16x16x32_bf16 v[94:97], v[236:239], v[180:183], v[94:97]
	v_mfma_f32_16x16x32_bf16 v[90:93], v[244:247], v[180:183], v[90:93]
	v_mfma_f32_16x16x32_bf16 v[86:89], v[236:239], v[188:191], v[86:89]
	v_mfma_f32_16x16x32_bf16 v[82:85], v[244:247], v[188:191], v[82:85]
	v_mfma_f32_16x16x32_bf16 v[78:81], v[236:239], v[196:199], v[78:81]
	v_mfma_f32_16x16x32_bf16 v[74:77], v[244:247], v[196:199], v[74:77]
	v_mfma_f32_16x16x32_bf16 v[70:73], v[236:239], v[222:225], v[70:73]
	v_mfma_f32_16x16x32_bf16 v[66:69], v[244:247], v[222:225], v[66:69]
	v_mfma_f32_16x16x32_bf16 v[94:97], v[240:243], v[184:187], v[94:97]
	v_mfma_f32_16x16x32_bf16 v[90:93], v[248:251], v[184:187], v[90:93]
	v_mfma_f32_16x16x32_bf16 v[86:89], v[240:243], v[192:195], v[86:89]
	v_mfma_f32_16x16x32_bf16 v[82:85], v[248:251], v[192:195], v[82:85]
	v_mfma_f32_16x16x32_bf16 v[78:81], v[240:243], v[200:203], v[78:81]
	v_mfma_f32_16x16x32_bf16 v[74:77], v[248:251], v[200:203], v[74:77]
	v_mfma_f32_16x16x32_bf16 v[70:73], v[240:243], v[232:235], v[70:73]
	v_mfma_f32_16x16x32_bf16 v[66:69], v[248:251], v[232:235], v[66:69]
	v_lshl_add_u64 v[158:159], v[204:205], 0, s[74:75]
	s_mov_b32 m0, s1
	s_barrier
	ds_read_b128 v[180:183], v0 offset:16384
	ds_read_b128 v[184:187], v0 offset:17408
	ds_read_b128 v[188:191], v0 offset:18432
	ds_read_b128 v[192:195], v0 offset:19456
	ds_read_b128 v[196:199], v0 offset:20480
	ds_read_b128 v[200:203], v0 offset:21504
	ds_read_b128 v[222:225], v0 offset:22528
	ds_read_b128 v[232:235], v0 offset:23552
	global_load_lds_dwordx4 v[158:159], off
	s_add_i32 m0, s1, 0x1f00
	s_nop 0
	global_load_lds_dwordx4 v[210:211], off offset:256
	s_barrier
	s_waitcnt lgkmcnt(0)
	v_mfma_f32_16x16x32_bf16 v[62:65], v[164:167], v[180:183], v[62:65]
	v_mfma_f32_16x16x32_bf16 v[58:61], v[172:175], v[180:183], v[58:61]
	v_mfma_f32_16x16x32_bf16 v[54:57], v[164:167], v[188:191], v[54:57]
	v_mfma_f32_16x16x32_bf16 v[50:53], v[172:175], v[188:191], v[50:53]
	v_mfma_f32_16x16x32_bf16 v[46:49], v[164:167], v[196:199], v[46:49]
	v_mfma_f32_16x16x32_bf16 v[42:45], v[172:175], v[196:199], v[42:45]
	v_mfma_f32_16x16x32_bf16 v[38:41], v[164:167], v[222:225], v[38:41]
	v_mfma_f32_16x16x32_bf16 v[34:37], v[172:175], v[222:225], v[34:37]
	v_mfma_f32_16x16x32_bf16 v[62:65], v[168:171], v[184:187], v[62:65]
	v_mfma_f32_16x16x32_bf16 v[58:61], v[176:179], v[184:187], v[58:61]
	v_mfma_f32_16x16x32_bf16 v[54:57], v[168:171], v[192:195], v[54:57]
	v_mfma_f32_16x16x32_bf16 v[50:53], v[176:179], v[192:195], v[50:53]
	v_mfma_f32_16x16x32_bf16 v[46:49], v[168:171], v[200:203], v[46:49]
	v_mfma_f32_16x16x32_bf16 v[42:45], v[176:179], v[200:203], v[42:45]
	v_mfma_f32_16x16x32_bf16 v[38:41], v[168:171], v[232:235], v[38:41]
	v_mfma_f32_16x16x32_bf16 v[34:37], v[176:179], v[232:235], v[34:37]
	s_barrier
	s_add_i32 m0, s1, 0x14000
	v_lshl_add_u64 v[154:155], v[216:217], 0, s[18:19]
	global_load_lds_dwordx4 v[154:155], off
	s_add_i32 m0, s1, 0x16000
	v_lshl_add_u64 v[156:157], v[218:219], 0, s[18:19]
	global_load_lds_dwordx4 v[156:157], off
	s_waitcnt vmcnt(6)
	s_barrier
	v_mfma_f32_16x16x32_bf16 v[30:33], v[236:239], v[180:183], v[30:33]
	v_mfma_f32_16x16x32_bf16 v[26:29], v[244:247], v[180:183], v[26:29]
	v_mfma_f32_16x16x32_bf16 v[22:25], v[236:239], v[188:191], v[22:25]
	v_mfma_f32_16x16x32_bf16 v[18:21], v[244:247], v[188:191], v[18:21]
	v_mfma_f32_16x16x32_bf16 v[14:17], v[236:239], v[196:199], v[14:17]
	v_mfma_f32_16x16x32_bf16 v[10:13], v[244:247], v[196:199], v[10:13]
	v_mfma_f32_16x16x32_bf16 v[6:9], v[236:239], v[222:225], v[6:9]
	v_mfma_f32_16x16x32_bf16 v[2:5], v[244:247], v[222:225], v[2:5]
	v_mfma_f32_16x16x32_bf16 v[30:33], v[240:243], v[184:187], v[30:33]
	v_mfma_f32_16x16x32_bf16 v[26:29], v[248:251], v[184:187], v[26:29]
	v_mfma_f32_16x16x32_bf16 v[22:25], v[240:243], v[192:195], v[22:25]
	v_mfma_f32_16x16x32_bf16 v[18:21], v[248:251], v[192:195], v[18:21]
	v_mfma_f32_16x16x32_bf16 v[14:17], v[240:243], v[200:203], v[14:17]
	v_mfma_f32_16x16x32_bf16 v[10:13], v[248:251], v[200:203], v[10:13]
	v_mfma_f32_16x16x32_bf16 v[6:9], v[240:243], v[232:235], v[6:9]
	v_mfma_f32_16x16x32_bf16 v[2:5], v[248:251], v[232:235], v[2:5]
	s_barrier
	ds_read_b128 v[164:167], v151 offset:32768
	ds_read_b128 v[168:171], v151 offset:33792
	ds_read_b128 v[172:175], v151 offset:34816
	ds_read_b128 v[176:179], v151 offset:35840
	s_add_i32 m0, s1, 0x3f80
	ds_read_b128 v[180:183], v0 offset:32768
	ds_read_b128 v[184:187], v0 offset:33792
	ds_read_b128 v[188:191], v0 offset:34816
	ds_read_b128 v[192:195], v0 offset:35840
	ds_read_b128 v[196:199], v0 offset:36864
	ds_read_b128 v[200:203], v0 offset:37888
	ds_read_b128 v[222:225], v0 offset:38912
	ds_read_b128 v[232:235], v0 offset:39936
	global_load_lds_dwordx4 v[228:229], off offset:128
	s_add_i32 m0, s1, 0x5f80
	s_nop 0
	global_load_lds_dwordx4 v[152:153], off offset:128
	s_waitcnt lgkmcnt(8)
	s_barrier
	s_waitcnt lgkmcnt(0)
	v_mfma_f32_16x16x32_bf16 v[126:129], v[164:167], v[180:183], v[126:129]
	v_mfma_f32_16x16x32_bf16 v[122:125], v[172:175], v[180:183], v[122:125]
	v_mfma_f32_16x16x32_bf16 v[118:121], v[164:167], v[188:191], v[118:121]
	v_mfma_f32_16x16x32_bf16 v[114:117], v[172:175], v[188:191], v[114:117]
	v_mfma_f32_16x16x32_bf16 v[110:113], v[164:167], v[196:199], v[110:113]
	v_mfma_f32_16x16x32_bf16 v[106:109], v[172:175], v[196:199], v[106:109]
	v_mfma_f32_16x16x32_bf16 v[102:105], v[164:167], v[222:225], v[102:105]
	v_mfma_f32_16x16x32_bf16 v[98:101], v[172:175], v[222:225], v[98:101]
	v_mfma_f32_16x16x32_bf16 v[126:129], v[168:171], v[184:187], v[126:129]
	v_mfma_f32_16x16x32_bf16 v[122:125], v[176:179], v[184:187], v[122:125]
	v_mfma_f32_16x16x32_bf16 v[118:121], v[168:171], v[192:195], v[118:121]
	v_mfma_f32_16x16x32_bf16 v[114:117], v[176:179], v[192:195], v[114:117]
	v_mfma_f32_16x16x32_bf16 v[110:113], v[168:171], v[200:203], v[110:113]
	v_mfma_f32_16x16x32_bf16 v[106:109], v[176:179], v[200:203], v[106:109]
	v_mfma_f32_16x16x32_bf16 v[102:105], v[168:171], v[232:235], v[102:105]
	v_mfma_f32_16x16x32_bf16 v[98:101], v[176:179], v[232:235], v[98:101]
	s_barrier
	s_add_i32 m0, s1, 0x17e80
	ds_read_b128 v[236:239], v151 offset:49152
	ds_read_b128 v[240:243], v151 offset:50176
	ds_read_b128 v[244:247], v151 offset:51200
	ds_read_b128 v[248:251], v151 offset:52224
	global_load_lds_dwordx4 v[216:217], off offset:384
	s_add_i32 m0, s1, 0x19e80
	s_nop 0
	global_load_lds_dwordx4 v[218:219], off offset:384
	s_barrier
	s_waitcnt lgkmcnt(0)
	v_mfma_f32_16x16x32_bf16 v[94:97], v[236:239], v[180:183], v[94:97]
	v_mfma_f32_16x16x32_bf16 v[90:93], v[244:247], v[180:183], v[90:93]
	v_mfma_f32_16x16x32_bf16 v[86:89], v[236:239], v[188:191], v[86:89]
	v_mfma_f32_16x16x32_bf16 v[82:85], v[244:247], v[188:191], v[82:85]
	v_mfma_f32_16x16x32_bf16 v[78:81], v[236:239], v[196:199], v[78:81]
	v_mfma_f32_16x16x32_bf16 v[74:77], v[244:247], v[196:199], v[74:77]
	v_mfma_f32_16x16x32_bf16 v[70:73], v[236:239], v[222:225], v[70:73]
	v_mfma_f32_16x16x32_bf16 v[66:69], v[244:247], v[222:225], v[66:69]
	v_mfma_f32_16x16x32_bf16 v[94:97], v[240:243], v[184:187], v[94:97]
	v_mfma_f32_16x16x32_bf16 v[90:93], v[248:251], v[184:187], v[90:93]
	v_mfma_f32_16x16x32_bf16 v[86:89], v[240:243], v[192:195], v[86:89]
	v_mfma_f32_16x16x32_bf16 v[82:85], v[248:251], v[192:195], v[82:85]
	v_mfma_f32_16x16x32_bf16 v[78:81], v[240:243], v[200:203], v[78:81]
	v_mfma_f32_16x16x32_bf16 v[74:77], v[248:251], v[200:203], v[74:77]
	v_mfma_f32_16x16x32_bf16 v[70:73], v[240:243], v[232:235], v[70:73]
	v_mfma_f32_16x16x32_bf16 v[66:69], v[248:251], v[232:235], v[66:69]
	s_add_i32 m0, s1, 0x7e80
	s_barrier
	ds_read_b128 v[180:183], v0 offset:49152
	ds_read_b128 v[184:187], v0 offset:50176
	ds_read_b128 v[188:191], v0 offset:51200
	ds_read_b128 v[192:195], v0 offset:52224
	ds_read_b128 v[196:199], v0 offset:53248
	ds_read_b128 v[200:203], v0 offset:54272
	ds_read_b128 v[222:225], v0 offset:55296
	ds_read_b128 v[232:235], v0 offset:56320
	global_load_lds_dwordx4 v[204:205], off offset:384
	s_add_i32 m0, s1, 0x9e80
	s_nop 0
	global_load_lds_dwordx4 v[210:211], off offset:384
	s_barrier
	s_waitcnt lgkmcnt(0)
	v_mfma_f32_16x16x32_bf16 v[62:65], v[164:167], v[180:183], v[62:65]
	v_mfma_f32_16x16x32_bf16 v[58:61], v[172:175], v[180:183], v[58:61]
	v_mfma_f32_16x16x32_bf16 v[54:57], v[164:167], v[188:191], v[54:57]
	v_mfma_f32_16x16x32_bf16 v[50:53], v[172:175], v[188:191], v[50:53]
	v_mfma_f32_16x16x32_bf16 v[46:49], v[164:167], v[196:199], v[46:49]
	v_mfma_f32_16x16x32_bf16 v[42:45], v[172:175], v[196:199], v[42:45]
	v_mfma_f32_16x16x32_bf16 v[38:41], v[164:167], v[222:225], v[38:41]
	v_mfma_f32_16x16x32_bf16 v[34:37], v[172:175], v[222:225], v[34:37]
	v_mfma_f32_16x16x32_bf16 v[62:65], v[168:171], v[184:187], v[62:65]
	v_mfma_f32_16x16x32_bf16 v[58:61], v[176:179], v[184:187], v[58:61]
	v_mfma_f32_16x16x32_bf16 v[54:57], v[168:171], v[192:195], v[54:57]
	v_mfma_f32_16x16x32_bf16 v[50:53], v[176:179], v[192:195], v[50:53]
	v_mfma_f32_16x16x32_bf16 v[46:49], v[168:171], v[200:203], v[46:49]
	v_mfma_f32_16x16x32_bf16 v[42:45], v[176:179], v[200:203], v[42:45]
	v_mfma_f32_16x16x32_bf16 v[38:41], v[168:171], v[232:235], v[38:41]
	v_mfma_f32_16x16x32_bf16 v[34:37], v[176:179], v[232:235], v[34:37]
	s_barrier
	s_add_i32 m0, s1, 0x1bf80
	s_nop 0
	global_load_lds_dwordx4 v[154:155], off offset:128
	s_add_i32 m0, s1, 0x1df80
	s_nop 0
	global_load_lds_dwordx4 v[156:157], off offset:128
	s_waitcnt vmcnt(6)
	s_barrier
	v_mfma_f32_16x16x32_bf16 v[30:33], v[236:239], v[180:183], v[30:33]
	v_mfma_f32_16x16x32_bf16 v[26:29], v[244:247], v[180:183], v[26:29]
	v_mfma_f32_16x16x32_bf16 v[22:25], v[236:239], v[188:191], v[22:25]
	v_mfma_f32_16x16x32_bf16 v[18:21], v[244:247], v[188:191], v[18:21]
	v_mfma_f32_16x16x32_bf16 v[14:17], v[236:239], v[196:199], v[14:17]
	v_mfma_f32_16x16x32_bf16 v[10:13], v[244:247], v[196:199], v[10:13]
	v_mfma_f32_16x16x32_bf16 v[6:9], v[236:239], v[222:225], v[6:9]
	v_mfma_f32_16x16x32_bf16 v[2:5], v[244:247], v[222:225], v[2:5]
	v_mfma_f32_16x16x32_bf16 v[30:33], v[240:243], v[184:187], v[30:33]
	v_mfma_f32_16x16x32_bf16 v[26:29], v[248:251], v[184:187], v[26:29]
	v_mfma_f32_16x16x32_bf16 v[22:25], v[240:243], v[192:195], v[22:25]
	v_mfma_f32_16x16x32_bf16 v[18:21], v[248:251], v[192:195], v[18:21]
	v_mfma_f32_16x16x32_bf16 v[14:17], v[240:243], v[200:203], v[14:17]
	v_mfma_f32_16x16x32_bf16 v[10:13], v[248:251], v[200:203], v[10:13]
	v_mfma_f32_16x16x32_bf16 v[6:9], v[240:243], v[232:235], v[6:9]
	v_mfma_f32_16x16x32_bf16 v[2:5], v[248:251], v[232:235], v[2:5]
	s_add_i32 s0, s0, 2
	s_add_u32 s12, s12, 0x100
	s_addc_u32 s13, s13, 0
	s_cmp_lt_u32 s0, 28
	s_barrier
	s_cbranch_scc1 .LBB0_180
	s_add_i32 s1, s1, 0x1e000
	s_mov_b64 s[12:13], 0xf80
	v_readfirstlane_b32 s0, v162
	v_lshl_add_u64 v[132:133], v[132:133], 0, s[12:13]
	s_mov_b32 m0, s0
	v_readfirstlane_b32 s0, v163
	ds_read_b128 v[134:137], v151
	ds_read_b128 v[138:141], v151 offset:1024
	ds_read_b128 v[152:155], v151 offset:2048
	ds_read_b128 v[156:159], v151 offset:3072
	ds_read_b128 v[164:167], v0
	ds_read_b128 v[168:171], v0 offset:1024
	ds_read_b128 v[172:175], v0 offset:2048
	ds_read_b128 v[176:179], v0 offset:3072
	ds_read_b128 v[180:183], v0 offset:4096
	ds_read_b128 v[184:187], v0 offset:5120
	ds_read_b128 v[188:191], v0 offset:6144
	ds_read_b128 v[192:195], v0 offset:7168
	global_load_lds_dwordx4 v[132:133], off
	v_lshl_add_u64 v[130:131], v[130:131], 0, s[12:13]
	s_mov_b32 m0, s0
	s_nop 0
	global_load_lds_dwordx4 v[130:131], off
	s_barrier
	s_waitcnt lgkmcnt(0)
	s_setprio 1
	s_waitcnt lgkmcnt(0)
	v_mfma_f32_16x16x32_bf16 v[126:129], v[134:137], v[164:167], v[126:129]
	v_mfma_f32_16x16x32_bf16 v[122:125], v[152:155], v[164:167], v[122:125]
	v_mfma_f32_16x16x32_bf16 v[114:117], v[152:155], v[172:175], v[114:117]
	v_mfma_f32_16x16x32_bf16 v[106:109], v[152:155], v[180:183], v[106:109]
	v_mfma_f32_16x16x32_bf16 v[98:101], v[152:155], v[188:191], v[98:101]
	v_mfma_f32_16x16x32_bf16 v[126:129], v[138:141], v[168:171], v[126:129]
	v_mfma_f32_16x16x32_bf16 v[122:125], v[156:159], v[168:171], v[122:125]
	v_mfma_f32_16x16x32_bf16 v[118:121], v[134:137], v[172:175], v[118:121]
	v_mfma_f32_16x16x32_bf16 v[114:117], v[156:159], v[176:179], v[114:117]
	v_mfma_f32_16x16x32_bf16 v[110:113], v[134:137], v[180:183], v[110:113]
	v_mfma_f32_16x16x32_bf16 v[106:109], v[156:159], v[184:187], v[106:109]
	v_mfma_f32_16x16x32_bf16 v[102:105], v[134:137], v[188:191], v[102:105]
	v_mfma_f32_16x16x32_bf16 v[98:101], v[156:159], v[192:195], v[98:101]
	v_mfma_f32_16x16x32_bf16 v[130:133], v[138:141], v[176:179], v[118:121]
	v_mfma_f32_16x16x32_bf16 v[160:163], v[138:141], v[184:187], v[110:113]
	v_mfma_f32_16x16x32_bf16 v[196:199], v[138:141], v[192:195], v[102:105]
	s_setprio 0
	s_barrier
	s_nop 0
	ds_read_b128 v[102:105], v151 offset:16384
	ds_read_b128 v[110:113], v151 offset:17408
	ds_read_b128 v[118:121], v151 offset:18432
	ds_read_b128 v[200:203], v151 offset:19456
	s_barrier
	s_waitcnt lgkmcnt(0)
	s_setprio 1
	s_waitcnt lgkmcnt(1)
	v_mfma_f32_16x16x32_bf16 v[90:93], v[118:121], v[164:167], v[90:93]
	v_mfma_f32_16x16x32_bf16 v[82:85], v[118:121], v[172:175], v[82:85]
	v_mfma_f32_16x16x32_bf16 v[74:77], v[118:121], v[180:183], v[74:77]
	v_mfma_f32_16x16x32_bf16 v[66:69], v[118:121], v[188:191], v[66:69]
	v_mfma_f32_16x16x32_bf16 v[94:97], v[102:105], v[164:167], v[94:97]
	s_waitcnt lgkmcnt(0)
	v_mfma_f32_16x16x32_bf16 v[90:93], v[200:203], v[168:171], v[90:93]
	v_mfma_f32_16x16x32_bf16 v[86:89], v[102:105], v[172:175], v[86:89]
	v_mfma_f32_16x16x32_bf16 v[82:85], v[200:203], v[176:179], v[82:85]
	v_mfma_f32_16x16x32_bf16 v[78:81], v[102:105], v[180:183], v[78:81]
	v_mfma_f32_16x16x32_bf16 v[74:77], v[200:203], v[184:187], v[74:77]
	v_mfma_f32_16x16x32_bf16 v[70:73], v[102:105], v[188:191], v[70:73]
	v_mfma_f32_16x16x32_bf16 v[66:69], v[200:203], v[192:195], v[66:69]
	v_mfma_f32_16x16x32_bf16 v[222:225], v[110:113], v[168:171], v[94:97]
	v_mfma_f32_16x16x32_bf16 v[164:167], v[110:113], v[176:179], v[86:89]
	v_mfma_f32_16x16x32_bf16 v[168:171], v[110:113], v[184:187], v[78:81]
	v_mfma_f32_16x16x32_bf16 v[172:175], v[110:113], v[192:195], v[70:73]
	s_setprio 0
	s_barrier
	s_nop 0
	ds_read_b128 v[70:73], v0 offset:16384
	ds_read_b128 v[78:81], v0 offset:17408
	ds_read_b128 v[86:89], v0 offset:18432
	ds_read_b128 v[94:97], v0 offset:19456
	ds_read_b128 v[176:179], v0 offset:20480
	ds_read_b128 v[180:183], v0 offset:21504
	ds_read_b128 v[184:187], v0 offset:22528
	ds_read_b128 v[188:191], v0 offset:23552
	s_waitcnt vmcnt(4)
	s_barrier
	s_waitcnt lgkmcnt(0)
	s_setprio 1
	s_waitcnt lgkmcnt(7)
	v_mfma_f32_16x16x32_bf16 v[62:65], v[134:137], v[70:73], v[62:65]
	v_mfma_f32_16x16x32_bf16 v[58:61], v[152:155], v[70:73], v[58:61]
	s_waitcnt lgkmcnt(5)
	v_mfma_f32_16x16x32_bf16 v[50:53], v[152:155], v[86:89], v[50:53]
	s_waitcnt lgkmcnt(3)
	v_mfma_f32_16x16x32_bf16 v[42:45], v[152:155], v[176:179], v[42:45]
	s_waitcnt lgkmcnt(1)
	v_mfma_f32_16x16x32_bf16 v[34:37], v[152:155], v[184:187], v[34:37]
	v_mfma_f32_16x16x32_bf16 v[62:65], v[138:141], v[78:81], v[62:65]
	v_mfma_f32_16x16x32_bf16 v[58:61], v[156:159], v[78:81], v[58:61]
	v_mfma_f32_16x16x32_bf16 v[54:57], v[134:137], v[86:89], v[54:57]
	v_mfma_f32_16x16x32_bf16 v[50:53], v[156:159], v[94:97], v[50:53]
	v_mfma_f32_16x16x32_bf16 v[46:49], v[134:137], v[176:179], v[46:49]
	v_mfma_f32_16x16x32_bf16 v[42:45], v[156:159], v[180:183], v[42:45]
	v_mfma_f32_16x16x32_bf16 v[38:41], v[134:137], v[184:187], v[38:41]
	s_waitcnt lgkmcnt(0)
	v_mfma_f32_16x16x32_bf16 v[34:37], v[156:159], v[188:191], v[34:37]
	v_mfma_f32_16x16x32_bf16 v[192:195], v[138:141], v[94:97], v[54:57]
	v_mfma_f32_16x16x32_bf16 v[232:235], v[138:141], v[180:183], v[46:49]
	v_mfma_f32_16x16x32_bf16 v[134:137], v[138:141], v[188:191], v[38:41]
	s_setprio 0
	s_setprio 1
	v_mfma_f32_16x16x32_bf16 v[26:29], v[118:121], v[70:73], v[26:29]
	v_mfma_f32_16x16x32_bf16 v[18:21], v[118:121], v[86:89], v[18:21]
	v_mfma_f32_16x16x32_bf16 v[10:13], v[118:121], v[176:179], v[10:13]
	v_mfma_f32_16x16x32_bf16 v[2:5], v[118:121], v[184:187], v[2:5]
	v_mfma_f32_16x16x32_bf16 v[30:33], v[102:105], v[70:73], v[30:33]
	v_mfma_f32_16x16x32_bf16 v[26:29], v[200:203], v[78:81], v[26:29]
	v_mfma_f32_16x16x32_bf16 v[22:25], v[102:105], v[86:89], v[22:25]
	v_mfma_f32_16x16x32_bf16 v[18:21], v[200:203], v[94:97], v[18:21]
	v_mfma_f32_16x16x32_bf16 v[14:17], v[102:105], v[176:179], v[14:17]
	v_mfma_f32_16x16x32_bf16 v[10:13], v[200:203], v[180:183], v[10:13]
	v_mfma_f32_16x16x32_bf16 v[6:9], v[102:105], v[184:187], v[6:9]
	v_mfma_f32_16x16x32_bf16 v[2:5], v[200:203], v[188:191], v[2:5]
	v_mfma_f32_16x16x32_bf16 v[138:141], v[110:113], v[78:81], v[30:33]
	v_mfma_f32_16x16x32_bf16 v[152:155], v[110:113], v[94:97], v[22:25]
	v_mfma_f32_16x16x32_bf16 v[156:159], v[110:113], v[180:183], v[14:17]
	v_mfma_f32_16x16x32_bf16 v[176:179], v[110:113], v[188:191], v[6:9]
	s_setprio 0
	s_barrier
	s_nop 0
	ds_read_b128 v[6:9], v151 offset:32768
	ds_read_b128 v[14:17], v151 offset:33792
	ds_read_b128 v[180:183], v151 offset:34816
	ds_read_b128 v[184:187], v151 offset:35840
	ds_read_b128 v[22:25], v0 offset:32768
	ds_read_b128 v[30:33], v0 offset:33792
	ds_read_b128 v[38:41], v0 offset:34816
	ds_read_b128 v[46:49], v0 offset:35840
	ds_read_b128 v[54:57], v0 offset:36864
	ds_read_b128 v[188:191], v0 offset:37888
	ds_read_b128 v[200:203], v0 offset:38912
	ds_read_b128 v[236:239], v0 offset:39936
	s_waitcnt vmcnt(2)
	s_barrier
	s_waitcnt lgkmcnt(0)
	s_setprio 1
	s_waitcnt lgkmcnt(7)
	v_mfma_f32_16x16x32_bf16 v[70:73], v[6:9], v[22:25], v[126:129]
	s_waitcnt lgkmcnt(6)
	v_mfma_f32_16x16x32_bf16 v[126:129], v[14:17], v[30:33], v[70:73]
	v_mfma_f32_16x16x32_bf16 v[70:73], v[180:183], v[22:25], v[122:125]
	v_mfma_f32_16x16x32_bf16 v[118:121], v[184:187], v[30:33], v[70:73]
	s_waitcnt lgkmcnt(5)
	v_mfma_f32_16x16x32_bf16 v[70:73], v[6:9], v[38:41], v[130:133]
	s_waitcnt lgkmcnt(4)
	v_mfma_f32_16x16x32_bf16 v[110:113], v[14:17], v[46:49], v[70:73]
	v_mfma_f32_16x16x32_bf16 v[70:73], v[180:183], v[38:41], v[114:117]
	v_mfma_f32_16x16x32_bf16 v[102:105], v[184:187], v[46:49], v[70:73]
	s_waitcnt lgkmcnt(3)
	v_mfma_f32_16x16x32_bf16 v[70:73], v[6:9], v[54:57], v[160:163]
	s_waitcnt lgkmcnt(2)
	v_mfma_f32_16x16x32_bf16 v[94:97], v[14:17], v[188:191], v[70:73]
	v_mfma_f32_16x16x32_bf16 v[70:73], v[180:183], v[54:57], v[106:109]
	v_mfma_f32_16x16x32_bf16 v[86:89], v[184:187], v[188:191], v[70:73]
	s_waitcnt lgkmcnt(1)
	v_mfma_f32_16x16x32_bf16 v[70:73], v[6:9], v[200:203], v[196:199]
	s_waitcnt lgkmcnt(0)
	v_mfma_f32_16x16x32_bf16 v[78:81], v[14:17], v[236:239], v[70:73]
	v_mfma_f32_16x16x32_bf16 v[70:73], v[180:183], v[200:203], v[98:101]
	v_mfma_f32_16x16x32_bf16 v[70:73], v[184:187], v[236:239], v[70:73]
	s_setprio 0
	s_barrier
	ds_read_b128 v[130:133], v151 offset:49152
	ds_read_b128 v[160:163], v151 offset:50176
	ds_read_b128 v[196:199], v151 offset:51200
	ds_read_b128 v[148:151], v151 offset:52224
	s_waitcnt vmcnt(0)
	s_barrier
	s_waitcnt lgkmcnt(0)
	s_setprio 1
	s_waitcnt lgkmcnt(3)
	v_mfma_f32_16x16x32_bf16 v[98:101], v[130:133], v[22:25], v[222:225]
	s_waitcnt lgkmcnt(1)
	v_mfma_f32_16x16x32_bf16 v[22:25], v[196:199], v[22:25], v[90:93]
	s_waitcnt lgkmcnt(0)
	v_mfma_f32_16x16x32_bf16 v[114:117], v[148:151], v[30:33], v[22:25]
	v_mfma_f32_16x16x32_bf16 v[22:25], v[130:133], v[38:41], v[164:167]
	v_mfma_f32_16x16x32_bf16 v[106:109], v[160:163], v[46:49], v[22:25]
	v_mfma_f32_16x16x32_bf16 v[22:25], v[196:199], v[38:41], v[82:85]
	v_mfma_f32_16x16x32_bf16 v[122:125], v[160:163], v[30:33], v[98:101]
	v_mfma_f32_16x16x32_bf16 v[98:101], v[148:151], v[46:49], v[22:25]
	v_mfma_f32_16x16x32_bf16 v[22:25], v[130:133], v[54:57], v[168:171]
	v_mfma_f32_16x16x32_bf16 v[90:93], v[160:163], v[188:191], v[22:25]
	v_mfma_f32_16x16x32_bf16 v[22:25], v[196:199], v[54:57], v[74:77]
	v_mfma_f32_16x16x32_bf16 v[82:85], v[148:151], v[188:191], v[22:25]
	v_mfma_f32_16x16x32_bf16 v[22:25], v[130:133], v[200:203], v[172:175]
	v_mfma_f32_16x16x32_bf16 v[74:77], v[160:163], v[236:239], v[22:25]
	v_mfma_f32_16x16x32_bf16 v[22:25], v[196:199], v[200:203], v[66:69]
	v_mfma_f32_16x16x32_bf16 v[66:69], v[148:151], v[236:239], v[22:25]
	s_setprio 0
	s_barrier
	ds_read_b128 v[164:167], v0 offset:49152
	ds_read_b128 v[168:171], v0 offset:50176
	ds_read_b128 v[172:175], v0 offset:51200
	ds_read_b128 v[188:191], v0 offset:52224
	ds_read_b128 v[200:203], v0 offset:53248
	ds_read_b128 v[222:225], v0 offset:54272
	ds_read_b128 v[236:239], v0 offset:55296
	ds_read_b128 v[240:243], v0 offset:56320
	s_barrier
	s_waitcnt lgkmcnt(0)
	s_setprio 1
	s_waitcnt lgkmcnt(7)
	v_mfma_f32_16x16x32_bf16 v[22:25], v[6:9], v[164:167], v[62:65]
	s_waitcnt lgkmcnt(6)
	v_mfma_f32_16x16x32_bf16 v[62:65], v[14:17], v[168:171], v[22:25]
	v_mfma_f32_16x16x32_bf16 v[22:25], v[180:183], v[164:167], v[58:61]
	v_mfma_f32_16x16x32_bf16 v[54:57], v[184:187], v[168:171], v[22:25]
	s_waitcnt lgkmcnt(5)
	v_mfma_f32_16x16x32_bf16 v[22:25], v[6:9], v[172:175], v[192:195]
	s_waitcnt lgkmcnt(4)
	v_mfma_f32_16x16x32_bf16 v[46:49], v[14:17], v[188:191], v[22:25]
	v_mfma_f32_16x16x32_bf16 v[22:25], v[180:183], v[172:175], v[50:53]
	v_mfma_f32_16x16x32_bf16 v[38:41], v[184:187], v[188:191], v[22:25]
	s_waitcnt lgkmcnt(3)
	v_mfma_f32_16x16x32_bf16 v[22:25], v[6:9], v[200:203], v[232:235]
	s_waitcnt lgkmcnt(1)
	v_mfma_f32_16x16x32_bf16 v[6:9], v[6:9], v[236:239], v[134:137]
	v_mfma_f32_16x16x32_bf16 v[30:33], v[14:17], v[222:225], v[22:25]
	v_mfma_f32_16x16x32_bf16 v[22:25], v[180:183], v[200:203], v[42:45]
	s_waitcnt lgkmcnt(0)
	v_mfma_f32_16x16x32_bf16 v[14:17], v[14:17], v[240:243], v[6:9]
	v_mfma_f32_16x16x32_bf16 v[6:9], v[180:183], v[236:239], v[34:37]
	v_mfma_f32_16x16x32_bf16 v[22:25], v[184:187], v[222:225], v[22:25]
	v_mfma_f32_16x16x32_bf16 v[6:9], v[184:187], v[240:243], v[6:9]
	s_setprio 0
	s_setprio 1
	v_mfma_f32_16x16x32_bf16 v[34:37], v[130:133], v[164:167], v[138:141]
	v_mfma_f32_16x16x32_bf16 v[26:29], v[196:199], v[164:167], v[26:29]
	v_mfma_f32_16x16x32_bf16 v[18:21], v[196:199], v[172:175], v[18:21]
	v_mfma_f32_16x16x32_bf16 v[58:61], v[160:163], v[168:171], v[34:37]
	v_mfma_f32_16x16x32_bf16 v[50:53], v[148:151], v[168:171], v[26:29]
	v_mfma_f32_16x16x32_bf16 v[26:29], v[130:133], v[172:175], v[152:155]
	v_mfma_f32_16x16x32_bf16 v[34:37], v[148:151], v[188:191], v[18:21]
	v_mfma_f32_16x16x32_bf16 v[18:21], v[130:133], v[200:203], v[156:159]
	v_mfma_f32_16x16x32_bf16 v[10:13], v[196:199], v[200:203], v[10:13]
	v_mfma_f32_16x16x32_bf16 v[42:45], v[160:163], v[188:191], v[26:29]
	v_mfma_f32_16x16x32_bf16 v[26:29], v[160:163], v[222:225], v[18:21]
	v_mfma_f32_16x16x32_bf16 v[18:21], v[148:151], v[222:225], v[10:13]
	v_mfma_f32_16x16x32_bf16 v[10:13], v[130:133], v[236:239], v[176:179]
	v_mfma_f32_16x16x32_bf16 v[2:5], v[196:199], v[236:239], v[2:5]
	v_mfma_f32_16x16x32_bf16 v[10:13], v[160:163], v[240:243], v[10:13]
	v_mfma_f32_16x16x32_bf16 v[2:5], v[148:151], v[240:243], v[2:5]
	s_setprio 0
	s_movk_i32 s0, 0x100
	v_cmp_gt_u32_e32 vcc, s0, v142
	s_barrier
	s_and_saveexec_b64 s[0:1], vcc
	s_cbranch_execz .LBB0_183
	s_barrier

.LBB0_678:
	ds_read_b128 v[164:167], v151
	ds_read_b128 v[168:171], v151 offset:1024
	ds_read_b128 v[172:175], v151 offset:2048
	ds_read_b128 v[176:179], v151 offset:3072
	v_lshl_add_u64 v[204:205], v[138:139], 0, s[8:9]
	v_lshl_add_u64 v[218:219], v[204:205], 0, s[60:61]
	s_add_i32 m0, s1, 0xc000
	ds_read_b128 v[180:183], v0
	ds_read_b128 v[184:187], v0 offset:1024
	ds_read_b128 v[188:191], v0 offset:2048
	ds_read_b128 v[192:195], v0 offset:3072
	ds_read_b128 v[196:199], v0 offset:4096
	ds_read_b128 v[200:203], v0 offset:5120
	ds_read_b128 v[232:235], v0 offset:6144
	ds_read_b128 v[236:239], v0 offset:7168
	global_load_lds_dwordx4 v[218:219], off
	v_lshl_add_u64 v[216:217], v[140:141], 0, s[8:9]
	s_add_i32 m0, s1, 0xe000
	v_lshl_add_u64 v[152:153], v[216:217], 0, s[60:61]
	global_load_lds_dwordx4 v[152:153], off
	s_waitcnt lgkmcnt(8)
	s_barrier
	s_waitcnt lgkmcnt(0)
	v_mfma_f32_16x16x32_bf16 v[126:129], v[164:167], v[180:183], v[126:129]
	v_mfma_f32_16x16x32_bf16 v[122:125], v[172:175], v[180:183], v[122:125]
	v_mfma_f32_16x16x32_bf16 v[118:121], v[164:167], v[188:191], v[118:121]
	v_mfma_f32_16x16x32_bf16 v[114:117], v[172:175], v[188:191], v[114:117]
	v_mfma_f32_16x16x32_bf16 v[110:113], v[164:167], v[196:199], v[110:113]
	v_mfma_f32_16x16x32_bf16 v[106:109], v[172:175], v[196:199], v[106:109]
	v_mfma_f32_16x16x32_bf16 v[102:105], v[164:167], v[232:235], v[102:105]
	v_mfma_f32_16x16x32_bf16 v[98:101], v[172:175], v[232:235], v[98:101]
	v_mfma_f32_16x16x32_bf16 v[126:129], v[168:171], v[184:187], v[126:129]
	v_mfma_f32_16x16x32_bf16 v[122:125], v[176:179], v[184:187], v[122:125]
	v_mfma_f32_16x16x32_bf16 v[118:121], v[168:171], v[192:195], v[118:121]
	v_mfma_f32_16x16x32_bf16 v[114:117], v[176:179], v[192:195], v[114:117]
	v_mfma_f32_16x16x32_bf16 v[110:113], v[168:171], v[200:203], v[110:113]
	v_mfma_f32_16x16x32_bf16 v[106:109], v[176:179], v[200:203], v[106:109]
	v_mfma_f32_16x16x32_bf16 v[102:105], v[168:171], v[236:239], v[102:105]
	v_mfma_f32_16x16x32_bf16 v[98:101], v[176:179], v[236:239], v[98:101]
	s_barrier
	v_lshl_add_u64 v[210:211], v[134:135], 0, s[8:9]
	s_add_i32 m0, s1, 0xff00
	ds_read_b128 v[240:243], v151 offset:16384
	ds_read_b128 v[244:247], v151 offset:17408
	ds_read_b128 v[248:251], v151 offset:18432
	ds_read_b128 v[222:225], v151 offset:19456
	global_load_lds_dwordx4 v[210:211], off offset:256
	s_add_i32 m0, s1, 0x11f00
	v_lshl_add_u64 v[228:229], v[136:137], 0, s[8:9]
	global_load_lds_dwordx4 v[228:229], off offset:256
	s_barrier
	s_waitcnt lgkmcnt(0)
	v_mfma_f32_16x16x32_bf16 v[94:97], v[240:243], v[180:183], v[94:97]
	v_mfma_f32_16x16x32_bf16 v[90:93], v[248:251], v[180:183], v[90:93]
	v_mfma_f32_16x16x32_bf16 v[86:89], v[240:243], v[188:191], v[86:89]
	v_mfma_f32_16x16x32_bf16 v[82:85], v[248:251], v[188:191], v[82:85]
	v_mfma_f32_16x16x32_bf16 v[78:81], v[240:243], v[196:199], v[78:81]
	v_mfma_f32_16x16x32_bf16 v[74:77], v[248:251], v[196:199], v[74:77]
	v_mfma_f32_16x16x32_bf16 v[70:73], v[240:243], v[232:235], v[70:73]
	v_mfma_f32_16x16x32_bf16 v[66:69], v[248:251], v[232:235], v[66:69]
	v_mfma_f32_16x16x32_bf16 v[94:97], v[244:247], v[184:187], v[94:97]
	v_mfma_f32_16x16x32_bf16 v[90:93], v[222:225], v[184:187], v[90:93]
	v_mfma_f32_16x16x32_bf16 v[86:89], v[244:247], v[192:195], v[86:89]
	v_mfma_f32_16x16x32_bf16 v[82:85], v[222:225], v[192:195], v[82:85]
	v_mfma_f32_16x16x32_bf16 v[78:81], v[244:247], v[200:203], v[78:81]
	v_mfma_f32_16x16x32_bf16 v[74:77], v[222:225], v[200:203], v[74:77]
	v_mfma_f32_16x16x32_bf16 v[70:73], v[244:247], v[236:239], v[70:73]
	v_mfma_f32_16x16x32_bf16 v[66:69], v[222:225], v[236:239], v[66:69]
	v_lshl_add_u64 v[158:159], v[204:205], 0, s[74:75]
	s_mov_b32 m0, s1
	s_barrier
	ds_read_b128 v[180:183], v0 offset:16384
	ds_read_b128 v[184:187], v0 offset:17408
	ds_read_b128 v[188:191], v0 offset:18432
	ds_read_b128 v[192:195], v0 offset:19456
	ds_read_b128 v[196:199], v0 offset:20480
	ds_read_b128 v[200:203], v0 offset:21504
	ds_read_b128 v[232:235], v0 offset:22528
	ds_read_b128 v[236:239], v0 offset:23552
	global_load_lds_dwordx4 v[158:159], off
	s_add_i32 m0, s1, 0x1f00
	s_nop 0
	global_load_lds_dwordx4 v[216:217], off offset:256
	s_barrier
	s_waitcnt lgkmcnt(0)
	v_mfma_f32_16x16x32_bf16 v[62:65], v[164:167], v[180:183], v[62:65]
	v_mfma_f32_16x16x32_bf16 v[58:61], v[172:175], v[180:183], v[58:61]
	v_mfma_f32_16x16x32_bf16 v[54:57], v[164:167], v[188:191], v[54:57]
	v_mfma_f32_16x16x32_bf16 v[50:53], v[172:175], v[188:191], v[50:53]
	v_mfma_f32_16x16x32_bf16 v[46:49], v[164:167], v[196:199], v[46:49]
	v_mfma_f32_16x16x32_bf16 v[42:45], v[172:175], v[196:199], v[42:45]
	v_mfma_f32_16x16x32_bf16 v[38:41], v[164:167], v[232:235], v[38:41]
	v_mfma_f32_16x16x32_bf16 v[34:37], v[172:175], v[232:235], v[34:37]
	v_mfma_f32_16x16x32_bf16 v[62:65], v[168:171], v[184:187], v[62:65]
	v_mfma_f32_16x16x32_bf16 v[58:61], v[176:179], v[184:187], v[58:61]
	v_mfma_f32_16x16x32_bf16 v[54:57], v[168:171], v[192:195], v[54:57]
	v_mfma_f32_16x16x32_bf16 v[50:53], v[176:179], v[192:195], v[50:53]
	v_mfma_f32_16x16x32_bf16 v[46:49], v[168:171], v[200:203], v[46:49]
	v_mfma_f32_16x16x32_bf16 v[42:45], v[176:179], v[200:203], v[42:45]
	v_mfma_f32_16x16x32_bf16 v[38:41], v[168:171], v[236:239], v[38:41]
	v_mfma_f32_16x16x32_bf16 v[34:37], v[176:179], v[236:239], v[34:37]
	s_barrier
	s_add_i32 m0, s1, 0x14000
	v_lshl_add_u64 v[154:155], v[210:211], 0, s[18:19]
	global_load_lds_dwordx4 v[154:155], off
	s_add_i32 m0, s1, 0x16000
	v_lshl_add_u64 v[156:157], v[228:229], 0, s[18:19]
	global_load_lds_dwordx4 v[156:157], off
	s_waitcnt vmcnt(6)
	s_barrier
	v_mfma_f32_16x16x32_bf16 v[30:33], v[240:243], v[180:183], v[30:33]
	v_mfma_f32_16x16x32_bf16 v[26:29], v[248:251], v[180:183], v[26:29]
	v_mfma_f32_16x16x32_bf16 v[22:25], v[240:243], v[188:191], v[22:25]
	v_mfma_f32_16x16x32_bf16 v[18:21], v[248:251], v[188:191], v[18:21]
	v_mfma_f32_16x16x32_bf16 v[14:17], v[240:243], v[196:199], v[14:17]
	v_mfma_f32_16x16x32_bf16 v[10:13], v[248:251], v[196:199], v[10:13]
	v_mfma_f32_16x16x32_bf16 v[6:9], v[240:243], v[232:235], v[6:9]
	v_mfma_f32_16x16x32_bf16 v[2:5], v[248:251], v[232:235], v[2:5]
	v_mfma_f32_16x16x32_bf16 v[30:33], v[244:247], v[184:187], v[30:33]
	v_mfma_f32_16x16x32_bf16 v[26:29], v[222:225], v[184:187], v[26:29]
	v_mfma_f32_16x16x32_bf16 v[22:25], v[244:247], v[192:195], v[22:25]
	v_mfma_f32_16x16x32_bf16 v[18:21], v[222:225], v[192:195], v[18:21]
	v_mfma_f32_16x16x32_bf16 v[14:17], v[244:247], v[200:203], v[14:17]
	v_mfma_f32_16x16x32_bf16 v[10:13], v[222:225], v[200:203], v[10:13]
	v_mfma_f32_16x16x32_bf16 v[6:9], v[244:247], v[236:239], v[6:9]
	v_mfma_f32_16x16x32_bf16 v[2:5], v[222:225], v[236:239], v[2:5]
	s_barrier
	ds_read_b128 v[164:167], v151 offset:32768
	ds_read_b128 v[168:171], v151 offset:33792
	ds_read_b128 v[172:175], v151 offset:34816
	ds_read_b128 v[176:179], v151 offset:35840
	s_add_i32 m0, s1, 0x3f80
	ds_read_b128 v[180:183], v0 offset:32768
	ds_read_b128 v[184:187], v0 offset:33792
	ds_read_b128 v[188:191], v0 offset:34816
	ds_read_b128 v[192:195], v0 offset:35840
	ds_read_b128 v[196:199], v0 offset:36864
	ds_read_b128 v[200:203], v0 offset:37888
	ds_read_b128 v[222:225], v0 offset:38912
	ds_read_b128 v[232:235], v0 offset:39936
	global_load_lds_dwordx4 v[218:219], off offset:128
	s_add_i32 m0, s1, 0x5f80
	s_nop 0
	global_load_lds_dwordx4 v[152:153], off offset:128
	s_waitcnt lgkmcnt(8)
	s_barrier
	s_waitcnt lgkmcnt(0)
	v_mfma_f32_16x16x32_bf16 v[126:129], v[164:167], v[180:183], v[126:129]
	v_mfma_f32_16x16x32_bf16 v[122:125], v[172:175], v[180:183], v[122:125]
	v_mfma_f32_16x16x32_bf16 v[118:121], v[164:167], v[188:191], v[118:121]
	v_mfma_f32_16x16x32_bf16 v[114:117], v[172:175], v[188:191], v[114:117]
	v_mfma_f32_16x16x32_bf16 v[110:113], v[164:167], v[196:199], v[110:113]
	v_mfma_f32_16x16x32_bf16 v[106:109], v[172:175], v[196:199], v[106:109]
	v_mfma_f32_16x16x32_bf16 v[102:105], v[164:167], v[222:225], v[102:105]
	v_mfma_f32_16x16x32_bf16 v[98:101], v[172:175], v[222:225], v[98:101]
	v_mfma_f32_16x16x32_bf16 v[126:129], v[168:171], v[184:187], v[126:129]
	v_mfma_f32_16x16x32_bf16 v[122:125], v[176:179], v[184:187], v[122:125]
	v_mfma_f32_16x16x32_bf16 v[118:121], v[168:171], v[192:195], v[118:121]
	v_mfma_f32_16x16x32_bf16 v[114:117], v[176:179], v[192:195], v[114:117]
	v_mfma_f32_16x16x32_bf16 v[110:113], v[168:171], v[200:203], v[110:113]
	v_mfma_f32_16x16x32_bf16 v[106:109], v[176:179], v[200:203], v[106:109]
	v_mfma_f32_16x16x32_bf16 v[102:105], v[168:171], v[232:235], v[102:105]
	v_mfma_f32_16x16x32_bf16 v[98:101], v[176:179], v[232:235], v[98:101]
	s_barrier
	s_add_i32 m0, s1, 0x17e80
	ds_read_b128 v[236:239], v151 offset:49152
	ds_read_b128 v[240:243], v151 offset:50176
	ds_read_b128 v[244:247], v151 offset:51200
	ds_read_b128 v[248:251], v151 offset:52224
	global_load_lds_dwordx4 v[210:211], off offset:384
	s_add_i32 m0, s1, 0x19e80
	s_nop 0
	global_load_lds_dwordx4 v[228:229], off offset:384
	s_barrier
	s_waitcnt lgkmcnt(0)
	v_mfma_f32_16x16x32_bf16 v[94:97], v[236:239], v[180:183], v[94:97]
	v_mfma_f32_16x16x32_bf16 v[90:93], v[244:247], v[180:183], v[90:93]
	v_mfma_f32_16x16x32_bf16 v[86:89], v[236:239], v[188:191], v[86:89]
	v_mfma_f32_16x16x32_bf16 v[82:85], v[244:247], v[188:191], v[82:85]
	v_mfma_f32_16x16x32_bf16 v[78:81], v[236:239], v[196:199], v[78:81]
	v_mfma_f32_16x16x32_bf16 v[74:77], v[244:247], v[196:199], v[74:77]
	v_mfma_f32_16x16x32_bf16 v[70:73], v[236:239], v[222:225], v[70:73]
	v_mfma_f32_16x16x32_bf16 v[66:69], v[244:247], v[222:225], v[66:69]
	v_mfma_f32_16x16x32_bf16 v[94:97], v[240:243], v[184:187], v[94:97]
	v_mfma_f32_16x16x32_bf16 v[90:93], v[248:251], v[184:187], v[90:93]
	v_mfma_f32_16x16x32_bf16 v[86:89], v[240:243], v[192:195], v[86:89]
	v_mfma_f32_16x16x32_bf16 v[82:85], v[248:251], v[192:195], v[82:85]
	v_mfma_f32_16x16x32_bf16 v[78:81], v[240:243], v[200:203], v[78:81]
	v_mfma_f32_16x16x32_bf16 v[74:77], v[248:251], v[200:203], v[74:77]
	v_mfma_f32_16x16x32_bf16 v[70:73], v[240:243], v[232:235], v[70:73]
	v_mfma_f32_16x16x32_bf16 v[66:69], v[248:251], v[232:235], v[66:69]
	s_add_i32 m0, s1, 0x7e80
	s_barrier
	ds_read_b128 v[180:183], v0 offset:49152
	ds_read_b128 v[184:187], v0 offset:50176
	ds_read_b128 v[188:191], v0 offset:51200
	ds_read_b128 v[192:195], v0 offset:52224
	ds_read_b128 v[196:199], v0 offset:53248
	ds_read_b128 v[200:203], v0 offset:54272
	ds_read_b128 v[222:225], v0 offset:55296
	ds_read_b128 v[232:235], v0 offset:56320
	global_load_lds_dwordx4 v[204:205], off offset:384
	s_add_i32 m0, s1, 0x9e80
	s_nop 0
	global_load_lds_dwordx4 v[216:217], off offset:384
	s_barrier
	s_waitcnt lgkmcnt(0)
	v_mfma_f32_16x16x32_bf16 v[62:65], v[164:167], v[180:183], v[62:65]
	v_mfma_f32_16x16x32_bf16 v[58:61], v[172:175], v[180:183], v[58:61]
	v_mfma_f32_16x16x32_bf16 v[54:57], v[164:167], v[188:191], v[54:57]
	v_mfma_f32_16x16x32_bf16 v[50:53], v[172:175], v[188:191], v[50:53]
	v_mfma_f32_16x16x32_bf16 v[46:49], v[164:167], v[196:199], v[46:49]
	v_mfma_f32_16x16x32_bf16 v[42:45], v[172:175], v[196:199], v[42:45]
	v_mfma_f32_16x16x32_bf16 v[38:41], v[164:167], v[222:225], v[38:41]
	v_mfma_f32_16x16x32_bf16 v[34:37], v[172:175], v[222:225], v[34:37]
	v_mfma_f32_16x16x32_bf16 v[62:65], v[168:171], v[184:187], v[62:65]
	v_mfma_f32_16x16x32_bf16 v[58:61], v[176:179], v[184:187], v[58:61]
	v_mfma_f32_16x16x32_bf16 v[54:57], v[168:171], v[192:195], v[54:57]
	v_mfma_f32_16x16x32_bf16 v[50:53], v[176:179], v[192:195], v[50:53]
	v_mfma_f32_16x16x32_bf16 v[46:49], v[168:171], v[200:203], v[46:49]
	v_mfma_f32_16x16x32_bf16 v[42:45], v[176:179], v[200:203], v[42:45]
	v_mfma_f32_16x16x32_bf16 v[38:41], v[168:171], v[232:235], v[38:41]
	v_mfma_f32_16x16x32_bf16 v[34:37], v[176:179], v[232:235], v[34:37]
	s_barrier
	s_add_i32 m0, s1, 0x1bf80
	s_nop 0
	global_load_lds_dwordx4 v[154:155], off offset:128
	s_add_i32 m0, s1, 0x1df80
	s_nop 0
	global_load_lds_dwordx4 v[156:157], off offset:128
	s_waitcnt vmcnt(6)
	s_barrier
	v_mfma_f32_16x16x32_bf16 v[30:33], v[236:239], v[180:183], v[30:33]
	v_mfma_f32_16x16x32_bf16 v[26:29], v[244:247], v[180:183], v[26:29]
	v_mfma_f32_16x16x32_bf16 v[22:25], v[236:239], v[188:191], v[22:25]
	v_mfma_f32_16x16x32_bf16 v[18:21], v[244:247], v[188:191], v[18:21]
	v_mfma_f32_16x16x32_bf16 v[14:17], v[236:239], v[196:199], v[14:17]
	v_mfma_f32_16x16x32_bf16 v[10:13], v[244:247], v[196:199], v[10:13]
	v_mfma_f32_16x16x32_bf16 v[6:9], v[236:239], v[222:225], v[6:9]
	v_mfma_f32_16x16x32_bf16 v[2:5], v[244:247], v[222:225], v[2:5]
	v_mfma_f32_16x16x32_bf16 v[30:33], v[240:243], v[184:187], v[30:33]
	v_mfma_f32_16x16x32_bf16 v[26:29], v[248:251], v[184:187], v[26:29]
	v_mfma_f32_16x16x32_bf16 v[22:25], v[240:243], v[192:195], v[22:25]
	v_mfma_f32_16x16x32_bf16 v[18:21], v[248:251], v[192:195], v[18:21]
	v_mfma_f32_16x16x32_bf16 v[14:17], v[240:243], v[200:203], v[14:17]
	v_mfma_f32_16x16x32_bf16 v[10:13], v[248:251], v[200:203], v[10:13]
	v_mfma_f32_16x16x32_bf16 v[6:9], v[240:243], v[232:235], v[6:9]
	v_mfma_f32_16x16x32_bf16 v[2:5], v[248:251], v[232:235], v[2:5]
	s_add_i32 s0, s0, 2
	s_add_u32 s8, s8, 0x100
	s_addc_u32 s9, s9, 0
	s_cmp_lt_u32 s0, 28
	s_barrier
	s_cbranch_scc1 .LBB0_678
	s_add_i32 s1, s1, 0x1e000
	s_mov_b64 s[8:9], 0xf80
	v_readfirstlane_b32 s0, v162
	v_lshl_add_u64 v[132:133], v[132:133], 0, s[8:9]
	s_mov_b32 m0, s0
	v_readfirstlane_b32 s0, v163
	ds_read_b128 v[134:137], v151
	ds_read_b128 v[138:141], v151 offset:1024
	ds_read_b128 v[152:155], v151 offset:2048
	ds_read_b128 v[156:159], v151 offset:3072
	ds_read_b128 v[164:167], v0
	ds_read_b128 v[168:171], v0 offset:1024
	ds_read_b128 v[172:175], v0 offset:2048
	ds_read_b128 v[176:179], v0 offset:3072
	ds_read_b128 v[180:183], v0 offset:4096
	ds_read_b128 v[184:187], v0 offset:5120
	ds_read_b128 v[188:191], v0 offset:6144
	ds_read_b128 v[192:195], v0 offset:7168
	global_load_lds_dwordx4 v[132:133], off
	v_lshl_add_u64 v[130:131], v[130:131], 0, s[8:9]
	s_mov_b32 m0, s0
	s_nop 0
	global_load_lds_dwordx4 v[130:131], off
	s_barrier
	s_waitcnt lgkmcnt(0)
	s_setprio 1
	s_waitcnt lgkmcnt(0)
	v_mfma_f32_16x16x32_bf16 v[126:129], v[134:137], v[164:167], v[126:129]
	v_mfma_f32_16x16x32_bf16 v[122:125], v[152:155], v[164:167], v[122:125]
	v_mfma_f32_16x16x32_bf16 v[114:117], v[152:155], v[172:175], v[114:117]
	v_mfma_f32_16x16x32_bf16 v[106:109], v[152:155], v[180:183], v[106:109]
	v_mfma_f32_16x16x32_bf16 v[98:101], v[152:155], v[188:191], v[98:101]
	v_mfma_f32_16x16x32_bf16 v[126:129], v[138:141], v[168:171], v[126:129]
	v_mfma_f32_16x16x32_bf16 v[122:125], v[156:159], v[168:171], v[122:125]
	v_mfma_f32_16x16x32_bf16 v[118:121], v[134:137], v[172:175], v[118:121]
	v_mfma_f32_16x16x32_bf16 v[114:117], v[156:159], v[176:179], v[114:117]
	v_mfma_f32_16x16x32_bf16 v[110:113], v[134:137], v[180:183], v[110:113]
	v_mfma_f32_16x16x32_bf16 v[106:109], v[156:159], v[184:187], v[106:109]
	v_mfma_f32_16x16x32_bf16 v[102:105], v[134:137], v[188:191], v[102:105]
	v_mfma_f32_16x16x32_bf16 v[98:101], v[156:159], v[192:195], v[98:101]
	v_mfma_f32_16x16x32_bf16 v[130:133], v[138:141], v[176:179], v[118:121]
	v_mfma_f32_16x16x32_bf16 v[160:163], v[138:141], v[184:187], v[110:113]
	v_mfma_f32_16x16x32_bf16 v[196:199], v[138:141], v[192:195], v[102:105]
	s_setprio 0
	s_barrier
	s_nop 0
	ds_read_b128 v[102:105], v151 offset:16384
	ds_read_b128 v[110:113], v151 offset:17408
	ds_read_b128 v[118:121], v151 offset:18432
	ds_read_b128 v[200:203], v151 offset:19456
	s_barrier
	s_waitcnt lgkmcnt(0)
	s_setprio 1
	s_waitcnt lgkmcnt(1)
	v_mfma_f32_16x16x32_bf16 v[90:93], v[118:121], v[164:167], v[90:93]
	v_mfma_f32_16x16x32_bf16 v[86:89], v[102:105], v[172:175], v[86:89]
	v_mfma_f32_16x16x32_bf16 v[82:85], v[118:121], v[172:175], v[82:85]
	v_mfma_f32_16x16x32_bf16 v[78:81], v[102:105], v[180:183], v[78:81]
	v_mfma_f32_16x16x32_bf16 v[70:73], v[102:105], v[188:191], v[70:73]
	v_mfma_f32_16x16x32_bf16 v[94:97], v[102:105], v[164:167], v[94:97]
	s_waitcnt lgkmcnt(0)
	v_mfma_f32_16x16x32_bf16 v[90:93], v[200:203], v[168:171], v[90:93]
	v_mfma_f32_16x16x32_bf16 v[86:89], v[110:113], v[176:179], v[86:89]
	v_mfma_f32_16x16x32_bf16 v[82:85], v[200:203], v[176:179], v[82:85]
	v_mfma_f32_16x16x32_bf16 v[78:81], v[110:113], v[184:187], v[78:81]
	v_mfma_f32_16x16x32_bf16 v[74:77], v[118:121], v[180:183], v[74:77]
	v_mfma_f32_16x16x32_bf16 v[70:73], v[110:113], v[192:195], v[70:73]
	v_mfma_f32_16x16x32_bf16 v[66:69], v[118:121], v[188:191], v[66:69]
	v_mfma_f32_16x16x32_bf16 v[222:225], v[110:113], v[168:171], v[94:97]
	v_mfma_f32_16x16x32_bf16 v[164:167], v[200:203], v[184:187], v[74:77]
	v_mfma_f32_16x16x32_bf16 v[168:171], v[200:203], v[192:195], v[66:69]
	s_setprio 0
	s_barrier
	s_nop 2
	ds_read_b128 v[66:69], v0 offset:16384
	ds_read_b128 v[74:77], v0 offset:17408
	ds_read_b128 v[94:97], v0 offset:18432
	ds_read_b128 v[172:175], v0 offset:19456
	ds_read_b128 v[176:179], v0 offset:20480
	ds_read_b128 v[180:183], v0 offset:21504
	ds_read_b128 v[184:187], v0 offset:22528
	ds_read_b128 v[188:191], v0 offset:23552
	s_waitcnt vmcnt(4)
	s_barrier
	s_waitcnt lgkmcnt(0)
	s_setprio 1
	s_waitcnt lgkmcnt(5)
	v_mfma_f32_16x16x32_bf16 v[54:57], v[134:137], v[94:97], v[54:57]
	v_mfma_f32_16x16x32_bf16 v[50:53], v[152:155], v[94:97], v[50:53]
	v_mfma_f32_16x16x32_bf16 v[62:65], v[134:137], v[66:69], v[62:65]
	v_mfma_f32_16x16x32_bf16 v[58:61], v[152:155], v[66:69], v[58:61]
	s_waitcnt lgkmcnt(4)
	v_mfma_f32_16x16x32_bf16 v[54:57], v[138:141], v[172:175], v[54:57]
	v_mfma_f32_16x16x32_bf16 v[50:53], v[156:159], v[172:175], v[50:53]
	s_waitcnt lgkmcnt(3)
	v_mfma_f32_16x16x32_bf16 v[46:49], v[134:137], v[176:179], v[46:49]
	v_mfma_f32_16x16x32_bf16 v[42:45], v[152:155], v[176:179], v[42:45]
	s_waitcnt lgkmcnt(1)
	v_mfma_f32_16x16x32_bf16 v[38:41], v[134:137], v[184:187], v[38:41]
	v_mfma_f32_16x16x32_bf16 v[34:37], v[152:155], v[184:187], v[34:37]
	v_mfma_f32_16x16x32_bf16 v[192:195], v[138:141], v[74:77], v[62:65]
	v_mfma_f32_16x16x32_bf16 v[232:235], v[156:159], v[74:77], v[58:61]
	v_mfma_f32_16x16x32_bf16 v[236:239], v[138:141], v[180:183], v[46:49]
	v_mfma_f32_16x16x32_bf16 v[240:243], v[156:159], v[180:183], v[42:45]
	s_waitcnt lgkmcnt(0)
	v_mfma_f32_16x16x32_bf16 v[134:137], v[138:141], v[188:191], v[38:41]
	v_mfma_f32_16x16x32_bf16 v[138:141], v[156:159], v[188:191], v[34:37]
	s_setprio 0
	s_setprio 1
	v_mfma_f32_16x16x32_bf16 v[30:33], v[102:105], v[66:69], v[30:33]
	v_mfma_f32_16x16x32_bf16 v[26:29], v[118:121], v[66:69], v[26:29]
	v_mfma_f32_16x16x32_bf16 v[14:17], v[102:105], v[176:179], v[14:17]
	v_mfma_f32_16x16x32_bf16 v[10:13], v[118:121], v[176:179], v[10:13]
	v_mfma_f32_16x16x32_bf16 v[30:33], v[110:113], v[74:77], v[30:33]
	v_mfma_f32_16x16x32_bf16 v[26:29], v[200:203], v[74:77], v[26:29]
	v_mfma_f32_16x16x32_bf16 v[22:25], v[102:105], v[94:97], v[22:25]
	v_mfma_f32_16x16x32_bf16 v[18:21], v[118:121], v[94:97], v[18:21]
	v_mfma_f32_16x16x32_bf16 v[14:17], v[110:113], v[180:183], v[14:17]
	v_mfma_f32_16x16x32_bf16 v[10:13], v[200:203], v[180:183], v[10:13]
	v_mfma_f32_16x16x32_bf16 v[6:9], v[102:105], v[184:187], v[6:9]
	v_mfma_f32_16x16x32_bf16 v[2:5], v[118:121], v[184:187], v[2:5]
	v_mfma_f32_16x16x32_bf16 v[152:155], v[110:113], v[172:175], v[22:25]
	v_mfma_f32_16x16x32_bf16 v[156:159], v[200:203], v[172:175], v[18:21]
	v_mfma_f32_16x16x32_bf16 v[172:175], v[110:113], v[188:191], v[6:9]
	v_mfma_f32_16x16x32_bf16 v[176:179], v[200:203], v[188:191], v[2:5]
	s_setprio 0
	s_barrier
	s_nop 1
	ds_read_b128 v[2:5], v151 offset:32768
	ds_read_b128 v[6:9], v151 offset:33792
	ds_read_b128 v[180:183], v151 offset:34816
	ds_read_b128 v[184:187], v151 offset:35840
	ds_read_b128 v[18:21], v0 offset:32768
	ds_read_b128 v[22:25], v0 offset:33792
	ds_read_b128 v[38:41], v0 offset:34816
	ds_read_b128 v[46:49], v0 offset:35840
	ds_read_b128 v[58:61], v0 offset:36864
	ds_read_b128 v[66:69], v0 offset:37888
	ds_read_b128 v[188:191], v0 offset:38912
	ds_read_b128 v[200:203], v0 offset:39936
	s_waitcnt vmcnt(2)
	s_barrier
	s_waitcnt lgkmcnt(0)
	s_setprio 1
	s_waitcnt lgkmcnt(7)
	v_mfma_f32_16x16x32_bf16 v[34:37], v[2:5], v[18:21], v[126:129]
	s_waitcnt lgkmcnt(6)
	v_mfma_f32_16x16x32_bf16 v[118:121], v[6:9], v[22:25], v[34:37]
	v_mfma_f32_16x16x32_bf16 v[34:37], v[180:183], v[18:21], v[122:125]
	v_mfma_f32_16x16x32_bf16 v[110:113], v[184:187], v[22:25], v[34:37]
	s_waitcnt lgkmcnt(5)
	v_mfma_f32_16x16x32_bf16 v[34:37], v[2:5], v[38:41], v[130:133]
	s_waitcnt lgkmcnt(4)
	v_mfma_f32_16x16x32_bf16 v[102:105], v[6:9], v[46:49], v[34:37]
	v_mfma_f32_16x16x32_bf16 v[34:37], v[180:183], v[38:41], v[114:117]
	v_mfma_f32_16x16x32_bf16 v[94:97], v[184:187], v[46:49], v[34:37]
	s_waitcnt lgkmcnt(3)
	v_mfma_f32_16x16x32_bf16 v[34:37], v[2:5], v[58:61], v[160:163]
	s_waitcnt lgkmcnt(2)
	v_mfma_f32_16x16x32_bf16 v[74:77], v[6:9], v[66:69], v[34:37]
	v_mfma_f32_16x16x32_bf16 v[34:37], v[180:183], v[58:61], v[106:109]
	v_mfma_f32_16x16x32_bf16 v[62:65], v[184:187], v[66:69], v[34:37]
	s_waitcnt lgkmcnt(1)
	v_mfma_f32_16x16x32_bf16 v[34:37], v[2:5], v[188:191], v[196:199]
	s_waitcnt lgkmcnt(0)
	v_mfma_f32_16x16x32_bf16 v[42:45], v[6:9], v[200:203], v[34:37]
	v_mfma_f32_16x16x32_bf16 v[34:37], v[180:183], v[188:191], v[98:101]
	v_mfma_f32_16x16x32_bf16 v[34:37], v[184:187], v[200:203], v[34:37]
	s_setprio 0
	s_barrier
	ds_read_b128 v[130:133], v151 offset:49152
	ds_read_b128 v[160:163], v151 offset:50176
	ds_read_b128 v[196:199], v151 offset:51200
	ds_read_b128 v[148:151], v151 offset:52224
	s_waitcnt vmcnt(0)
	s_barrier
	s_waitcnt lgkmcnt(0)
	s_setprio 1
	s_waitcnt lgkmcnt(3)
	v_mfma_f32_16x16x32_bf16 v[98:101], v[130:133], v[18:21], v[222:225]
	s_waitcnt lgkmcnt(1)
	v_mfma_f32_16x16x32_bf16 v[18:21], v[196:199], v[18:21], v[90:93]
	s_waitcnt lgkmcnt(0)
	v_mfma_f32_16x16x32_bf16 v[122:125], v[148:151], v[22:25], v[18:21]
	v_mfma_f32_16x16x32_bf16 v[18:21], v[130:133], v[38:41], v[86:89]
	v_mfma_f32_16x16x32_bf16 v[114:117], v[160:163], v[46:49], v[18:21]
	v_mfma_f32_16x16x32_bf16 v[18:21], v[196:199], v[38:41], v[82:85]
	v_mfma_f32_16x16x32_bf16 v[106:109], v[148:151], v[46:49], v[18:21]
	v_mfma_f32_16x16x32_bf16 v[18:21], v[130:133], v[58:61], v[78:81]
	v_mfma_f32_16x16x32_bf16 v[126:129], v[160:163], v[22:25], v[98:101]
	v_mfma_f32_16x16x32_bf16 v[98:101], v[160:163], v[66:69], v[18:21]
	v_mfma_f32_16x16x32_bf16 v[18:21], v[196:199], v[58:61], v[164:167]
	v_mfma_f32_16x16x32_bf16 v[90:93], v[148:151], v[66:69], v[18:21]
	v_mfma_f32_16x16x32_bf16 v[18:21], v[130:133], v[188:191], v[70:73]
	v_mfma_f32_16x16x32_bf16 v[66:69], v[160:163], v[200:203], v[18:21]
	v_mfma_f32_16x16x32_bf16 v[18:21], v[196:199], v[188:191], v[168:171]
	v_mfma_f32_16x16x32_bf16 v[58:61], v[148:151], v[200:203], v[18:21]
	s_setprio 0
	s_barrier
	ds_read_b128 v[82:85], v0 offset:49152
	ds_read_b128 v[164:167], v0 offset:50176
	ds_read_b128 v[168:171], v0 offset:51200
	ds_read_b128 v[188:191], v0 offset:52224
	ds_read_b128 v[200:203], v0 offset:53248
	ds_read_b128 v[222:225], v0 offset:54272
	ds_read_b128 v[244:247], v0 offset:55296
	ds_read_b128 v[248:251], v0 offset:56320
	s_barrier
	s_waitcnt lgkmcnt(0)
	s_setprio 1
	s_waitcnt lgkmcnt(7)
	v_mfma_f32_16x16x32_bf16 v[18:21], v[2:5], v[82:85], v[192:195]
	s_waitcnt lgkmcnt(6)
	v_mfma_f32_16x16x32_bf16 v[78:81], v[6:9], v[164:167], v[18:21]
	v_mfma_f32_16x16x32_bf16 v[18:21], v[180:183], v[82:85], v[232:235]
	v_mfma_f32_16x16x32_bf16 v[70:73], v[184:187], v[164:167], v[18:21]
	s_waitcnt lgkmcnt(5)
	v_mfma_f32_16x16x32_bf16 v[18:21], v[2:5], v[168:171], v[54:57]
	s_waitcnt lgkmcnt(4)
	v_mfma_f32_16x16x32_bf16 v[46:49], v[6:9], v[188:191], v[18:21]
	v_mfma_f32_16x16x32_bf16 v[18:21], v[180:183], v[168:171], v[50:53]
	v_mfma_f32_16x16x32_bf16 v[38:41], v[184:187], v[188:191], v[18:21]
	s_waitcnt lgkmcnt(3)
	v_mfma_f32_16x16x32_bf16 v[18:21], v[2:5], v[200:203], v[236:239]
	s_waitcnt lgkmcnt(1)
	v_mfma_f32_16x16x32_bf16 v[2:5], v[2:5], v[244:247], v[134:137]
	v_mfma_f32_16x16x32_bf16 v[22:25], v[6:9], v[222:225], v[18:21]
	v_mfma_f32_16x16x32_bf16 v[18:21], v[180:183], v[200:203], v[240:243]
	s_waitcnt lgkmcnt(0)
	v_mfma_f32_16x16x32_bf16 v[6:9], v[6:9], v[248:251], v[2:5]
	v_mfma_f32_16x16x32_bf16 v[2:5], v[180:183], v[244:247], v[138:141]
	v_mfma_f32_16x16x32_bf16 v[18:21], v[184:187], v[222:225], v[18:21]
	v_mfma_f32_16x16x32_bf16 v[2:5], v[184:187], v[248:251], v[2:5]
	s_setprio 0
	s_setprio 1
	v_mfma_f32_16x16x32_bf16 v[26:29], v[196:199], v[82:85], v[26:29]
	v_mfma_f32_16x16x32_bf16 v[30:33], v[130:133], v[82:85], v[30:33]
	v_mfma_f32_16x16x32_bf16 v[82:85], v[148:151], v[164:167], v[26:29]
	v_mfma_f32_16x16x32_bf16 v[26:29], v[130:133], v[168:171], v[152:155]
	v_mfma_f32_16x16x32_bf16 v[54:57], v[160:163], v[188:191], v[26:29]
	v_mfma_f32_16x16x32_bf16 v[26:29], v[196:199], v[168:171], v[156:159]
	v_mfma_f32_16x16x32_bf16 v[10:13], v[196:199], v[200:203], v[10:13]
	v_mfma_f32_16x16x32_bf16 v[50:53], v[148:151], v[188:191], v[26:29]
	v_mfma_f32_16x16x32_bf16 v[14:17], v[130:133], v[200:203], v[14:17]
	v_mfma_f32_16x16x32_bf16 v[26:29], v[148:151], v[222:225], v[10:13]
	v_mfma_f32_16x16x32_bf16 v[10:13], v[130:133], v[244:247], v[172:175]
	v_mfma_f32_16x16x32_bf16 v[86:89], v[160:163], v[164:167], v[30:33]
	v_mfma_f32_16x16x32_bf16 v[30:33], v[160:163], v[222:225], v[14:17]
	v_mfma_f32_16x16x32_bf16 v[14:17], v[160:163], v[248:251], v[10:13]
	v_mfma_f32_16x16x32_bf16 v[10:13], v[196:199], v[244:247], v[176:179]
	v_mfma_f32_16x16x32_bf16 v[10:13], v[148:151], v[248:251], v[10:13]
	s_setprio 0
	s_movk_i32 s0, 0x100
	v_cmp_gt_u32_e32 vcc, s0, v142
	s_barrier
	s_and_saveexec_b64 s[0:1], vcc
	s_cbranch_execz .LBB0_674
	s_barrier
	s_branch .LBB0_674

.LBB0_689:
	ds_read_b128 v[104:107], v95
	ds_read_b128 v[108:111], v95 offset:1024
	ds_read_b128 v[112:115], v95 offset:2048
	ds_read_b128 v[116:119], v95 offset:3072
	v_lshl_add_u64 v[152:153], v[72:73], 0, s[10:11]
	v_lshl_add_u64 v[164:165], v[152:153], 0, s[34:35]
	s_add_i32 m0, s1, 0xc000
	ds_read_b128 v[120:123], v93
	ds_read_b128 v[124:127], v93 offset:1024
	ds_read_b128 v[128:131], v93 offset:2048
	ds_read_b128 v[132:135], v93 offset:3072
	ds_read_b128 v[136:139], v93 offset:4096
	ds_read_b128 v[140:143], v93 offset:5120
	ds_read_b128 v[144:147], v93 offset:6144
	ds_read_b128 v[148:151], v93 offset:7168
	global_load_lds_dwordx4 v[164:165], off
	v_lshl_add_u64 v[154:155], v[74:75], 0, s[10:11]
	s_add_i32 m0, s1, 0xe000
	v_lshl_add_u64 v[86:87], v[154:155], 0, s[34:35]
	global_load_lds_dwordx4 v[86:87], off
	s_waitcnt lgkmcnt(8)
	s_barrier
	s_waitcnt lgkmcnt(0)
	v_mfma_f32_16x16x32_bf16 v[62:65], v[104:107], v[120:123], v[62:65]
	v_mfma_f32_16x16x32_bf16 v[58:61], v[112:115], v[120:123], v[58:61]
	v_mfma_f32_16x16x32_bf16 v[54:57], v[104:107], v[128:131], v[54:57]
	v_mfma_f32_16x16x32_bf16 v[50:53], v[112:115], v[128:131], v[50:53]
	v_mfma_f32_16x16x32_bf16 v[46:49], v[104:107], v[136:139], v[46:49]
	v_mfma_f32_16x16x32_bf16 v[42:45], v[112:115], v[136:139], v[42:45]
	v_mfma_f32_16x16x32_bf16 v[38:41], v[104:107], v[144:147], v[38:41]
	v_mfma_f32_16x16x32_bf16 v[34:37], v[112:115], v[144:147], v[34:37]
	v_mfma_f32_16x16x32_bf16 v[62:65], v[108:111], v[124:127], v[62:65]
	v_mfma_f32_16x16x32_bf16 v[58:61], v[116:119], v[124:127], v[58:61]
	v_mfma_f32_16x16x32_bf16 v[54:57], v[108:111], v[132:135], v[54:57]
	v_mfma_f32_16x16x32_bf16 v[50:53], v[116:119], v[132:135], v[50:53]
	v_mfma_f32_16x16x32_bf16 v[46:49], v[108:111], v[140:143], v[46:49]
	v_mfma_f32_16x16x32_bf16 v[42:45], v[116:119], v[140:143], v[42:45]
	v_mfma_f32_16x16x32_bf16 v[38:41], v[108:111], v[148:151], v[38:41]
	v_mfma_f32_16x16x32_bf16 v[34:37], v[116:119], v[148:151], v[34:37]
	s_barrier
	v_lshl_add_u64 v[156:157], v[68:69], 0, s[10:11]
	s_add_i32 m0, s1, 0xff00
	s_nop 0
	global_load_lds_dwordx4 v[156:157], off offset:256
	s_add_i32 m0, s1, 0x11f00
	v_lshl_add_u64 v[158:159], v[70:71], 0, s[10:11]
	global_load_lds_dwordx4 v[158:159], off offset:256
	v_lshl_add_u64 v[88:89], v[152:153], 0, s[74:75]
	s_mov_b32 m0, s1
	s_barrier
	s_waitcnt lgkmcnt(0)
	s_barrier
	ds_read_b128 v[120:123], v93 offset:16384
	ds_read_b128 v[124:127], v93 offset:17408
	ds_read_b128 v[128:131], v93 offset:18432
	ds_read_b128 v[132:135], v93 offset:19456
	ds_read_b128 v[136:139], v93 offset:20480
	ds_read_b128 v[140:143], v93 offset:21504
	ds_read_b128 v[144:147], v93 offset:22528
	ds_read_b128 v[148:151], v93 offset:23552
	global_load_lds_dwordx4 v[88:89], off
	s_add_i32 m0, s1, 0x1f00
	s_nop 0
	global_load_lds_dwordx4 v[154:155], off offset:256
	s_barrier
	s_waitcnt lgkmcnt(0)
	v_mfma_f32_16x16x32_bf16 v[2:5], v[104:107], v[120:123], v[2:5]
	v_mfma_f32_16x16x32_bf16 v[6:9], v[112:115], v[120:123], v[6:9]
	v_mfma_f32_16x16x32_bf16 v[10:13], v[104:107], v[128:131], v[10:13]
	v_mfma_f32_16x16x32_bf16 v[14:17], v[112:115], v[128:131], v[14:17]
	v_mfma_f32_16x16x32_bf16 v[18:21], v[104:107], v[136:139], v[18:21]
	v_mfma_f32_16x16x32_bf16 v[22:25], v[112:115], v[136:139], v[22:25]
	v_mfma_f32_16x16x32_bf16 v[26:29], v[104:107], v[144:147], v[26:29]
	v_mfma_f32_16x16x32_bf16 v[30:33], v[112:115], v[144:147], v[30:33]
	v_mfma_f32_16x16x32_bf16 v[2:5], v[108:111], v[124:127], v[2:5]
	v_mfma_f32_16x16x32_bf16 v[6:9], v[116:119], v[124:127], v[6:9]
	v_mfma_f32_16x16x32_bf16 v[10:13], v[108:111], v[132:135], v[10:13]
	v_mfma_f32_16x16x32_bf16 v[14:17], v[116:119], v[132:135], v[14:17]
	v_mfma_f32_16x16x32_bf16 v[18:21], v[108:111], v[140:143], v[18:21]
	v_mfma_f32_16x16x32_bf16 v[22:25], v[116:119], v[140:143], v[22:25]
	v_mfma_f32_16x16x32_bf16 v[26:29], v[108:111], v[148:151], v[26:29]
	v_mfma_f32_16x16x32_bf16 v[30:33], v[116:119], v[148:151], v[30:33]
	s_barrier
	v_lshl_add_u64 v[160:161], v[76:77], 0, s[10:11]
	s_add_i32 m0, s1, 0x13f00
	s_nop 0
	global_load_lds_dwordx4 v[160:161], off offset:256
	s_add_i32 m0, s1, 0x15f00
	v_lshl_add_u64 v[162:163], v[78:79], 0, s[10:11]
	global_load_lds_dwordx4 v[162:163], off offset:256
	s_waitcnt vmcnt(6)
	s_barrier
	s_barrier
	ds_read_b128 v[104:107], v95 offset:32768
	ds_read_b128 v[108:111], v95 offset:33792
	ds_read_b128 v[112:115], v95 offset:34816
	ds_read_b128 v[116:119], v95 offset:35840
	s_add_i32 m0, s1, 0x3f80
	ds_read_b128 v[120:123], v93 offset:32768
	ds_read_b128 v[124:127], v93 offset:33792
	ds_read_b128 v[128:131], v93 offset:34816
	ds_read_b128 v[132:135], v93 offset:35840
	ds_read_b128 v[136:139], v93 offset:36864
	ds_read_b128 v[140:143], v93 offset:37888
	ds_read_b128 v[144:147], v93 offset:38912
	ds_read_b128 v[148:151], v93 offset:39936
	global_load_lds_dwordx4 v[164:165], off offset:128
	s_add_i32 m0, s1, 0x5f80
	s_nop 0
	global_load_lds_dwordx4 v[86:87], off offset:128
	s_waitcnt lgkmcnt(8)
	s_barrier
	s_waitcnt lgkmcnt(0)
	v_mfma_f32_16x16x32_bf16 v[62:65], v[104:107], v[120:123], v[62:65]
	v_mfma_f32_16x16x32_bf16 v[58:61], v[112:115], v[120:123], v[58:61]
	v_mfma_f32_16x16x32_bf16 v[54:57], v[104:107], v[128:131], v[54:57]
	v_mfma_f32_16x16x32_bf16 v[50:53], v[112:115], v[128:131], v[50:53]
	v_mfma_f32_16x16x32_bf16 v[46:49], v[104:107], v[136:139], v[46:49]
	v_mfma_f32_16x16x32_bf16 v[42:45], v[112:115], v[136:139], v[42:45]
	v_mfma_f32_16x16x32_bf16 v[38:41], v[104:107], v[144:147], v[38:41]
	v_mfma_f32_16x16x32_bf16 v[34:37], v[112:115], v[144:147], v[34:37]
	v_mfma_f32_16x16x32_bf16 v[62:65], v[108:111], v[124:127], v[62:65]
	v_mfma_f32_16x16x32_bf16 v[58:61], v[116:119], v[124:127], v[58:61]
	v_mfma_f32_16x16x32_bf16 v[54:57], v[108:111], v[132:135], v[54:57]
	v_mfma_f32_16x16x32_bf16 v[50:53], v[116:119], v[132:135], v[50:53]
	v_mfma_f32_16x16x32_bf16 v[46:49], v[108:111], v[140:143], v[46:49]
	v_mfma_f32_16x16x32_bf16 v[42:45], v[116:119], v[140:143], v[42:45]
	v_mfma_f32_16x16x32_bf16 v[38:41], v[108:111], v[148:151], v[38:41]
	v_mfma_f32_16x16x32_bf16 v[34:37], v[116:119], v[148:151], v[34:37]
	s_barrier
	s_add_i32 m0, s1, 0x17e80
	s_nop 0
	global_load_lds_dwordx4 v[156:157], off offset:384
	s_add_i32 m0, s1, 0x19e80
	s_nop 0
	global_load_lds_dwordx4 v[158:159], off offset:384
	s_add_i32 m0, s1, 0x7e80
	s_barrier
	s_waitcnt lgkmcnt(0)
	s_barrier
	ds_read_b128 v[120:123], v93 offset:49152
	ds_read_b128 v[124:127], v93 offset:50176
	ds_read_b128 v[128:131], v93 offset:51200
	ds_read_b128 v[132:135], v93 offset:52224
	ds_read_b128 v[136:139], v93 offset:53248
	ds_read_b128 v[140:143], v93 offset:54272
	ds_read_b128 v[144:147], v93 offset:55296
	ds_read_b128 v[148:151], v93 offset:56320
	global_load_lds_dwordx4 v[152:153], off offset:384
	s_add_i32 m0, s1, 0x9e80
	s_nop 0
	global_load_lds_dwordx4 v[154:155], off offset:384
	s_barrier
	s_waitcnt lgkmcnt(0)
	v_mfma_f32_16x16x32_bf16 v[2:5], v[104:107], v[120:123], v[2:5]
	v_mfma_f32_16x16x32_bf16 v[6:9], v[112:115], v[120:123], v[6:9]
	v_mfma_f32_16x16x32_bf16 v[10:13], v[104:107], v[128:131], v[10:13]
	v_mfma_f32_16x16x32_bf16 v[14:17], v[112:115], v[128:131], v[14:17]
	v_mfma_f32_16x16x32_bf16 v[18:21], v[104:107], v[136:139], v[18:21]
	v_mfma_f32_16x16x32_bf16 v[22:25], v[112:115], v[136:139], v[22:25]
	v_mfma_f32_16x16x32_bf16 v[26:29], v[104:107], v[144:147], v[26:29]
	v_mfma_f32_16x16x32_bf16 v[30:33], v[112:115], v[144:147], v[30:33]
	v_mfma_f32_16x16x32_bf16 v[2:5], v[108:111], v[124:127], v[2:5]
	v_mfma_f32_16x16x32_bf16 v[6:9], v[116:119], v[124:127], v[6:9]
	v_mfma_f32_16x16x32_bf16 v[10:13], v[108:111], v[132:135], v[10:13]
	v_mfma_f32_16x16x32_bf16 v[14:17], v[116:119], v[132:135], v[14:17]
	v_mfma_f32_16x16x32_bf16 v[18:21], v[108:111], v[140:143], v[18:21]
	v_mfma_f32_16x16x32_bf16 v[22:25], v[116:119], v[140:143], v[22:25]
	v_mfma_f32_16x16x32_bf16 v[26:29], v[108:111], v[148:151], v[26:29]
	v_mfma_f32_16x16x32_bf16 v[30:33], v[116:119], v[148:151], v[30:33]
	s_barrier
	s_add_i32 m0, s1, 0x1be80
	s_nop 0
	global_load_lds_dwordx4 v[160:161], off offset:384
	s_add_i32 m0, s1, 0x1de80
	s_add_i32 s0, s0, 2
	global_load_lds_dwordx4 v[162:163], off offset:384
	s_waitcnt vmcnt(6)
	s_add_u32 s10, s10, 0x100
	s_addc_u32 s11, s11, 0
	s_cmpk_lt_u32 s0, 0x54
	s_barrier
	s_barrier
	s_cbranch_scc1 .LBB0_689
	s_add_i32 s1, s1, 0x1e000
	s_add_u32 s0, s8, 0x2b80
	s_addc_u32 s1, s9, 0
	v_readfirstlane_b32 s8, v101
	v_lshl_add_u64 v[90:91], s[0:1], 0, v[0:1]
	s_mov_b32 m0, s8
	v_lshl_add_u64 v[66:67], s[0:1], 0, v[66:67]
	v_readfirstlane_b32 s0, v102
	ds_read_b128 v[68:71], v95
	ds_read_b128 v[72:75], v95 offset:1024
	ds_read_b128 v[76:79], v95 offset:2048
	ds_read_b128 v[86:89], v95 offset:3072
	ds_read_b128 v[96:99], v93
	ds_read_b128 v[104:107], v93 offset:1024
	ds_read_b128 v[108:111], v93 offset:2048
	ds_read_b128 v[112:115], v93 offset:3072
	ds_read_b128 v[116:119], v93 offset:4096
	ds_read_b128 v[120:123], v93 offset:5120
	ds_read_b128 v[124:127], v93 offset:6144
	ds_read_b128 v[128:131], v93 offset:7168
	global_load_lds_dwordx4 v[90:91], off
	s_mov_b32 m0, s0
	s_nop 0
	global_load_lds_dwordx4 v[66:67], off
	s_barrier
	s_waitcnt lgkmcnt(0)
	s_setprio 1
	s_waitcnt lgkmcnt(0)
	v_mfma_f32_16x16x32_bf16 v[62:65], v[68:71], v[96:99], v[62:65]
	v_mfma_f32_16x16x32_bf16 v[58:61], v[76:79], v[96:99], v[58:61]
	v_mfma_f32_16x16x32_bf16 v[54:57], v[68:71], v[108:111], v[54:57]
	v_mfma_f32_16x16x32_bf16 v[50:53], v[76:79], v[108:111], v[50:53]
	v_mfma_f32_16x16x32_bf16 v[46:49], v[68:71], v[116:119], v[46:49]
	v_mfma_f32_16x16x32_bf16 v[42:45], v[76:79], v[116:119], v[42:45]
	v_mfma_f32_16x16x32_bf16 v[38:41], v[68:71], v[124:127], v[38:41]
	v_mfma_f32_16x16x32_bf16 v[34:37], v[76:79], v[124:127], v[34:37]
	v_mfma_f32_16x16x32_bf16 v[62:65], v[72:75], v[104:107], v[62:65]
	v_mfma_f32_16x16x32_bf16 v[58:61], v[86:89], v[104:107], v[58:61]
	v_mfma_f32_16x16x32_bf16 v[54:57], v[72:75], v[112:115], v[54:57]
	v_mfma_f32_16x16x32_bf16 v[50:53], v[86:89], v[112:115], v[50:53]
	v_mfma_f32_16x16x32_bf16 v[46:49], v[72:75], v[120:123], v[46:49]
	v_mfma_f32_16x16x32_bf16 v[42:45], v[86:89], v[120:123], v[42:45]
	v_mfma_f32_16x16x32_bf16 v[38:41], v[72:75], v[128:131], v[38:41]
	v_mfma_f32_16x16x32_bf16 v[34:37], v[86:89], v[128:131], v[34:37]
	s_setprio 0
	s_barrier
	s_barrier
	s_waitcnt lgkmcnt(0)
	s_barrier
	ds_read_b128 v[96:99], v93 offset:16384
	ds_read_b128 v[100:103], v93 offset:17408
	ds_read_b128 v[104:107], v93 offset:18432
	ds_read_b128 v[108:111], v93 offset:19456
	ds_read_b128 v[112:115], v93 offset:20480
	ds_read_b128 v[116:119], v93 offset:21504
	ds_read_b128 v[120:123], v93 offset:22528
	ds_read_b128 v[124:127], v93 offset:23552
	s_waitcnt vmcnt(4)
	s_barrier
	s_waitcnt lgkmcnt(0)
	s_setprio 1
	s_waitcnt lgkmcnt(3)
	v_mfma_f32_16x16x32_bf16 v[18:21], v[68:71], v[112:115], v[18:21]
	v_mfma_f32_16x16x32_bf16 v[2:5], v[68:71], v[96:99], v[2:5]
	v_mfma_f32_16x16x32_bf16 v[6:9], v[76:79], v[96:99], v[6:9]
	s_waitcnt lgkmcnt(2)
	v_mfma_f32_16x16x32_bf16 v[96:99], v[72:75], v[116:119], v[18:21]
	v_mfma_f32_16x16x32_bf16 v[18:21], v[76:79], v[112:115], v[22:25]
	v_mfma_f32_16x16x32_bf16 v[2:5], v[72:75], v[100:103], v[2:5]
	v_mfma_f32_16x16x32_bf16 v[6:9], v[86:89], v[100:103], v[6:9]
	v_mfma_f32_16x16x32_bf16 v[10:13], v[68:71], v[104:107], v[10:13]
	v_mfma_f32_16x16x32_bf16 v[14:17], v[76:79], v[104:107], v[14:17]
	v_mfma_f32_16x16x32_bf16 v[100:103], v[86:89], v[116:119], v[18:21]
	s_waitcnt lgkmcnt(1)
	v_mfma_f32_16x16x32_bf16 v[18:21], v[68:71], v[120:123], v[26:29]
	v_mfma_f32_16x16x32_bf16 v[10:13], v[72:75], v[108:111], v[10:13]
	v_mfma_f32_16x16x32_bf16 v[14:17], v[86:89], v[108:111], v[14:17]
	s_waitcnt lgkmcnt(0)
	v_mfma_f32_16x16x32_bf16 v[66:69], v[72:75], v[124:127], v[18:21]
	v_mfma_f32_16x16x32_bf16 v[18:21], v[76:79], v[120:123], v[30:33]
	v_mfma_f32_16x16x32_bf16 v[70:73], v[86:89], v[124:127], v[18:21]
	s_setprio 0
	s_barrier
	ds_read_b128 v[74:77], v95 offset:32768
	ds_read_b128 v[86:89], v95 offset:33792
	ds_read_b128 v[104:107], v95 offset:34816
	ds_read_b128 v[108:111], v95 offset:35840
	s_nop 0
	ds_read_b128 v[18:21], v93 offset:32768
	ds_read_b128 v[22:25], v93 offset:33792
	ds_read_b128 v[26:29], v93 offset:34816
	ds_read_b128 v[30:33], v93 offset:35840
	ds_read_b128 v[112:115], v93 offset:36864
	ds_read_b128 v[116:119], v93 offset:37888
	ds_read_b128 v[120:123], v93 offset:38912
	ds_read_b128 v[124:127], v93 offset:39936
	s_waitcnt vmcnt(2)
	s_barrier
	s_waitcnt lgkmcnt(0)
	s_setprio 1
	s_waitcnt lgkmcnt(7)
	v_mfma_f32_16x16x32_bf16 v[62:65], v[74:77], v[18:21], v[62:65]
	v_mfma_f32_16x16x32_bf16 v[18:21], v[104:107], v[18:21], v[58:61]
	s_waitcnt lgkmcnt(6)
	v_mfma_f32_16x16x32_bf16 v[58:61], v[108:111], v[22:25], v[18:21]
	s_waitcnt lgkmcnt(5)
	v_mfma_f32_16x16x32_bf16 v[18:21], v[74:77], v[26:29], v[54:57]
	s_waitcnt lgkmcnt(4)
	v_mfma_f32_16x16x32_bf16 v[54:57], v[86:89], v[30:33], v[18:21]
	v_mfma_f32_16x16x32_bf16 v[18:21], v[104:107], v[26:29], v[50:53]
	v_mfma_f32_16x16x32_bf16 v[50:53], v[108:111], v[30:33], v[18:21]
	s_waitcnt lgkmcnt(3)
	v_mfma_f32_16x16x32_bf16 v[18:21], v[74:77], v[112:115], v[46:49]
	s_waitcnt lgkmcnt(2)
	v_mfma_f32_16x16x32_bf16 v[46:49], v[86:89], v[116:119], v[18:21]
	v_mfma_f32_16x16x32_bf16 v[18:21], v[104:107], v[112:115], v[42:45]
	v_mfma_f32_16x16x32_bf16 v[42:45], v[108:111], v[116:119], v[18:21]
	s_waitcnt lgkmcnt(1)
	v_mfma_f32_16x16x32_bf16 v[18:21], v[74:77], v[120:123], v[38:41]
	s_waitcnt lgkmcnt(0)
	v_mfma_f32_16x16x32_bf16 v[38:41], v[86:89], v[124:127], v[18:21]
	v_mfma_f32_16x16x32_bf16 v[18:21], v[104:107], v[120:123], v[34:37]
	v_mfma_f32_16x16x32_bf16 v[62:65], v[86:89], v[22:25], v[62:65]
	v_mfma_f32_16x16x32_bf16 v[34:37], v[108:111], v[124:127], v[18:21]
	s_setprio 0
	s_barrier
	s_waitcnt vmcnt(0)
	s_barrier
	s_waitcnt lgkmcnt(0)
	s_barrier
	s_nop 1
	ds_read_b128 v[18:21], v93 offset:49152
	ds_read_b128 v[22:25], v93 offset:50176
	ds_read_b128 v[112:115], v93 offset:51200
	ds_read_b128 v[116:119], v93 offset:52224
	ds_read_b128 v[120:123], v93 offset:53248
	ds_read_b128 v[124:127], v93 offset:54272
	ds_read_b128 v[128:131], v93 offset:55296
	ds_read_b128 v[90:93], v93 offset:56320
	s_barrier
	s_waitcnt lgkmcnt(0)
	s_setprio 1
	s_waitcnt lgkmcnt(7)
	v_mfma_f32_16x16x32_bf16 v[2:5], v[74:77], v[18:21], v[2:5]
	s_waitcnt lgkmcnt(6)
	v_mfma_f32_16x16x32_bf16 v[30:33], v[86:89], v[22:25], v[2:5]
	v_mfma_f32_16x16x32_bf16 v[2:5], v[104:107], v[18:21], v[6:9]
	v_mfma_f32_16x16x32_bf16 v[26:29], v[108:111], v[22:25], v[2:5]
	s_waitcnt lgkmcnt(5)
	v_mfma_f32_16x16x32_bf16 v[2:5], v[74:77], v[112:115], v[10:13]
	s_waitcnt lgkmcnt(4)
	v_mfma_f32_16x16x32_bf16 v[22:25], v[86:89], v[116:119], v[2:5]
	v_mfma_f32_16x16x32_bf16 v[2:5], v[104:107], v[112:115], v[14:17]
	v_mfma_f32_16x16x32_bf16 v[18:21], v[108:111], v[116:119], v[2:5]
	s_waitcnt lgkmcnt(3)
	v_mfma_f32_16x16x32_bf16 v[2:5], v[74:77], v[120:123], v[96:99]
	s_waitcnt lgkmcnt(2)
	v_mfma_f32_16x16x32_bf16 v[14:17], v[86:89], v[124:127], v[2:5]
	v_mfma_f32_16x16x32_bf16 v[2:5], v[104:107], v[120:123], v[100:103]
	v_mfma_f32_16x16x32_bf16 v[10:13], v[108:111], v[124:127], v[2:5]
	s_waitcnt lgkmcnt(1)
	v_mfma_f32_16x16x32_bf16 v[2:5], v[74:77], v[128:131], v[66:69]
	s_waitcnt lgkmcnt(0)
	v_mfma_f32_16x16x32_bf16 v[6:9], v[86:89], v[90:93], v[2:5]
	v_mfma_f32_16x16x32_bf16 v[2:5], v[104:107], v[128:131], v[70:73]
	v_mfma_f32_16x16x32_bf16 v[2:5], v[108:111], v[90:93], v[2:5]
	s_setprio 0
	s_movk_i32 s0, 0x100
	v_cmp_gt_u32_e32 vcc, s0, v80
	s_barrier
	s_and_saveexec_b64 s[0:1], vcc
	s_cbranch_execz .LBB0_692
	s_barrier

.LBB0_761:
	ds_read_b128 v[164:167], v148
	ds_read_b128 v[168:171], v148 offset:1024
	ds_read_b128 v[172:175], v148 offset:2048
	ds_read_b128 v[176:179], v148 offset:3072
	v_lshl_add_u64 v[204:205], v[136:137], 0, s[10:11]
	v_lshl_add_u64 v[228:229], v[204:205], 0, s[34:35]
	s_add_i32 m0, s1, 0xc000
	ds_read_b128 v[180:183], v147
	ds_read_b128 v[184:187], v147 offset:1024
	ds_read_b128 v[188:191], v147 offset:2048
	ds_read_b128 v[192:195], v147 offset:3072
	ds_read_b128 v[196:199], v147 offset:4096
	ds_read_b128 v[200:203], v147 offset:5120
	ds_read_b128 v[222:225], v147 offset:6144
	ds_read_b128 v[232:235], v147 offset:7168
	global_load_lds_dwordx4 v[228:229], off
	v_lshl_add_u64 v[210:211], v[138:139], 0, s[10:11]
	s_add_i32 m0, s1, 0xe000
	v_lshl_add_u64 v[152:153], v[210:211], 0, s[34:35]
	global_load_lds_dwordx4 v[152:153], off
	s_waitcnt lgkmcnt(8)
	s_barrier
	s_waitcnt lgkmcnt(0)
	v_mfma_f32_16x16x32_bf16 v[126:129], v[164:167], v[180:183], v[126:129]
	v_mfma_f32_16x16x32_bf16 v[122:125], v[172:175], v[180:183], v[122:125]
	v_mfma_f32_16x16x32_bf16 v[118:121], v[164:167], v[188:191], v[118:121]
	v_mfma_f32_16x16x32_bf16 v[114:117], v[172:175], v[188:191], v[114:117]
	v_mfma_f32_16x16x32_bf16 v[110:113], v[164:167], v[196:199], v[110:113]
	v_mfma_f32_16x16x32_bf16 v[106:109], v[172:175], v[196:199], v[106:109]
	v_mfma_f32_16x16x32_bf16 v[102:105], v[164:167], v[222:225], v[102:105]
	v_mfma_f32_16x16x32_bf16 v[98:101], v[172:175], v[222:225], v[98:101]
	v_mfma_f32_16x16x32_bf16 v[126:129], v[168:171], v[184:187], v[126:129]
	v_mfma_f32_16x16x32_bf16 v[122:125], v[176:179], v[184:187], v[122:125]
	v_mfma_f32_16x16x32_bf16 v[118:121], v[168:171], v[192:195], v[118:121]
	v_mfma_f32_16x16x32_bf16 v[114:117], v[176:179], v[192:195], v[114:117]
	v_mfma_f32_16x16x32_bf16 v[110:113], v[168:171], v[200:203], v[110:113]
	v_mfma_f32_16x16x32_bf16 v[106:109], v[176:179], v[200:203], v[106:109]
	v_mfma_f32_16x16x32_bf16 v[102:105], v[168:171], v[232:235], v[102:105]
	v_mfma_f32_16x16x32_bf16 v[98:101], v[176:179], v[232:235], v[98:101]
	s_barrier
	v_lshl_add_u64 v[216:217], v[132:133], 0, s[10:11]
	s_add_i32 m0, s1, 0xff00
	ds_read_b128 v[236:239], v148 offset:16384
	ds_read_b128 v[240:243], v148 offset:17408
	ds_read_b128 v[244:247], v148 offset:18432
	ds_read_b128 v[248:251], v148 offset:19456
	global_load_lds_dwordx4 v[216:217], off offset:256
	s_add_i32 m0, s1, 0x11f00
	v_lshl_add_u64 v[218:219], v[134:135], 0, s[10:11]
	global_load_lds_dwordx4 v[218:219], off offset:256
	s_barrier
	s_waitcnt lgkmcnt(0)
	v_mfma_f32_16x16x32_bf16 v[94:97], v[236:239], v[180:183], v[94:97]
	v_mfma_f32_16x16x32_bf16 v[90:93], v[244:247], v[180:183], v[90:93]
	v_mfma_f32_16x16x32_bf16 v[86:89], v[236:239], v[188:191], v[86:89]
	v_mfma_f32_16x16x32_bf16 v[82:85], v[244:247], v[188:191], v[82:85]
	v_mfma_f32_16x16x32_bf16 v[78:81], v[236:239], v[196:199], v[78:81]
	v_mfma_f32_16x16x32_bf16 v[74:77], v[244:247], v[196:199], v[74:77]
	v_mfma_f32_16x16x32_bf16 v[70:73], v[236:239], v[222:225], v[70:73]
	v_mfma_f32_16x16x32_bf16 v[66:69], v[244:247], v[222:225], v[66:69]
	v_mfma_f32_16x16x32_bf16 v[94:97], v[240:243], v[184:187], v[94:97]
	v_mfma_f32_16x16x32_bf16 v[90:93], v[248:251], v[184:187], v[90:93]
	v_mfma_f32_16x16x32_bf16 v[86:89], v[240:243], v[192:195], v[86:89]
	v_mfma_f32_16x16x32_bf16 v[82:85], v[248:251], v[192:195], v[82:85]
	v_mfma_f32_16x16x32_bf16 v[78:81], v[240:243], v[200:203], v[78:81]
	v_mfma_f32_16x16x32_bf16 v[74:77], v[248:251], v[200:203], v[74:77]
	v_mfma_f32_16x16x32_bf16 v[70:73], v[240:243], v[232:235], v[70:73]
	v_mfma_f32_16x16x32_bf16 v[66:69], v[248:251], v[232:235], v[66:69]
	v_lshl_add_u64 v[158:159], v[204:205], 0, s[74:75]
	s_mov_b32 m0, s1
	s_barrier
	ds_read_b128 v[180:183], v147 offset:16384
	ds_read_b128 v[184:187], v147 offset:17408
	ds_read_b128 v[188:191], v147 offset:18432
	ds_read_b128 v[192:195], v147 offset:19456
	ds_read_b128 v[196:199], v147 offset:20480
	ds_read_b128 v[200:203], v147 offset:21504
	ds_read_b128 v[222:225], v147 offset:22528
	ds_read_b128 v[232:235], v147 offset:23552
	global_load_lds_dwordx4 v[158:159], off
	s_add_i32 m0, s1, 0x1f00
	s_nop 0
	global_load_lds_dwordx4 v[210:211], off offset:256
	s_barrier
	s_waitcnt lgkmcnt(0)
	v_mfma_f32_16x16x32_bf16 v[62:65], v[164:167], v[180:183], v[62:65]
	v_mfma_f32_16x16x32_bf16 v[58:61], v[172:175], v[180:183], v[58:61]
	v_mfma_f32_16x16x32_bf16 v[54:57], v[164:167], v[188:191], v[54:57]
	v_mfma_f32_16x16x32_bf16 v[50:53], v[172:175], v[188:191], v[50:53]
	v_mfma_f32_16x16x32_bf16 v[46:49], v[164:167], v[196:199], v[46:49]
	v_mfma_f32_16x16x32_bf16 v[42:45], v[172:175], v[196:199], v[42:45]
	v_mfma_f32_16x16x32_bf16 v[38:41], v[164:167], v[222:225], v[38:41]
	v_mfma_f32_16x16x32_bf16 v[34:37], v[172:175], v[222:225], v[34:37]
	v_mfma_f32_16x16x32_bf16 v[62:65], v[168:171], v[184:187], v[62:65]
	v_mfma_f32_16x16x32_bf16 v[58:61], v[176:179], v[184:187], v[58:61]
	v_mfma_f32_16x16x32_bf16 v[54:57], v[168:171], v[192:195], v[54:57]
	v_mfma_f32_16x16x32_bf16 v[50:53], v[176:179], v[192:195], v[50:53]
	v_mfma_f32_16x16x32_bf16 v[46:49], v[168:171], v[200:203], v[46:49]
	v_mfma_f32_16x16x32_bf16 v[42:45], v[176:179], v[200:203], v[42:45]
	v_mfma_f32_16x16x32_bf16 v[38:41], v[168:171], v[232:235], v[38:41]
	v_mfma_f32_16x16x32_bf16 v[34:37], v[176:179], v[232:235], v[34:37]
	s_barrier
	s_add_i32 m0, s1, 0x14000
	v_lshl_add_u64 v[154:155], v[216:217], 0, s[78:79]
	global_load_lds_dwordx4 v[154:155], off
	s_add_i32 m0, s1, 0x16000
	v_lshl_add_u64 v[156:157], v[218:219], 0, s[78:79]
	global_load_lds_dwordx4 v[156:157], off
	s_waitcnt vmcnt(6)
	s_barrier
	v_mfma_f32_16x16x32_bf16 v[30:33], v[236:239], v[180:183], v[30:33]
	v_mfma_f32_16x16x32_bf16 v[26:29], v[244:247], v[180:183], v[26:29]
	v_mfma_f32_16x16x32_bf16 v[22:25], v[236:239], v[188:191], v[22:25]
	v_mfma_f32_16x16x32_bf16 v[18:21], v[244:247], v[188:191], v[18:21]
	v_mfma_f32_16x16x32_bf16 v[14:17], v[236:239], v[196:199], v[14:17]
	v_mfma_f32_16x16x32_bf16 v[10:13], v[244:247], v[196:199], v[10:13]
	v_mfma_f32_16x16x32_bf16 v[6:9], v[236:239], v[222:225], v[6:9]
	v_mfma_f32_16x16x32_bf16 v[2:5], v[244:247], v[222:225], v[2:5]
	v_mfma_f32_16x16x32_bf16 v[30:33], v[240:243], v[184:187], v[30:33]
	v_mfma_f32_16x16x32_bf16 v[26:29], v[248:251], v[184:187], v[26:29]
	v_mfma_f32_16x16x32_bf16 v[22:25], v[240:243], v[192:195], v[22:25]
	v_mfma_f32_16x16x32_bf16 v[18:21], v[248:251], v[192:195], v[18:21]
	v_mfma_f32_16x16x32_bf16 v[14:17], v[240:243], v[200:203], v[14:17]
	v_mfma_f32_16x16x32_bf16 v[10:13], v[248:251], v[200:203], v[10:13]
	v_mfma_f32_16x16x32_bf16 v[6:9], v[240:243], v[232:235], v[6:9]
	v_mfma_f32_16x16x32_bf16 v[2:5], v[248:251], v[232:235], v[2:5]
	s_barrier
	ds_read_b128 v[164:167], v148 offset:32768
	ds_read_b128 v[168:171], v148 offset:33792
	ds_read_b128 v[172:175], v148 offset:34816
	ds_read_b128 v[176:179], v148 offset:35840
	s_add_i32 m0, s1, 0x3f80
	ds_read_b128 v[180:183], v147 offset:32768
	ds_read_b128 v[184:187], v147 offset:33792
	ds_read_b128 v[188:191], v147 offset:34816
	ds_read_b128 v[192:195], v147 offset:35840
	ds_read_b128 v[196:199], v147 offset:36864
	ds_read_b128 v[200:203], v147 offset:37888
	ds_read_b128 v[222:225], v147 offset:38912
	ds_read_b128 v[232:235], v147 offset:39936
	global_load_lds_dwordx4 v[228:229], off offset:128
	s_add_i32 m0, s1, 0x5f80
	s_nop 0
	global_load_lds_dwordx4 v[152:153], off offset:128
	s_waitcnt lgkmcnt(8)
	s_barrier
	s_waitcnt lgkmcnt(0)
	v_mfma_f32_16x16x32_bf16 v[126:129], v[164:167], v[180:183], v[126:129]
	v_mfma_f32_16x16x32_bf16 v[122:125], v[172:175], v[180:183], v[122:125]
	v_mfma_f32_16x16x32_bf16 v[118:121], v[164:167], v[188:191], v[118:121]
	v_mfma_f32_16x16x32_bf16 v[114:117], v[172:175], v[188:191], v[114:117]
	v_mfma_f32_16x16x32_bf16 v[110:113], v[164:167], v[196:199], v[110:113]
	v_mfma_f32_16x16x32_bf16 v[106:109], v[172:175], v[196:199], v[106:109]
	v_mfma_f32_16x16x32_bf16 v[102:105], v[164:167], v[222:225], v[102:105]
	v_mfma_f32_16x16x32_bf16 v[98:101], v[172:175], v[222:225], v[98:101]
	v_mfma_f32_16x16x32_bf16 v[126:129], v[168:171], v[184:187], v[126:129]
	v_mfma_f32_16x16x32_bf16 v[122:125], v[176:179], v[184:187], v[122:125]
	v_mfma_f32_16x16x32_bf16 v[118:121], v[168:171], v[192:195], v[118:121]
	v_mfma_f32_16x16x32_bf16 v[114:117], v[176:179], v[192:195], v[114:117]
	v_mfma_f32_16x16x32_bf16 v[110:113], v[168:171], v[200:203], v[110:113]
	v_mfma_f32_16x16x32_bf16 v[106:109], v[176:179], v[200:203], v[106:109]
	v_mfma_f32_16x16x32_bf16 v[102:105], v[168:171], v[232:235], v[102:105]
	v_mfma_f32_16x16x32_bf16 v[98:101], v[176:179], v[232:235], v[98:101]
	s_barrier
	s_add_i32 m0, s1, 0x17e80
	ds_read_b128 v[236:239], v148 offset:49152
	ds_read_b128 v[240:243], v148 offset:50176
	ds_read_b128 v[244:247], v148 offset:51200
	ds_read_b128 v[248:251], v148 offset:52224
	global_load_lds_dwordx4 v[216:217], off offset:384
	s_add_i32 m0, s1, 0x19e80
	s_nop 0
	global_load_lds_dwordx4 v[218:219], off offset:384
	s_barrier
	s_waitcnt lgkmcnt(0)
	v_mfma_f32_16x16x32_bf16 v[94:97], v[236:239], v[180:183], v[94:97]
	v_mfma_f32_16x16x32_bf16 v[90:93], v[244:247], v[180:183], v[90:93]
	v_mfma_f32_16x16x32_bf16 v[86:89], v[236:239], v[188:191], v[86:89]
	v_mfma_f32_16x16x32_bf16 v[82:85], v[244:247], v[188:191], v[82:85]
	v_mfma_f32_16x16x32_bf16 v[78:81], v[236:239], v[196:199], v[78:81]
	v_mfma_f32_16x16x32_bf16 v[74:77], v[244:247], v[196:199], v[74:77]
	v_mfma_f32_16x16x32_bf16 v[70:73], v[236:239], v[222:225], v[70:73]
	v_mfma_f32_16x16x32_bf16 v[66:69], v[244:247], v[222:225], v[66:69]
	v_mfma_f32_16x16x32_bf16 v[94:97], v[240:243], v[184:187], v[94:97]
	v_mfma_f32_16x16x32_bf16 v[90:93], v[248:251], v[184:187], v[90:93]
	v_mfma_f32_16x16x32_bf16 v[86:89], v[240:243], v[192:195], v[86:89]
	v_mfma_f32_16x16x32_bf16 v[82:85], v[248:251], v[192:195], v[82:85]
	v_mfma_f32_16x16x32_bf16 v[78:81], v[240:243], v[200:203], v[78:81]
	v_mfma_f32_16x16x32_bf16 v[74:77], v[248:251], v[200:203], v[74:77]
	v_mfma_f32_16x16x32_bf16 v[70:73], v[240:243], v[232:235], v[70:73]
	v_mfma_f32_16x16x32_bf16 v[66:69], v[248:251], v[232:235], v[66:69]
	s_add_i32 m0, s1, 0x7e80
	s_barrier
	ds_read_b128 v[180:183], v147 offset:49152
	ds_read_b128 v[184:187], v147 offset:50176
	ds_read_b128 v[188:191], v147 offset:51200
	ds_read_b128 v[192:195], v147 offset:52224
	ds_read_b128 v[196:199], v147 offset:53248
	ds_read_b128 v[200:203], v147 offset:54272
	ds_read_b128 v[222:225], v147 offset:55296
	ds_read_b128 v[232:235], v147 offset:56320
	global_load_lds_dwordx4 v[204:205], off offset:384
	s_add_i32 m0, s1, 0x9e80
	s_nop 0
	global_load_lds_dwordx4 v[210:211], off offset:384
	s_barrier
	s_waitcnt lgkmcnt(0)
	v_mfma_f32_16x16x32_bf16 v[62:65], v[164:167], v[180:183], v[62:65]
	v_mfma_f32_16x16x32_bf16 v[58:61], v[172:175], v[180:183], v[58:61]
	v_mfma_f32_16x16x32_bf16 v[54:57], v[164:167], v[188:191], v[54:57]
	v_mfma_f32_16x16x32_bf16 v[50:53], v[172:175], v[188:191], v[50:53]
	v_mfma_f32_16x16x32_bf16 v[46:49], v[164:167], v[196:199], v[46:49]
	v_mfma_f32_16x16x32_bf16 v[42:45], v[172:175], v[196:199], v[42:45]
	v_mfma_f32_16x16x32_bf16 v[38:41], v[164:167], v[222:225], v[38:41]
	v_mfma_f32_16x16x32_bf16 v[34:37], v[172:175], v[222:225], v[34:37]
	v_mfma_f32_16x16x32_bf16 v[62:65], v[168:171], v[184:187], v[62:65]
	v_mfma_f32_16x16x32_bf16 v[58:61], v[176:179], v[184:187], v[58:61]
	v_mfma_f32_16x16x32_bf16 v[54:57], v[168:171], v[192:195], v[54:57]
	v_mfma_f32_16x16x32_bf16 v[50:53], v[176:179], v[192:195], v[50:53]
	v_mfma_f32_16x16x32_bf16 v[46:49], v[168:171], v[200:203], v[46:49]
	v_mfma_f32_16x16x32_bf16 v[42:45], v[176:179], v[200:203], v[42:45]
	v_mfma_f32_16x16x32_bf16 v[38:41], v[168:171], v[232:235], v[38:41]
	v_mfma_f32_16x16x32_bf16 v[34:37], v[176:179], v[232:235], v[34:37]
	s_barrier
	s_add_i32 m0, s1, 0x1bf80
	s_nop 0
	global_load_lds_dwordx4 v[154:155], off offset:128
	s_add_i32 m0, s1, 0x1df80
	s_nop 0
	global_load_lds_dwordx4 v[156:157], off offset:128
	s_waitcnt vmcnt(6)
	s_barrier
	v_mfma_f32_16x16x32_bf16 v[30:33], v[236:239], v[180:183], v[30:33]
	v_mfma_f32_16x16x32_bf16 v[26:29], v[244:247], v[180:183], v[26:29]
	v_mfma_f32_16x16x32_bf16 v[22:25], v[236:239], v[188:191], v[22:25]
	v_mfma_f32_16x16x32_bf16 v[18:21], v[244:247], v[188:191], v[18:21]
	v_mfma_f32_16x16x32_bf16 v[14:17], v[236:239], v[196:199], v[14:17]
	v_mfma_f32_16x16x32_bf16 v[10:13], v[244:247], v[196:199], v[10:13]
	v_mfma_f32_16x16x32_bf16 v[6:9], v[236:239], v[222:225], v[6:9]
	v_mfma_f32_16x16x32_bf16 v[2:5], v[244:247], v[222:225], v[2:5]
	v_mfma_f32_16x16x32_bf16 v[30:33], v[240:243], v[184:187], v[30:33]
	v_mfma_f32_16x16x32_bf16 v[26:29], v[248:251], v[184:187], v[26:29]
	v_mfma_f32_16x16x32_bf16 v[22:25], v[240:243], v[192:195], v[22:25]
	v_mfma_f32_16x16x32_bf16 v[18:21], v[248:251], v[192:195], v[18:21]
	v_mfma_f32_16x16x32_bf16 v[14:17], v[240:243], v[200:203], v[14:17]
	v_mfma_f32_16x16x32_bf16 v[10:13], v[248:251], v[200:203], v[10:13]
	v_mfma_f32_16x16x32_bf16 v[6:9], v[240:243], v[232:235], v[6:9]
	v_mfma_f32_16x16x32_bf16 v[2:5], v[248:251], v[232:235], v[2:5]
	s_add_i32 s0, s0, 2
	s_add_u32 s10, s10, 0x100
	s_addc_u32 s11, s11, 0
	s_cmpk_lt_u32 s0, 0x54
	s_barrier
	s_cbranch_scc1 .LBB0_761
	s_add_i32 s1, s1, 0x1e000
	s_add_u32 s0, s8, 0x162b80
	s_addc_u32 s1, s9, 0
	v_readfirstlane_b32 s8, v161
	v_lshl_add_u64 v[158:159], s[0:1], 0, v[0:1]
	s_mov_b32 m0, s8
	v_lshl_add_u64 v[130:131], s[0:1], 0, v[130:131]
	v_readfirstlane_b32 s0, v162
	ds_read_b128 v[132:135], v148
	ds_read_b128 v[136:139], v148 offset:1024
	ds_read_b128 v[150:153], v148 offset:2048
	ds_read_b128 v[154:157], v148 offset:3072
	ds_read_b128 v[164:167], v147
	ds_read_b128 v[168:171], v147 offset:1024
	ds_read_b128 v[172:175], v147 offset:2048
	ds_read_b128 v[176:179], v147 offset:3072
	ds_read_b128 v[180:183], v147 offset:4096
	ds_read_b128 v[184:187], v147 offset:5120
	ds_read_b128 v[188:191], v147 offset:6144
	ds_read_b128 v[192:195], v147 offset:7168
	global_load_lds_dwordx4 v[158:159], off
	s_mov_b32 m0, s0
	s_nop 0
	global_load_lds_dwordx4 v[130:131], off
	s_barrier
	s_waitcnt lgkmcnt(0)
	s_setprio 1
	s_waitcnt lgkmcnt(0)
	v_mfma_f32_16x16x32_bf16 v[122:125], v[150:153], v[164:167], v[122:125]
	v_mfma_f32_16x16x32_bf16 v[118:121], v[132:135], v[172:175], v[118:121]
	v_mfma_f32_16x16x32_bf16 v[114:117], v[150:153], v[172:175], v[114:117]
	v_mfma_f32_16x16x32_bf16 v[102:105], v[132:135], v[188:191], v[102:105]
	v_mfma_f32_16x16x32_bf16 v[98:101], v[150:153], v[188:191], v[98:101]
	v_mfma_f32_16x16x32_bf16 v[126:129], v[132:135], v[164:167], v[126:129]
	v_mfma_f32_16x16x32_bf16 v[122:125], v[154:157], v[168:171], v[122:125]
	v_mfma_f32_16x16x32_bf16 v[118:121], v[136:139], v[176:179], v[118:121]
	v_mfma_f32_16x16x32_bf16 v[114:117], v[154:157], v[176:179], v[114:117]
	v_mfma_f32_16x16x32_bf16 v[110:113], v[132:135], v[180:183], v[110:113]
	v_mfma_f32_16x16x32_bf16 v[106:109], v[150:153], v[180:183], v[106:109]
	v_mfma_f32_16x16x32_bf16 v[102:105], v[136:139], v[192:195], v[102:105]
	v_mfma_f32_16x16x32_bf16 v[98:101], v[154:157], v[192:195], v[98:101]
	v_mfma_f32_16x16x32_bf16 v[126:129], v[136:139], v[168:171], v[126:129]
	v_mfma_f32_16x16x32_bf16 v[158:161], v[136:139], v[184:187], v[110:113]
	v_mfma_f32_16x16x32_bf16 v[196:199], v[154:157], v[184:187], v[106:109]
	s_setprio 0
	s_barrier
	ds_read_b128 v[106:109], v148 offset:16384
	ds_read_b128 v[110:113], v148 offset:17408
	ds_read_b128 v[200:203], v148 offset:18432
	ds_read_b128 v[222:225], v148 offset:19456
	s_barrier
	s_waitcnt lgkmcnt(0)
	s_setprio 1
	s_waitcnt lgkmcnt(3)
	v_mfma_f32_16x16x32_bf16 v[86:89], v[106:109], v[172:175], v[86:89]
	s_waitcnt lgkmcnt(1)
	v_mfma_f32_16x16x32_bf16 v[82:85], v[200:203], v[172:175], v[82:85]
	v_mfma_f32_16x16x32_bf16 v[70:73], v[106:109], v[188:191], v[70:73]
	v_mfma_f32_16x16x32_bf16 v[66:69], v[200:203], v[188:191], v[66:69]
	v_mfma_f32_16x16x32_bf16 v[94:97], v[106:109], v[164:167], v[94:97]
	v_mfma_f32_16x16x32_bf16 v[90:93], v[200:203], v[164:167], v[90:93]
	v_mfma_f32_16x16x32_bf16 v[86:89], v[110:113], v[176:179], v[86:89]
	s_waitcnt lgkmcnt(0)
	v_mfma_f32_16x16x32_bf16 v[82:85], v[222:225], v[176:179], v[82:85]
	v_mfma_f32_16x16x32_bf16 v[78:81], v[106:109], v[180:183], v[78:81]
	v_mfma_f32_16x16x32_bf16 v[74:77], v[200:203], v[180:183], v[74:77]
	v_mfma_f32_16x16x32_bf16 v[70:73], v[110:113], v[192:195], v[70:73]
	v_mfma_f32_16x16x32_bf16 v[66:69], v[222:225], v[192:195], v[66:69]
	v_mfma_f32_16x16x32_bf16 v[232:235], v[110:113], v[168:171], v[94:97]
	v_mfma_f32_16x16x32_bf16 v[162:165], v[222:225], v[168:171], v[90:93]
	v_mfma_f32_16x16x32_bf16 v[166:169], v[110:113], v[184:187], v[78:81]
	v_mfma_f32_16x16x32_bf16 v[170:173], v[222:225], v[184:187], v[74:77]
	s_setprio 0
	s_barrier
	s_nop 0
	ds_read_b128 v[74:77], v147 offset:16384
	ds_read_b128 v[78:81], v147 offset:17408
	ds_read_b128 v[90:93], v147 offset:18432
	ds_read_b128 v[94:97], v147 offset:19456
	ds_read_b128 v[174:177], v147 offset:20480
	ds_read_b128 v[178:181], v147 offset:21504
	ds_read_b128 v[182:185], v147 offset:22528
	ds_read_b128 v[186:189], v147 offset:23552
	s_waitcnt vmcnt(4)
	s_barrier
	s_waitcnt lgkmcnt(0)
	s_setprio 1
	s_waitcnt lgkmcnt(7)
	v_mfma_f32_16x16x32_bf16 v[62:65], v[132:135], v[74:77], v[62:65]
	v_mfma_f32_16x16x32_bf16 v[58:61], v[150:153], v[74:77], v[58:61]
	s_waitcnt lgkmcnt(5)
	v_mfma_f32_16x16x32_bf16 v[54:57], v[132:135], v[90:93], v[54:57]
	v_mfma_f32_16x16x32_bf16 v[50:53], v[150:153], v[90:93], v[50:53]
	s_waitcnt lgkmcnt(1)
	v_mfma_f32_16x16x32_bf16 v[38:41], v[132:135], v[182:185], v[38:41]
	v_mfma_f32_16x16x32_bf16 v[34:37], v[150:153], v[182:185], v[34:37]
	v_mfma_f32_16x16x32_bf16 v[62:65], v[136:139], v[78:81], v[62:65]
	v_mfma_f32_16x16x32_bf16 v[58:61], v[154:157], v[78:81], v[58:61]
	v_mfma_f32_16x16x32_bf16 v[54:57], v[136:139], v[94:97], v[54:57]
	v_mfma_f32_16x16x32_bf16 v[50:53], v[154:157], v[94:97], v[50:53]
	v_mfma_f32_16x16x32_bf16 v[46:49], v[132:135], v[174:177], v[46:49]
	v_mfma_f32_16x16x32_bf16 v[42:45], v[150:153], v[174:177], v[42:45]
	s_waitcnt lgkmcnt(0)
	v_mfma_f32_16x16x32_bf16 v[38:41], v[136:139], v[186:189], v[38:41]
	v_mfma_f32_16x16x32_bf16 v[34:37], v[154:157], v[186:189], v[34:37]
	v_mfma_f32_16x16x32_bf16 v[190:193], v[136:139], v[178:181], v[46:49]
	v_mfma_f32_16x16x32_bf16 v[236:239], v[154:157], v[178:181], v[42:45]
	s_setprio 0
	s_setprio 1
	v_mfma_f32_16x16x32_bf16 v[22:25], v[106:109], v[90:93], v[22:25]
	v_mfma_f32_16x16x32_bf16 v[18:21], v[200:203], v[90:93], v[18:21]
	v_mfma_f32_16x16x32_bf16 v[6:9], v[106:109], v[182:185], v[6:9]
	v_mfma_f32_16x16x32_bf16 v[2:5], v[200:203], v[182:185], v[2:5]
	v_mfma_f32_16x16x32_bf16 v[30:33], v[106:109], v[74:77], v[30:33]
	v_mfma_f32_16x16x32_bf16 v[26:29], v[200:203], v[74:77], v[26:29]
	v_mfma_f32_16x16x32_bf16 v[22:25], v[110:113], v[94:97], v[22:25]
	v_mfma_f32_16x16x32_bf16 v[18:21], v[222:225], v[94:97], v[18:21]
	v_mfma_f32_16x16x32_bf16 v[14:17], v[106:109], v[174:177], v[14:17]
	v_mfma_f32_16x16x32_bf16 v[10:13], v[200:203], v[174:177], v[10:13]
	v_mfma_f32_16x16x32_bf16 v[6:9], v[110:113], v[186:189], v[6:9]
	v_mfma_f32_16x16x32_bf16 v[2:5], v[222:225], v[186:189], v[2:5]
	v_mfma_f32_16x16x32_bf16 v[134:137], v[110:113], v[78:81], v[30:33]
	v_mfma_f32_16x16x32_bf16 v[150:153], v[222:225], v[78:81], v[26:29]
	v_mfma_f32_16x16x32_bf16 v[154:157], v[110:113], v[178:181], v[14:17]
	v_mfma_f32_16x16x32_bf16 v[174:177], v[222:225], v[178:181], v[10:13]
	s_setprio 0
	s_barrier
	s_nop 0
	ds_read_b128 v[10:13], v148 offset:32768
	ds_read_b128 v[14:17], v148 offset:33792
	ds_read_b128 v[178:181], v148 offset:34816
	ds_read_b128 v[182:185], v148 offset:35840
	ds_read_b128 v[26:29], v147 offset:32768
	ds_read_b128 v[30:33], v147 offset:33792
	ds_read_b128 v[42:45], v147 offset:34816
	ds_read_b128 v[46:49], v147 offset:35840
	ds_read_b128 v[186:189], v147 offset:36864
	ds_read_b128 v[200:203], v147 offset:37888
	ds_read_b128 v[222:225], v147 offset:38912
	ds_read_b128 v[240:243], v147 offset:39936
	s_waitcnt vmcnt(2)
	s_barrier
	s_waitcnt lgkmcnt(0)
	s_setprio 1
	s_waitcnt lgkmcnt(7)
	v_mfma_f32_16x16x32_bf16 v[74:77], v[10:13], v[26:29], v[126:129]
	s_waitcnt lgkmcnt(6)
	v_mfma_f32_16x16x32_bf16 v[130:133], v[14:17], v[30:33], v[74:77]
	v_mfma_f32_16x16x32_bf16 v[74:77], v[178:181], v[26:29], v[122:125]
	v_mfma_f32_16x16x32_bf16 v[122:125], v[182:185], v[30:33], v[74:77]
	s_waitcnt lgkmcnt(5)
	v_mfma_f32_16x16x32_bf16 v[74:77], v[10:13], v[42:45], v[118:121]
	s_waitcnt lgkmcnt(4)
	v_mfma_f32_16x16x32_bf16 v[110:113], v[14:17], v[46:49], v[74:77]
	v_mfma_f32_16x16x32_bf16 v[74:77], v[178:181], v[42:45], v[114:117]
	v_mfma_f32_16x16x32_bf16 v[106:109], v[182:185], v[46:49], v[74:77]
	s_waitcnt lgkmcnt(3)
	v_mfma_f32_16x16x32_bf16 v[74:77], v[10:13], v[186:189], v[158:161]
	s_waitcnt lgkmcnt(2)
	v_mfma_f32_16x16x32_bf16 v[94:97], v[14:17], v[200:203], v[74:77]
	v_mfma_f32_16x16x32_bf16 v[74:77], v[178:181], v[186:189], v[196:199]
	v_mfma_f32_16x16x32_bf16 v[90:93], v[182:185], v[200:203], v[74:77]
	s_waitcnt lgkmcnt(1)
	v_mfma_f32_16x16x32_bf16 v[74:77], v[10:13], v[222:225], v[102:105]
	s_waitcnt lgkmcnt(0)
	v_mfma_f32_16x16x32_bf16 v[78:81], v[14:17], v[240:243], v[74:77]
	v_mfma_f32_16x16x32_bf16 v[74:77], v[178:181], v[222:225], v[98:101]
	v_mfma_f32_16x16x32_bf16 v[74:77], v[182:185], v[240:243], v[74:77]
	s_setprio 0
	s_barrier
	ds_read_b128 v[126:129], v148 offset:49152
	ds_read_b128 v[158:161], v148 offset:50176
	ds_read_b128 v[194:197], v148 offset:51200
	ds_read_b128 v[244:247], v148 offset:52224
	s_waitcnt vmcnt(0)
	s_barrier
	s_waitcnt lgkmcnt(0)
	s_setprio 1
	s_waitcnt lgkmcnt(3)
	v_mfma_f32_16x16x32_bf16 v[98:101], v[126:129], v[26:29], v[232:235]
	s_waitcnt lgkmcnt(1)
	v_mfma_f32_16x16x32_bf16 v[26:29], v[194:197], v[26:29], v[162:165]
	s_waitcnt lgkmcnt(0)
	v_mfma_f32_16x16x32_bf16 v[114:117], v[244:247], v[30:33], v[26:29]
	v_mfma_f32_16x16x32_bf16 v[26:29], v[126:129], v[42:45], v[86:89]
	v_mfma_f32_16x16x32_bf16 v[102:105], v[158:161], v[46:49], v[26:29]
	v_mfma_f32_16x16x32_bf16 v[26:29], v[194:197], v[42:45], v[82:85]
	v_mfma_f32_16x16x32_bf16 v[118:121], v[158:161], v[30:33], v[98:101]
	v_mfma_f32_16x16x32_bf16 v[98:101], v[244:247], v[46:49], v[26:29]
	v_mfma_f32_16x16x32_bf16 v[26:29], v[126:129], v[186:189], v[166:169]
	v_mfma_f32_16x16x32_bf16 v[86:89], v[158:161], v[200:203], v[26:29]
	v_mfma_f32_16x16x32_bf16 v[26:29], v[194:197], v[186:189], v[170:173]
	v_mfma_f32_16x16x32_bf16 v[82:85], v[244:247], v[200:203], v[26:29]
	v_mfma_f32_16x16x32_bf16 v[26:29], v[126:129], v[222:225], v[70:73]
	v_mfma_f32_16x16x32_bf16 v[70:73], v[158:161], v[240:243], v[26:29]
	v_mfma_f32_16x16x32_bf16 v[26:29], v[194:197], v[222:225], v[66:69]
	v_mfma_f32_16x16x32_bf16 v[66:69], v[244:247], v[240:243], v[26:29]
	s_setprio 0
	s_barrier
	ds_read_b128 v[162:165], v147 offset:49152
	ds_read_b128 v[166:169], v147 offset:50176
	ds_read_b128 v[170:173], v147 offset:51200
	ds_read_b128 v[186:189], v147 offset:52224
	ds_read_b128 v[198:201], v147 offset:53248
	ds_read_b128 v[202:205], v147 offset:54272
	ds_read_b128 v[222:225], v147 offset:55296
	ds_read_b128 v[146:149], v147 offset:56320
	s_barrier
	s_waitcnt lgkmcnt(0)
	s_setprio 1
	s_waitcnt lgkmcnt(7)
	v_mfma_f32_16x16x32_bf16 v[26:29], v[10:13], v[162:165], v[62:65]
	s_waitcnt lgkmcnt(6)
	v_mfma_f32_16x16x32_bf16 v[62:65], v[14:17], v[166:169], v[26:29]
	v_mfma_f32_16x16x32_bf16 v[26:29], v[178:181], v[162:165], v[58:61]
	v_mfma_f32_16x16x32_bf16 v[58:61], v[182:185], v[166:169], v[26:29]
	s_waitcnt lgkmcnt(5)
	v_mfma_f32_16x16x32_bf16 v[26:29], v[10:13], v[170:173], v[54:57]
	s_waitcnt lgkmcnt(4)
	v_mfma_f32_16x16x32_bf16 v[46:49], v[14:17], v[186:189], v[26:29]
	v_mfma_f32_16x16x32_bf16 v[26:29], v[178:181], v[170:173], v[50:53]
	v_mfma_f32_16x16x32_bf16 v[42:45], v[182:185], v[186:189], v[26:29]
	s_waitcnt lgkmcnt(3)
	v_mfma_f32_16x16x32_bf16 v[26:29], v[10:13], v[198:201], v[190:193]
	s_waitcnt lgkmcnt(1)
	v_mfma_f32_16x16x32_bf16 v[10:13], v[10:13], v[222:225], v[38:41]
	v_mfma_f32_16x16x32_bf16 v[30:33], v[14:17], v[202:205], v[26:29]
	v_mfma_f32_16x16x32_bf16 v[26:29], v[178:181], v[198:201], v[236:239]
	s_waitcnt lgkmcnt(0)
	v_mfma_f32_16x16x32_bf16 v[14:17], v[14:17], v[146:149], v[10:13]
	v_mfma_f32_16x16x32_bf16 v[10:13], v[178:181], v[222:225], v[34:37]
	v_mfma_f32_16x16x32_bf16 v[26:29], v[182:185], v[202:205], v[26:29]
	v_mfma_f32_16x16x32_bf16 v[10:13], v[182:185], v[146:149], v[10:13]
	s_setprio 0
	s_setprio 1
	v_mfma_f32_16x16x32_bf16 v[34:37], v[126:129], v[162:165], v[134:137]
	v_mfma_f32_16x16x32_bf16 v[54:57], v[158:161], v[166:169], v[34:37]
	v_mfma_f32_16x16x32_bf16 v[34:37], v[194:197], v[162:165], v[150:153]
	v_mfma_f32_16x16x32_bf16 v[18:21], v[194:197], v[170:173], v[18:21]
	v_mfma_f32_16x16x32_bf16 v[50:53], v[244:247], v[166:169], v[34:37]
	v_mfma_f32_16x16x32_bf16 v[22:25], v[126:129], v[170:173], v[22:25]
	v_mfma_f32_16x16x32_bf16 v[34:37], v[244:247], v[186:189], v[18:21]
	v_mfma_f32_16x16x32_bf16 v[18:21], v[126:129], v[198:201], v[154:157]
	v_mfma_f32_16x16x32_bf16 v[38:41], v[158:161], v[186:189], v[22:25]
	v_mfma_f32_16x16x32_bf16 v[22:25], v[158:161], v[202:205], v[18:21]
	v_mfma_f32_16x16x32_bf16 v[18:21], v[194:197], v[198:201], v[174:177]
	v_mfma_f32_16x16x32_bf16 v[6:9], v[126:129], v[222:225], v[6:9]
	v_mfma_f32_16x16x32_bf16 v[2:5], v[194:197], v[222:225], v[2:5]
	v_mfma_f32_16x16x32_bf16 v[18:21], v[244:247], v[202:205], v[18:21]
	v_mfma_f32_16x16x32_bf16 v[6:9], v[158:161], v[146:149], v[6:9]
	v_mfma_f32_16x16x32_bf16 v[2:5], v[244:247], v[146:149], v[2:5]
	s_setprio 0
	s_movk_i32 s0, 0x100
	v_cmp_gt_u32_e32 vcc, s0, v140
	s_barrier
	s_and_saveexec_b64 s[0:1], vcc
	s_cbranch_execz .LBB0_764
	s_barrier
